# decode attention: discarded L2 warm-up loads 2-3 batches ahead of the double-buffered K/V streams, all vmcnt waits recomputed; on top of previous best
# baseline (speedup 1.0000x reference)
; #define DEC_LOADK(dst, i0) do { asm volatile("" ::: "memory"); _Pragma("unroll") for (int u = 0; u < 4; ++u) { const float* kr = ck + rbase + (size_t)((i0) + u) * 512; dst[u][0] = __builtin_nontemporal_load((const f32x4*)(kr + 4 * lane)); dst[u][1] = __builtin_nontemporal_load((const f32x4*)(kr + 256 + 4 * lane)); } } while (0)
; __device__ __forceinline__ void decode_item(Frame& F, const Args& a, int l, int item, unsigned char* ws) {
;     ...
;     const float* QS = (const float*)(ws + WS_QS); const int* pt = (const int*)a.in[4] + sb * NPAGES;
;     const float* ck = (const float*)a.in[2] + (size_t)l * NPHYS * 128 * 512; const float* cv = (const float*)a.in[3] + (size_t)l * NPHYS * 128 * 512;
;     const float* bias = (const float*)a.in[17] + l * 4;
;     f32x4 Qr[4][2];
; #pragma unroll
;     for (int qi = 0; qi < 4; ++qi)
; #pragma unroll
;         for (int g = 0; g < 2; ++g) Qr[qi][g] = *(const f32x4*)(QS + (size_t)(sb * 4 + qi) * BW + g * 256 + 4 * lane);
;     const int page = pt[seg * 2 + (w >> 2)];
;     const size_t rbase = ((size_t)page * 128 + (w & 3) * 32) * 512;
;     const int b4 = (lane >> 4) & 1, b3 = (lane >> 3) & 1, b2 = (lane >> 2) & 1;
;     const int vidx = b4 * 4 + b3 * 2 + b2, qi_m = vidx >> 1, head_m = (vidx & 1) * 2 + (lane >> 5);
;     const float bias_m = bias[head_m] * LOG2E;
;     const int pos_m = (head_m & 1) * 8 + qi_m * 2 + (head_m >> 1);
;     {
;         f32x4 ka[4][2], kb[4][2];
;     ...
;         DEC_LOADK(ka, 0); DEC_LOADK(kb, 4); DEC_SCORE(ka, 0); DEC_LOADK(ka, 8); DEC_SCORE(kb, 4); DEC_LOADK(kb, 12); DEC_SCORE(ka, 8); DEC_LOADK(ka, 16); DEC_SCORE(kb, 12); DEC_LOADK(kb, 20); DEC_SCORE(ka, 16); DEC_LOADK(ka, 24); DEC_SCORE(kb, 20); DEC_LOADK(kb, 28); DEC_SCORE(ka, 24); DEC_SCORE(kb, 28);
.LBB0_1149:
	s_lshl_b32 s0, s13, 2
	s_or_b32 s5, s4, s0
	v_readlane_b32 s0, v253, 1
	s_add_i32 s4, s5, s0
	v_lshlrev_b32_e32 v116, 2, v122
	s_ashr_i32 s15, s4, 6
	v_ashrrev_i32_e32 v117, 31, v116
	s_lshl_b32 s16, s15, 2
	v_lshlrev_b64 v[36:37], 2, v[116:117]
	v_lshl_add_u64 v[2:3], s[10:11], 0, v[36:37]
	s_mov_b64 s[24:25], 0x34600000
	s_ashr_i32 s17, s16, 31
	v_lshl_add_u64 v[26:27], v[2:3], 0, s[24:25]
	s_lshl_b64 s[24:25], s[16:17], 11
	v_lshl_add_u64 v[2:3], v[26:27], 0, s[24:25]
	s_or_b32 s24, s16, 1
	s_ashr_i32 s25, s24, 31
	s_lshl_b64 s[24:25], s[24:25], 11
	s_lshl_b32 s6, s15, 7
	v_lshl_add_u64 v[10:11], v[26:27], 0, s[24:25]
	s_or_b32 s24, s16, 2
	s_or_b32 s16, s16, 3
	s_ashr_i32 s7, s6, 31
	s_lshl_b32 s2, s12, 2
	s_ashr_i32 s25, s24, 31
	s_ashr_i32 s17, s16, 31
	v_readlane_b32 s36, v252, 21
	s_ashr_i32 s3, s2, 31
	s_lshl_b64 s[24:25], s[24:25], 11
	s_lshl_b64 s[16:17], s[16:17], 11
	s_lshl_b64 s[6:7], s[6:7], 2
	v_readlane_b32 s44, v252, 29
	s_mul_hi_i32 s1, s12, 0x5000000
	s_mul_i32 s0, s12, 0x5000000
	v_lshl_add_u64 v[18:19], v[26:27], 0, s[24:25]
	v_lshl_add_u64 v[26:27], v[26:27], 0, s[16:17]
	v_readlane_b32 s45, v252, 30
	s_add_u32 s16, s44, s6
	v_readlane_b32 s40, v252, 25
	s_addc_u32 s17, s45, s7
	s_lshl_b64 s[6:7], s[0:1], 2
	v_readlane_b32 s41, v252, 26
	s_add_u32 s0, s40, s6
	s_addc_u32 s1, s41, s7
	s_lshl_b64 s[2:3], s[2:3], 2
	v_readlane_b32 s24, v254, 0
	v_readlane_b32 s25, v254, 1
	s_add_u32 s2, s24, s2
	s_addc_u32 s3, s25, s3
	s_lshl_b32 s5, s5, 1
	s_and_b32 s5, s5, 0x7e
	v_ashrrev_i32_e64 v34, 2, s18
	v_add_u32_e32 v38, s5, v34
	v_ashrrev_i32_e32 v39, 31, v38
	v_lshl_add_u64 v[38:39], v[38:39], 2, s[16:17]
	global_load_dwordx4 v[6:9], v[2:3], off
	s_nop 0
	global_load_dwordx4 v[2:5], v[2:3], off offset:1024
	s_nop 0
	global_load_dwordx4 v[14:17], v[10:11], off
	s_nop 0
	global_load_dwordx4 v[10:13], v[10:11], off offset:1024
	s_nop 0
	global_load_dwordx4 v[22:25], v[18:19], off
	s_nop 0
	global_load_dwordx4 v[18:21], v[18:19], off offset:1024
	s_nop 0
	global_load_dwordx4 v[30:33], v[26:27], off
	s_nop 0
	global_load_dwordx4 v[26:29], v[26:27], off offset:1024
	v_lshlrev_b32_e64 v34, 14, s18
	global_load_dword v38, v[38:39], off
	s_mov_b32 s5, 0xc000
	v_ashrrev_i32_e32 v124, 5, v122
	v_bfe_u32 v94, v122, 4, 1
	v_bfe_u32 v95, v122, 3, 1
	v_lshlrev_b32_e32 v42, 3, v124
	v_lshlrev_b32_e32 v43, 2, v94
	v_lshlrev_b32_e32 v44, 1, v95
	v_and_b32_e32 v106, 64, v218
	v_add_u32_e32 v106, 64, v106
	v_readlane_b32 s42, v252, 27
	v_readlane_b32 s43, v252, 28
	v_readlane_b32 s38, v252, 23
	v_readlane_b32 s39, v252, 24
	v_cmp_eq_u32_e64 s[38:39], 0, v95
	v_readlane_b32 s37, v252, 22
	v_readlane_b32 s46, v252, 31
	v_readlane_b32 s47, v252, 32
	v_readlane_b32 s48, v252, 33
	v_readlane_b32 s49, v252, 34
	v_readlane_b32 s50, v252, 35
	v_readlane_b32 s51, v252, 36
	s_waitcnt vmcnt(0)
	v_ashrrev_i32_e32 v39, 31, v38
	v_lshlrev_b64 v[118:119], 16, v[38:39]
	v_and_or_b32 v118, v34, s5, v118
	v_lshrrev_b32_e32 v34, 1, v122
	v_and_b32_e32 v34, 2, v34
	v_add_u32_e32 v38, v34, v124
	v_ashrrev_i32_e32 v39, 31, v38
	v_lshl_add_u64 v[40:41], v[38:39], 2, s[2:3]
	v_lshl_add_u64 v[92:93], v[118:119], 2, s[0:1]
	global_load_dword v34, v[40:41], off
	v_lshl_add_u64 v[36:37], v[92:93], 0, v[36:37]
	global_load_dwordx4 v[96:99], v[36:37], off nt
	global_load_dwordx4 v[100:103], v[36:37], off offset:1024 nt
	global_load_dwordx4 v[88:91], v[36:37], off offset:2048 nt
	global_load_dwordx4 v[84:87], v[36:37], off offset:3072 nt
	v_add_co_u32_e32 v184, vcc, 0x5000, v36
	s_nop 1
	v_addc_co_u32_e32 v185, vcc, 0, v37, vcc
	v_add_co_u32_e32 v186, vcc, 0x7000, v36
	s_nop 1
	v_addc_co_u32_e32 v187, vcc, 0, v37, vcc
	v_add_co_u32_e32 v188, vcc, 0x9000, v36
	s_nop 1
	v_addc_co_u32_e32 v189, vcc, 0, v37, vcc
	v_add_co_u32_e32 v190, vcc, 0xb000, v36
	s_nop 1
	v_addc_co_u32_e32 v191, vcc, 0, v37, vcc
	v_add_co_u32_e32 v192, vcc, 0xd000, v36
	s_nop 1
	v_addc_co_u32_e32 v193, vcc, 0, v37, vcc
	v_add_co_u32_e32 v194, vcc, 0xf000, v36
	s_nop 1
	v_addc_co_u32_e32 v195, vcc, 0, v37, vcc
	v_ashrrev_i32_e32 v104, 1, v38
	v_add_co_u32_e32 v38, vcc, s69, v36
	s_movk_i32 s0, 0x2000
	s_nop 0
	v_addc_co_u32_e32 v39, vcc, 0, v37, vcc
	v_add_co_u32_e32 v40, vcc, s0, v36
	s_movk_i32 s0, 0x3000
	s_nop 0
	v_addc_co_u32_e32 v41, vcc, 0, v37, vcc
	v_add_co_u32_e32 v36, vcc, s0, v36
	global_load_dwordx4 v[80:83], v[40:41], off offset:-4096 nt
	global_load_dwordx4 v[76:79], v[38:39], off offset:1024 nt
	global_load_dwordx4 v[72:75], v[38:39], off offset:2048 nt
	global_load_dwordx4 v[68:71], v[38:39], off offset:3072 nt
	v_and_b32_e32 v38, 8, v42
	v_addc_co_u32_e32 v37, vcc, 0, v37, vcc
	v_or3_b32 v105, v43, v44, v38
	global_load_dwordx4 v[64:67], v[40:41], off nt
	global_load_dwordx4 v[60:63], v[40:41], off offset:1024 nt
	global_load_dwordx4 v[52:55], v[40:41], off offset:2048 nt
	global_load_dwordx4 v[44:47], v[40:41], off offset:3072 nt
	global_load_dwordx4 v[56:59], v[36:37], off nt
	global_load_dwordx4 v[48:51], v[36:37], off offset:1024 nt
	s_nop 0
	global_load_dwordx4 v[40:43], v[36:37], off offset:2048 nt
	s_nop 0
	global_load_dwordx4 v[36:39], v[36:37], off offset:3072 nt
	global_load_dwordx4 v[204:207], v[184:185], off offset:-4096
	global_load_dwordx4 v[204:207], v[184:185], off offset:-3072
	global_load_dwordx4 v[204:207], v[184:185], off offset:-2048
	global_load_dwordx4 v[204:207], v[184:185], off offset:-1024
	global_load_dwordx4 v[204:207], v[184:185], off
	global_load_dwordx4 v[204:207], v[184:185], off offset:1024
	global_load_dwordx4 v[204:207], v[184:185], off offset:2048
	global_load_dwordx4 v[204:207], v[184:185], off offset:3072
	global_load_dwordx4 v[204:207], v[186:187], off offset:-4096
	global_load_dwordx4 v[204:207], v[186:187], off offset:-3072
	global_load_dwordx4 v[204:207], v[186:187], off offset:-2048
	global_load_dwordx4 v[204:207], v[186:187], off offset:-1024
	global_load_dwordx4 v[204:207], v[186:187], off
	global_load_dwordx4 v[204:207], v[186:187], off offset:1024
	global_load_dwordx4 v[204:207], v[186:187], off offset:2048
	global_load_dwordx4 v[204:207], v[186:187], off offset:3072
	v_cmp_eq_u32_e64 s[0:1], 0, v94
	v_xor_b32_e32 v94, 16, v218
	v_cmp_lt_i32_e32 vcc, v94, v106
	s_waitcnt vmcnt(32)
; #define DEC_LOADK(dst, i0) do { asm volatile("" ::: "memory"); _Pragma("unroll") for (int u = 0; u < 4; ++u) { const float* kr = ck + rbase + (size_t)((i0) + u) * 512; dst[u][0] = __builtin_nontemporal_load((const f32x4*)(kr + 4 * lane)); dst[u][1] = __builtin_nontemporal_load((const f32x4*)(kr + 256 + 4 * lane)); } } while (0)
; __device__ __forceinline__ void decode_item(Frame& F, const Args& a, int l, int item, unsigned char* ws) {
;     ...
;         DEC_LOADK(ka, 0); DEC_LOADK(kb, 4); DEC_SCORE(ka, 0); DEC_LOADK(ka, 8); DEC_SCORE(kb, 4); DEC_LOADK(kb, 12); DEC_SCORE(ka, 8); DEC_LOADK(ka, 16); DEC_SCORE(kb, 12); DEC_LOADK(kb, 20); DEC_SCORE(ka, 16); DEC_LOADK(ka, 24); DEC_SCORE(kb, 20); DEC_LOADK(kb, 28); DEC_SCORE(ka, 24); DEC_SCORE(kb, 28);
	v_mul_f32_e32 v34, 0x3fb8aa3b, v34
	v_cndmask_b32_e32 v94, v218, v94, vcc
	v_lshlrev_b32_e32 v125, 2, v94
	v_and_b32_e32 v94, 4, v122
	v_cmp_eq_u32_e64 s[42:43], 0, v94
	v_and_b32_e32 v94, 3, v122
	v_cmp_eq_u32_e64 s[44:45], 0, v94
	v_lshlrev_b32_e64 v94, 9, s18
	v_add3_u32 v94, v105, v104, v94
	s_waitcnt vmcnt(31)
	v_pk_mul_f32 v[104:105], v[6:7], v[96:97]
	v_lshl_add_u32 v126, v94, 2, 0
	v_pk_fma_f32 v[104:105], v[98:99], v[8:9], v[104:105]
	s_nop 0
	v_add_f32_e32 v95, v104, v105
	s_waitcnt vmcnt(30)
	v_pk_mul_f32 v[104:105], v[2:3], v[100:101]
	s_nop 0
	v_pk_fma_f32 v[104:105], v[102:103], v[4:5], v[104:105]
	s_nop 0
	v_add_f32_e32 v106, v104, v105
	v_pk_mul_f32 v[104:105], v[14:15], v[96:97]
	s_nop 0
	v_pk_fma_f32 v[104:105], v[98:99], v[16:17], v[104:105]
	s_nop 0
	v_add_f32_e32 v107, v104, v105
	v_pk_mul_f32 v[104:105], v[10:11], v[100:101]
	s_nop 0
	v_pk_fma_f32 v[104:105], v[102:103], v[12:13], v[104:105]
	s_nop 0
	v_add_f32_e32 v108, v104, v105
	v_pk_mul_f32 v[104:105], v[22:23], v[96:97]
	v_pk_mul_f32 v[96:97], v[30:31], v[96:97]
	v_pk_fma_f32 v[104:105], v[98:99], v[24:25], v[104:105]
	v_pk_fma_f32 v[96:97], v[98:99], v[32:33], v[96:97]
	v_add_f32_e32 v109, v104, v105
	v_add_f32_e32 v98, v96, v97
	v_pk_mul_f32 v[96:97], v[26:27], v[100:101]
	v_pk_mul_f32 v[104:105], v[18:19], v[100:101]
	v_pk_fma_f32 v[96:97], v[102:103], v[28:29], v[96:97]
	v_pk_fma_f32 v[104:105], v[102:103], v[20:21], v[104:105]
	v_add_f32_e32 v96, v96, v97
	v_cndmask_b32_e64 v97, v95, v109, s[0:1]
	ds_bpermute_b32 v97, v125, v97
	v_add_f32_e32 v104, v104, v105
	v_cndmask_b32_e64 v95, v109, v95, s[0:1]
	v_cndmask_b32_e64 v99, v104, v106, s[0:1]
	s_waitcnt lgkmcnt(0)
	v_add_f32_e32 v95, v95, v97
	v_cndmask_b32_e64 v97, v106, v104, s[0:1]
	ds_bpermute_b32 v97, v125, v97
	s_waitcnt lgkmcnt(0)
	v_add_f32_e32 v97, v99, v97
	v_cndmask_b32_e64 v99, v107, v98, s[0:1]
	ds_bpermute_b32 v99, v125, v99
	v_cndmask_b32_e64 v98, v98, v107, s[0:1]
	s_waitcnt lgkmcnt(0)
	v_add_f32_e32 v98, v98, v99
	v_cndmask_b32_e64 v99, v108, v96, s[0:1]
	ds_bpermute_b32 v99, v125, v99
	v_cndmask_b32_e64 v96, v96, v108, s[0:1]
	s_waitcnt lgkmcnt(0)
	v_add_f32_e32 v96, v96, v99
	v_cndmask_b32_e64 v99, v95, v98, s[38:39]
	v_cndmask_b32_e64 v95, v98, v95, s[38:39]
	v_cndmask_b32_e64 v98, v97, v96, s[38:39]
	v_cndmask_b32_e64 v96, v96, v97, s[38:39]
	v_add_f32_dpp v95, v99, v95 row_ror:8 row_mask:0xf bank_mask:0xf bound_ctrl:1
	s_nop 0
	v_add_f32_dpp v96, v98, v96 row_ror:8 row_mask:0xf bank_mask:0xf bound_ctrl:1
	v_cndmask_b32_e64 v97, v95, v96, s[42:43]
	v_cndmask_b32_e64 v95, v96, v95, s[42:43]
	v_mov_b32_e32 v96, v35
	v_mov_b32_e32 v98, v35
	s_nop 0
	v_mov_b32_dpp v96, v97 row_ror:4 row_mask:0xf bank_mask:0xf
	v_mov_b32_dpp v98, v97 row_ror:12 row_mask:0xf bank_mask:0xf
	v_cndmask_b32_e64 v96, v96, v98, s[42:43]
	v_add_f32_e32 v95, v95, v96
	v_mov_b32_e32 v96, 0
	s_nop 0
	v_add_f32_dpp v95, v95, v95 quad_perm:[2,3,0,1] row_mask:0xf bank_mask:0xf bound_ctrl:1
	s_nop 1
	v_mov_b32_dpp v96, v95 quad_perm:[1,0,3,2] row_mask:0xf bank_mask:0xf
	s_and_saveexec_b64 s[2:3], s[44:45]
	s_cbranch_execz .LBB0_1151
	v_add_f32_e32 v94, v95, v96
	v_add_f32_e32 v94, v34, v94
	v_exp_f32_e32 v94, v94
	s_nop 0
	v_add_f32_e32 v95, 1.0, v94
	v_rcp_f32_e32 v95, v95
	s_nop 0
	v_mul_f32_e32 v94, v94, v95
	ds_write2st64_b32 v126, v95, v94 offset1:64
.LBB0_1151:
	s_or_b64 exec, exec, s[2:3]
	s_waitcnt vmcnt(29)
	v_pk_mul_f32 v[94:95], v[6:7], v[88:89]
	s_nop 0
	v_pk_fma_f32 v[94:95], v[90:91], v[8:9], v[94:95]
	s_nop 0
	v_add_f32_e32 v96, v94, v95
	s_waitcnt vmcnt(28)
	v_pk_mul_f32 v[94:95], v[2:3], v[84:85]
	s_nop 0
	v_pk_fma_f32 v[94:95], v[86:87], v[4:5], v[94:95]
	s_nop 0
	v_add_f32_e32 v97, v94, v95
	v_pk_mul_f32 v[94:95], v[14:15], v[88:89]
	s_nop 0
	v_pk_fma_f32 v[94:95], v[90:91], v[16:17], v[94:95]
	s_nop 0
	v_add_f32_e32 v98, v94, v95
	v_pk_mul_f32 v[94:95], v[10:11], v[84:85]
	s_nop 0
	v_pk_fma_f32 v[94:95], v[86:87], v[12:13], v[94:95]
	s_nop 0
	v_add_f32_e32 v99, v94, v95
	v_pk_mul_f32 v[94:95], v[22:23], v[88:89]
	v_pk_mul_f32 v[88:89], v[30:31], v[88:89]
	v_pk_fma_f32 v[94:95], v[90:91], v[24:25], v[94:95]
	v_pk_fma_f32 v[88:89], v[90:91], v[32:33], v[88:89]
	v_add_f32_e32 v100, v94, v95
	v_add_f32_e32 v88, v88, v89
	v_cndmask_b32_e64 v89, v96, v100, s[0:1]
	ds_bpermute_b32 v89, v125, v89
	v_pk_mul_f32 v[94:95], v[18:19], v[84:85]
	v_pk_mul_f32 v[84:85], v[26:27], v[84:85]
	v_pk_fma_f32 v[94:95], v[86:87], v[20:21], v[94:95]
	v_pk_fma_f32 v[84:85], v[86:87], v[28:29], v[84:85]
	v_add_f32_e32 v94, v94, v95
	v_add_f32_e32 v84, v84, v85
	v_cndmask_b32_e64 v85, v100, v96, s[0:1]
	v_cndmask_b32_e64 v86, v97, v94, s[0:1]
	s_waitcnt lgkmcnt(0)
	v_add_f32_e32 v85, v85, v89
	ds_bpermute_b32 v86, v125, v86
	v_cndmask_b32_e64 v89, v98, v88, s[0:1]
	v_cndmask_b32_e64 v90, v99, v84, s[0:1]
	ds_bpermute_b32 v89, v125, v89
	ds_bpermute_b32 v90, v125, v90
	v_cndmask_b32_e64 v87, v94, v97, s[0:1]
	s_waitcnt lgkmcnt(2)
	v_add_f32_e32 v86, v87, v86
	v_cndmask_b32_e64 v87, v88, v98, s[0:1]
	v_cndmask_b32_e64 v84, v84, v99, s[0:1]
	s_waitcnt lgkmcnt(1)
	v_add_f32_e32 v87, v87, v89
	s_waitcnt lgkmcnt(0)
	v_add_f32_e32 v84, v84, v90
	v_cndmask_b32_e64 v88, v85, v87, s[38:39]
	v_cndmask_b32_e64 v85, v87, v85, s[38:39]
	v_cndmask_b32_e64 v87, v86, v84, s[38:39]
	v_cndmask_b32_e64 v84, v84, v86, s[38:39]
	v_add_f32_dpp v85, v88, v85 row_ror:8 row_mask:0xf bank_mask:0xf bound_ctrl:1
	s_nop 0
	v_add_f32_dpp v84, v87, v84 row_ror:8 row_mask:0xf bank_mask:0xf bound_ctrl:1
	v_cndmask_b32_e64 v86, v85, v84, s[42:43]
	v_cndmask_b32_e64 v84, v84, v85, s[42:43]
	v_mov_b32_e32 v85, v35
	v_mov_b32_e32 v87, v35
	s_nop 0
	v_mov_b32_dpp v85, v86 row_ror:4 row_mask:0xf bank_mask:0xf
	v_mov_b32_dpp v87, v86 row_ror:12 row_mask:0xf bank_mask:0xf
	v_cndmask_b32_e64 v85, v85, v87, s[42:43]
	v_add_f32_e32 v84, v84, v85
	v_mov_b32_e32 v85, 0
	s_nop 0
	v_add_f32_dpp v84, v84, v84 quad_perm:[2,3,0,1] row_mask:0xf bank_mask:0xf bound_ctrl:1
	s_nop 1
	v_mov_b32_dpp v85, v84 quad_perm:[1,0,3,2] row_mask:0xf bank_mask:0xf
	s_and_saveexec_b64 s[2:3], s[44:45]
	s_cbranch_execz .LBB0_1153
	v_add_f32_e32 v84, v84, v85
	v_add_f32_e32 v84, v34, v84
	v_exp_f32_e32 v84, v84
	v_add_u32_e32 v86, 64, v126
	v_add_f32_e32 v85, 1.0, v84
	v_rcp_f32_e32 v85, v85
	s_nop 0
	v_mul_f32_e32 v84, v84, v85
	ds_write2st64_b32 v86, v85, v84 offset1:64
; #define DEC_LOADK(dst, i0) do { asm volatile("" ::: "memory"); _Pragma("unroll") for (int u = 0; u < 4; ++u) { const float* kr = ck + rbase + (size_t)((i0) + u) * 512; dst[u][0] = __builtin_nontemporal_load((const f32x4*)(kr + 4 * lane)); dst[u][1] = __builtin_nontemporal_load((const f32x4*)(kr + 256 + 4 * lane)); } } while (0)
; __device__ __forceinline__ void decode_item(Frame& F, const Args& a, int l, int item, unsigned char* ws) {
;     ...
;         DEC_LOADK(ka, 0); DEC_LOADK(kb, 4); DEC_SCORE(ka, 0); DEC_LOADK(ka, 8); DEC_SCORE(kb, 4); DEC_LOADK(kb, 12); DEC_SCORE(ka, 8); DEC_LOADK(ka, 16); DEC_SCORE(kb, 12); DEC_LOADK(kb, 20); DEC_SCORE(ka, 16); DEC_LOADK(ka, 24); DEC_SCORE(kb, 20); DEC_LOADK(kb, 28); DEC_SCORE(ka, 24); DEC_SCORE(kb, 28);
.LBB0_1153:
	s_or_b64 exec, exec, s[2:3]
	s_waitcnt vmcnt(27)
	v_pk_mul_f32 v[84:85], v[6:7], v[80:81]
	s_nop 0
	v_pk_fma_f32 v[84:85], v[82:83], v[8:9], v[84:85]
	s_nop 0
	v_add_f32_e32 v86, v84, v85
	s_waitcnt vmcnt(26)
	v_pk_mul_f32 v[84:85], v[2:3], v[76:77]
	s_nop 0
	v_pk_fma_f32 v[84:85], v[78:79], v[4:5], v[84:85]
	s_nop 0
	v_add_f32_e32 v87, v84, v85
	v_pk_mul_f32 v[84:85], v[14:15], v[80:81]
	s_nop 0
	v_pk_fma_f32 v[84:85], v[82:83], v[16:17], v[84:85]
	s_nop 0
	v_add_f32_e32 v88, v84, v85
	v_pk_mul_f32 v[84:85], v[10:11], v[76:77]
	s_nop 0
	v_pk_fma_f32 v[84:85], v[78:79], v[12:13], v[84:85]
	s_nop 0
	v_add_f32_e32 v89, v84, v85
	v_pk_mul_f32 v[84:85], v[22:23], v[80:81]
	v_pk_mul_f32 v[80:81], v[30:31], v[80:81]
	v_pk_fma_f32 v[84:85], v[82:83], v[24:25], v[84:85]
	v_pk_fma_f32 v[80:81], v[82:83], v[32:33], v[80:81]
	v_add_f32_e32 v90, v84, v85
	v_add_f32_e32 v80, v80, v81
	v_cndmask_b32_e64 v81, v86, v90, s[0:1]
	ds_bpermute_b32 v81, v125, v81
	v_pk_mul_f32 v[84:85], v[18:19], v[76:77]
	v_pk_mul_f32 v[76:77], v[26:27], v[76:77]
	v_pk_fma_f32 v[84:85], v[78:79], v[20:21], v[84:85]
	v_pk_fma_f32 v[76:77], v[78:79], v[28:29], v[76:77]
	v_add_f32_e32 v84, v84, v85
	v_add_f32_e32 v76, v76, v77
	v_cndmask_b32_e64 v77, v90, v86, s[0:1]
	v_cndmask_b32_e64 v78, v87, v84, s[0:1]
	s_waitcnt lgkmcnt(0)
	v_add_f32_e32 v77, v77, v81
	ds_bpermute_b32 v78, v125, v78
	v_cndmask_b32_e64 v81, v88, v80, s[0:1]
	v_cndmask_b32_e64 v82, v89, v76, s[0:1]
	ds_bpermute_b32 v81, v125, v81
	ds_bpermute_b32 v82, v125, v82
	v_cndmask_b32_e64 v79, v84, v87, s[0:1]
	s_waitcnt lgkmcnt(2)
	v_add_f32_e32 v78, v79, v78
	v_cndmask_b32_e64 v79, v80, v88, s[0:1]
	v_cndmask_b32_e64 v76, v76, v89, s[0:1]
	s_waitcnt lgkmcnt(1)
	v_add_f32_e32 v79, v79, v81
	s_waitcnt lgkmcnt(0)
	v_add_f32_e32 v76, v76, v82
	v_cndmask_b32_e64 v80, v77, v79, s[38:39]
	v_cndmask_b32_e64 v77, v79, v77, s[38:39]
	v_cndmask_b32_e64 v79, v78, v76, s[38:39]
	v_cndmask_b32_e64 v76, v76, v78, s[38:39]
	v_add_f32_dpp v77, v80, v77 row_ror:8 row_mask:0xf bank_mask:0xf bound_ctrl:1
	s_nop 0
	v_add_f32_dpp v76, v79, v76 row_ror:8 row_mask:0xf bank_mask:0xf bound_ctrl:1
	v_cndmask_b32_e64 v78, v77, v76, s[42:43]
	v_cndmask_b32_e64 v76, v76, v77, s[42:43]
	v_mov_b32_e32 v77, v35
	v_mov_b32_e32 v79, v35
	s_nop 0
	v_mov_b32_dpp v77, v78 row_ror:4 row_mask:0xf bank_mask:0xf
	v_mov_b32_dpp v79, v78 row_ror:12 row_mask:0xf bank_mask:0xf
	v_cndmask_b32_e64 v77, v77, v79, s[42:43]
	v_add_f32_e32 v76, v76, v77
	v_mov_b32_e32 v77, 0
	s_nop 0
	v_add_f32_dpp v76, v76, v76 quad_perm:[2,3,0,1] row_mask:0xf bank_mask:0xf bound_ctrl:1
	s_nop 1
	v_mov_b32_dpp v77, v76 quad_perm:[1,0,3,2] row_mask:0xf bank_mask:0xf
	s_and_saveexec_b64 s[2:3], s[44:45]
	s_cbranch_execz .LBB0_1155
	v_add_f32_e32 v76, v76, v77
	v_add_f32_e32 v76, v34, v76
	v_exp_f32_e32 v76, v76
	v_add_u32_e32 v78, 0x80, v126
	v_add_f32_e32 v77, 1.0, v76
	v_rcp_f32_e32 v77, v77
	s_nop 0
	v_mul_f32_e32 v76, v76, v77
	ds_write2st64_b32 v78, v77, v76 offset1:64
.LBB0_1155:
	s_or_b64 exec, exec, s[2:3]
	s_waitcnt vmcnt(25)
	v_pk_mul_f32 v[76:77], v[6:7], v[72:73]
	s_nop 0
	v_pk_fma_f32 v[76:77], v[74:75], v[8:9], v[76:77]
	s_nop 0
	v_add_f32_e32 v78, v76, v77
	s_waitcnt vmcnt(24)
	v_pk_mul_f32 v[76:77], v[2:3], v[68:69]
	s_nop 0
	v_pk_fma_f32 v[76:77], v[70:71], v[4:5], v[76:77]
	s_nop 0
	v_add_f32_e32 v79, v76, v77
	v_pk_mul_f32 v[76:77], v[14:15], v[72:73]
	s_nop 0
	v_pk_fma_f32 v[76:77], v[74:75], v[16:17], v[76:77]
	s_nop 0
	v_add_f32_e32 v80, v76, v77
	v_pk_mul_f32 v[76:77], v[10:11], v[68:69]
	s_nop 0
	v_pk_fma_f32 v[76:77], v[70:71], v[12:13], v[76:77]
	s_nop 0
	v_add_f32_e32 v81, v76, v77
	v_pk_mul_f32 v[76:77], v[22:23], v[72:73]
	v_pk_mul_f32 v[72:73], v[30:31], v[72:73]
	v_pk_fma_f32 v[76:77], v[74:75], v[24:25], v[76:77]
	v_pk_fma_f32 v[72:73], v[74:75], v[32:33], v[72:73]
	v_add_f32_e32 v82, v76, v77
	v_add_f32_e32 v72, v72, v73
	v_cndmask_b32_e64 v73, v78, v82, s[0:1]
	ds_bpermute_b32 v73, v125, v73
	v_pk_mul_f32 v[76:77], v[18:19], v[68:69]
	v_pk_mul_f32 v[68:69], v[26:27], v[68:69]
	v_pk_fma_f32 v[76:77], v[70:71], v[20:21], v[76:77]
	v_pk_fma_f32 v[68:69], v[70:71], v[28:29], v[68:69]
	v_add_f32_e32 v76, v76, v77
	v_add_f32_e32 v68, v68, v69
	v_cndmask_b32_e64 v69, v82, v78, s[0:1]
	v_cndmask_b32_e64 v70, v79, v76, s[0:1]
	s_waitcnt lgkmcnt(0)
	v_add_f32_e32 v69, v69, v73
	ds_bpermute_b32 v70, v125, v70
	v_cndmask_b32_e64 v73, v80, v72, s[0:1]
	v_cndmask_b32_e64 v74, v81, v68, s[0:1]
	ds_bpermute_b32 v73, v125, v73
	ds_bpermute_b32 v74, v125, v74
	v_cndmask_b32_e64 v71, v76, v79, s[0:1]
	s_waitcnt lgkmcnt(2)
	v_add_f32_e32 v70, v71, v70
	v_cndmask_b32_e64 v71, v72, v80, s[0:1]
	v_cndmask_b32_e64 v68, v68, v81, s[0:1]
	s_waitcnt lgkmcnt(1)
	v_add_f32_e32 v71, v71, v73
	s_waitcnt lgkmcnt(0)
	v_add_f32_e32 v68, v68, v74
	v_cndmask_b32_e64 v72, v69, v71, s[38:39]
	v_cndmask_b32_e64 v69, v71, v69, s[38:39]
	v_cndmask_b32_e64 v71, v70, v68, s[38:39]
	v_cndmask_b32_e64 v68, v68, v70, s[38:39]
	v_add_f32_dpp v69, v72, v69 row_ror:8 row_mask:0xf bank_mask:0xf bound_ctrl:1
	s_nop 0
	v_add_f32_dpp v68, v71, v68 row_ror:8 row_mask:0xf bank_mask:0xf bound_ctrl:1
	v_cndmask_b32_e64 v70, v69, v68, s[42:43]
	v_cndmask_b32_e64 v68, v68, v69, s[42:43]
	v_mov_b32_e32 v69, v35
	v_mov_b32_e32 v71, v35
	s_nop 0
	v_mov_b32_dpp v69, v70 row_ror:4 row_mask:0xf bank_mask:0xf
	v_mov_b32_dpp v71, v70 row_ror:12 row_mask:0xf bank_mask:0xf
	v_cndmask_b32_e64 v69, v69, v71, s[42:43]
	v_add_f32_e32 v68, v68, v69
	v_mov_b32_e32 v69, 0
	s_nop 0
	v_add_f32_dpp v68, v68, v68 quad_perm:[2,3,0,1] row_mask:0xf bank_mask:0xf bound_ctrl:1
	s_nop 1
	v_mov_b32_dpp v69, v68 quad_perm:[1,0,3,2] row_mask:0xf bank_mask:0xf
	s_and_saveexec_b64 s[2:3], s[44:45]
	s_cbranch_execz .LBB0_1157
	v_add_f32_e32 v68, v68, v69
	v_add_f32_e32 v68, v34, v68
	v_exp_f32_e32 v68, v68
	v_add_u32_e32 v70, 0xc0, v126
	v_add_f32_e32 v69, 1.0, v68
	v_rcp_f32_e32 v69, v69
	s_nop 0
	v_mul_f32_e32 v68, v68, v69
	ds_write2st64_b32 v70, v69, v68 offset1:64
; #define DEC_LOADK(dst, i0) do { asm volatile("" ::: "memory"); _Pragma("unroll") for (int u = 0; u < 4; ++u) { const float* kr = ck + rbase + (size_t)((i0) + u) * 512; dst[u][0] = __builtin_nontemporal_load((const f32x4*)(kr + 4 * lane)); dst[u][1] = __builtin_nontemporal_load((const f32x4*)(kr + 256 + 4 * lane)); } } while (0)
; __device__ __forceinline__ void decode_item(Frame& F, const Args& a, int l, int item, unsigned char* ws) {
;     ...
;         DEC_LOADK(ka, 0); DEC_LOADK(kb, 4); DEC_SCORE(ka, 0); DEC_LOADK(ka, 8); DEC_SCORE(kb, 4); DEC_LOADK(kb, 12); DEC_SCORE(ka, 8); DEC_LOADK(ka, 16); DEC_SCORE(kb, 12); DEC_LOADK(kb, 20); DEC_SCORE(ka, 16); DEC_LOADK(ka, 24); DEC_SCORE(kb, 20); DEC_LOADK(kb, 28); DEC_SCORE(ka, 24); DEC_SCORE(kb, 28);
.LBB0_1157:
	s_or_b64 exec, exec, s[2:3]
	v_lshl_add_u64 v[120:121], v[116:117], 2, v[92:93]
	v_add_co_u32_e32 v68, vcc, 0x4000, v120
	s_waitcnt vmcnt(23)
	v_pk_mul_f32 v[84:85], v[6:7], v[64:65]
	v_addc_co_u32_e32 v69, vcc, 0, v121, vcc
	global_load_dwordx4 v[112:115], v[68:69], off nt
	global_load_dwordx4 v[104:107], v[68:69], off offset:1024 nt
	global_load_dwordx4 v[96:99], v[68:69], off offset:2048 nt
	global_load_dwordx4 v[88:91], v[68:69], off offset:3072 nt
	v_add_co_u32_e32 v68, vcc, 0x5000, v120
	v_pk_fma_f32 v[84:85], v[66:67], v[8:9], v[84:85]
	s_nop 0
	v_addc_co_u32_e32 v69, vcc, 0, v121, vcc
	global_load_dwordx4 v[80:83], v[68:69], off nt
	global_load_dwordx4 v[76:79], v[68:69], off offset:1024 nt
	global_load_dwordx4 v[72:75], v[68:69], off offset:2048 nt
	s_nop 0
	global_load_dwordx4 v[68:71], v[68:69], off offset:3072 nt
	global_load_dwordx4 v[204:207], v[188:189], off offset:-4096
	global_load_dwordx4 v[204:207], v[188:189], off offset:-3072
	global_load_dwordx4 v[204:207], v[188:189], off offset:-2048
	global_load_dwordx4 v[204:207], v[188:189], off offset:-1024
	global_load_dwordx4 v[204:207], v[188:189], off
	global_load_dwordx4 v[204:207], v[188:189], off offset:1024
	global_load_dwordx4 v[204:207], v[188:189], off offset:2048
	global_load_dwordx4 v[204:207], v[188:189], off offset:3072
	v_add_f32_e32 v86, v84, v85
	s_waitcnt vmcnt(38)
	v_pk_mul_f32 v[84:85], v[2:3], v[60:61]
	s_nop 0
	v_pk_fma_f32 v[84:85], v[62:63], v[4:5], v[84:85]
	s_nop 0
	v_add_f32_e32 v87, v84, v85
	v_pk_mul_f32 v[84:85], v[14:15], v[64:65]
	s_nop 0
	v_pk_fma_f32 v[84:85], v[66:67], v[16:17], v[84:85]
	s_nop 0
	v_add_f32_e32 v92, v84, v85
	v_pk_mul_f32 v[84:85], v[10:11], v[60:61]
	s_nop 0
	v_pk_fma_f32 v[84:85], v[62:63], v[12:13], v[84:85]
	s_nop 0
	v_add_f32_e32 v93, v84, v85
	v_pk_mul_f32 v[84:85], v[22:23], v[64:65]
	v_pk_mul_f32 v[64:65], v[30:31], v[64:65]
	v_pk_fma_f32 v[84:85], v[66:67], v[24:25], v[84:85]
	v_pk_fma_f32 v[64:65], v[66:67], v[32:33], v[64:65]
	v_add_f32_e32 v94, v84, v85
	v_add_f32_e32 v64, v64, v65
	v_cndmask_b32_e64 v65, v86, v94, s[0:1]
	ds_bpermute_b32 v65, v125, v65
	v_pk_mul_f32 v[84:85], v[18:19], v[60:61]
	v_pk_mul_f32 v[60:61], v[26:27], v[60:61]
	v_pk_fma_f32 v[84:85], v[62:63], v[20:21], v[84:85]
	v_pk_fma_f32 v[60:61], v[62:63], v[28:29], v[60:61]
	v_add_f32_e32 v84, v84, v85
	v_add_f32_e32 v60, v60, v61
	v_cndmask_b32_e64 v61, v94, v86, s[0:1]
	v_cndmask_b32_e64 v62, v87, v84, s[0:1]
	s_waitcnt lgkmcnt(0)
	v_add_f32_e32 v61, v61, v65
	ds_bpermute_b32 v62, v125, v62
	v_cndmask_b32_e64 v65, v92, v64, s[0:1]
	v_cndmask_b32_e64 v66, v93, v60, s[0:1]
	ds_bpermute_b32 v65, v125, v65
	ds_bpermute_b32 v66, v125, v66
	v_cndmask_b32_e64 v63, v84, v87, s[0:1]
	s_waitcnt lgkmcnt(2)
	v_add_f32_e32 v62, v63, v62
	v_cndmask_b32_e64 v63, v64, v92, s[0:1]
	v_cndmask_b32_e64 v60, v60, v93, s[0:1]
	s_waitcnt lgkmcnt(1)
	v_add_f32_e32 v63, v63, v65
	s_waitcnt lgkmcnt(0)
	v_add_f32_e32 v60, v60, v66
	v_cndmask_b32_e64 v64, v61, v63, s[38:39]
	v_cndmask_b32_e64 v61, v63, v61, s[38:39]
	v_cndmask_b32_e64 v63, v62, v60, s[38:39]
	v_cndmask_b32_e64 v60, v60, v62, s[38:39]
	v_add_f32_dpp v61, v64, v61 row_ror:8 row_mask:0xf bank_mask:0xf bound_ctrl:1
	s_nop 0
	v_add_f32_dpp v60, v63, v60 row_ror:8 row_mask:0xf bank_mask:0xf bound_ctrl:1
	v_cndmask_b32_e64 v62, v61, v60, s[42:43]
	v_cndmask_b32_e64 v60, v60, v61, s[42:43]
	v_mov_b32_e32 v61, v35
	v_mov_b32_e32 v63, v35
	s_nop 0
	v_mov_b32_dpp v61, v62 row_ror:4 row_mask:0xf bank_mask:0xf
	v_mov_b32_dpp v63, v62 row_ror:12 row_mask:0xf bank_mask:0xf
	v_cndmask_b32_e64 v61, v61, v63, s[42:43]
	v_add_f32_e32 v60, v60, v61
	v_mov_b32_e32 v61, 0
	s_nop 0
	v_add_f32_dpp v60, v60, v60 quad_perm:[2,3,0,1] row_mask:0xf bank_mask:0xf bound_ctrl:1
	s_nop 1
	v_mov_b32_dpp v61, v60 quad_perm:[1,0,3,2] row_mask:0xf bank_mask:0xf
	s_and_saveexec_b64 s[2:3], s[44:45]
	s_cbranch_execz .LBB0_1159
	v_add_f32_e32 v60, v60, v61
	v_add_f32_e32 v60, v34, v60
	v_exp_f32_e32 v60, v60
	s_nop 0
	v_add_f32_e32 v61, 1.0, v60
	v_rcp_f32_e32 v61, v61
	s_nop 0
	v_mul_f32_e32 v60, v60, v61
	ds_write2st64_b32 v126, v61, v60 offset0:1 offset1:65
.LBB0_1159:
	s_or_b64 exec, exec, s[2:3]
	s_waitcnt vmcnt(37)
	v_pk_mul_f32 v[60:61], v[6:7], v[52:53]
	s_nop 0
	v_pk_fma_f32 v[60:61], v[54:55], v[8:9], v[60:61]
	s_nop 0
	v_add_f32_e32 v62, v60, v61
	s_waitcnt vmcnt(36)
	v_pk_mul_f32 v[60:61], v[2:3], v[44:45]
	s_nop 0
	v_pk_fma_f32 v[60:61], v[46:47], v[4:5], v[60:61]
	s_nop 0
	v_add_f32_e32 v63, v60, v61
	v_pk_mul_f32 v[60:61], v[14:15], v[52:53]
	s_nop 0
	v_pk_fma_f32 v[60:61], v[54:55], v[16:17], v[60:61]
	s_nop 0
	v_add_f32_e32 v64, v60, v61
	v_pk_mul_f32 v[60:61], v[10:11], v[44:45]
	s_nop 0
	v_pk_fma_f32 v[60:61], v[46:47], v[12:13], v[60:61]
	s_nop 0
	v_add_f32_e32 v65, v60, v61
	v_pk_mul_f32 v[60:61], v[22:23], v[52:53]
	v_pk_mul_f32 v[52:53], v[30:31], v[52:53]
	v_pk_fma_f32 v[60:61], v[54:55], v[24:25], v[60:61]
	v_pk_fma_f32 v[52:53], v[54:55], v[32:33], v[52:53]
	v_add_f32_e32 v66, v60, v61
	v_add_f32_e32 v52, v52, v53
	v_cndmask_b32_e64 v53, v62, v66, s[0:1]
	ds_bpermute_b32 v53, v125, v53
	v_pk_mul_f32 v[60:61], v[18:19], v[44:45]
	v_pk_mul_f32 v[44:45], v[26:27], v[44:45]
	v_pk_fma_f32 v[60:61], v[46:47], v[20:21], v[60:61]
	v_pk_fma_f32 v[44:45], v[46:47], v[28:29], v[44:45]
	v_add_f32_e32 v60, v60, v61
	v_add_f32_e32 v44, v44, v45
	v_cndmask_b32_e64 v45, v66, v62, s[0:1]
	v_cndmask_b32_e64 v46, v63, v60, s[0:1]
	s_waitcnt lgkmcnt(0)
	v_add_f32_e32 v45, v45, v53
	ds_bpermute_b32 v46, v125, v46
	v_cndmask_b32_e64 v53, v64, v52, s[0:1]
	v_cndmask_b32_e64 v54, v65, v44, s[0:1]
	ds_bpermute_b32 v53, v125, v53
	ds_bpermute_b32 v54, v125, v54
	v_cndmask_b32_e64 v47, v60, v63, s[0:1]
	s_waitcnt lgkmcnt(2)
	v_add_f32_e32 v46, v47, v46
	v_cndmask_b32_e64 v47, v52, v64, s[0:1]
	v_cndmask_b32_e64 v44, v44, v65, s[0:1]
	s_waitcnt lgkmcnt(1)
	v_add_f32_e32 v47, v47, v53
	s_waitcnt lgkmcnt(0)
	v_add_f32_e32 v44, v44, v54
	v_cndmask_b32_e64 v52, v45, v47, s[38:39]
	v_cndmask_b32_e64 v45, v47, v45, s[38:39]
	v_cndmask_b32_e64 v47, v46, v44, s[38:39]
	v_cndmask_b32_e64 v44, v44, v46, s[38:39]
	v_add_f32_dpp v45, v52, v45 row_ror:8 row_mask:0xf bank_mask:0xf bound_ctrl:1
	s_nop 0
	v_add_f32_dpp v44, v47, v44 row_ror:8 row_mask:0xf bank_mask:0xf bound_ctrl:1
	v_cndmask_b32_e64 v46, v45, v44, s[42:43]
	v_cndmask_b32_e64 v44, v44, v45, s[42:43]
	v_mov_b32_e32 v45, v35
	v_mov_b32_e32 v47, v35
	s_nop 0
	v_mov_b32_dpp v45, v46 row_ror:4 row_mask:0xf bank_mask:0xf
	v_mov_b32_dpp v47, v46 row_ror:12 row_mask:0xf bank_mask:0xf
	v_cndmask_b32_e64 v45, v45, v47, s[42:43]
	v_add_f32_e32 v44, v44, v45
	v_mov_b32_e32 v45, 0
	s_nop 0
	v_add_f32_dpp v44, v44, v44 quad_perm:[2,3,0,1] row_mask:0xf bank_mask:0xf bound_ctrl:1
	s_nop 1
	v_mov_b32_dpp v45, v44 quad_perm:[1,0,3,2] row_mask:0xf bank_mask:0xf
	s_and_saveexec_b64 s[2:3], s[44:45]
	s_cbranch_execz .LBB0_1161
; #define DEC_LOADK(dst, i0) do { asm volatile("" ::: "memory"); _Pragma("unroll") for (int u = 0; u < 4; ++u) { const float* kr = ck + rbase + (size_t)((i0) + u) * 512; dst[u][0] = __builtin_nontemporal_load((const f32x4*)(kr + 4 * lane)); dst[u][1] = __builtin_nontemporal_load((const f32x4*)(kr + 256 + 4 * lane)); } } while (0)
; __device__ __forceinline__ void decode_item(Frame& F, const Args& a, int l, int item, unsigned char* ws) {
;     ...
;         DEC_LOADK(ka, 0); DEC_LOADK(kb, 4); DEC_SCORE(ka, 0); DEC_LOADK(ka, 8); DEC_SCORE(kb, 4); DEC_LOADK(kb, 12); DEC_SCORE(ka, 8); DEC_LOADK(ka, 16); DEC_SCORE(kb, 12); DEC_LOADK(kb, 20); DEC_SCORE(ka, 16); DEC_LOADK(ka, 24); DEC_SCORE(kb, 20); DEC_LOADK(kb, 28); DEC_SCORE(ka, 24); DEC_SCORE(kb, 28);
	v_add_f32_e32 v44, v44, v45
	v_add_f32_e32 v44, v34, v44
	v_exp_f32_e32 v44, v44
	v_add_u32_e32 v46, 64, v126
	v_add_f32_e32 v45, 1.0, v44
	v_rcp_f32_e32 v45, v45
	s_nop 0
	v_mul_f32_e32 v44, v44, v45
	ds_write2st64_b32 v46, v45, v44 offset0:1 offset1:65
.LBB0_1161:
	s_or_b64 exec, exec, s[2:3]
	s_waitcnt vmcnt(35)
	v_pk_mul_f32 v[44:45], v[6:7], v[56:57]
	s_nop 0
	v_pk_fma_f32 v[44:45], v[58:59], v[8:9], v[44:45]
	s_nop 0
	v_add_f32_e32 v46, v44, v45
	s_waitcnt vmcnt(34)
	v_pk_mul_f32 v[44:45], v[2:3], v[48:49]
	s_nop 0
	v_pk_fma_f32 v[44:45], v[50:51], v[4:5], v[44:45]
	s_nop 0
	v_add_f32_e32 v47, v44, v45
	v_pk_mul_f32 v[44:45], v[14:15], v[56:57]
	s_nop 0
	v_pk_fma_f32 v[44:45], v[58:59], v[16:17], v[44:45]
	s_nop 0
	v_add_f32_e32 v52, v44, v45
	v_pk_mul_f32 v[44:45], v[10:11], v[48:49]
	s_nop 0
	v_pk_fma_f32 v[44:45], v[50:51], v[12:13], v[44:45]
	s_nop 0
	v_add_f32_e32 v53, v44, v45
	v_pk_mul_f32 v[44:45], v[22:23], v[56:57]
	s_nop 0
	v_pk_fma_f32 v[44:45], v[58:59], v[24:25], v[44:45]
	s_nop 0
	v_add_f32_e32 v54, v44, v45
	v_pk_mul_f32 v[44:45], v[18:19], v[48:49]
	s_nop 0
	v_pk_fma_f32 v[44:45], v[50:51], v[20:21], v[44:45]
	s_nop 0
	v_add_f32_e32 v55, v44, v45
	v_pk_mul_f32 v[44:45], v[30:31], v[56:57]
	s_nop 0
	v_pk_fma_f32 v[44:45], v[58:59], v[32:33], v[44:45]
	s_nop 0
	v_add_f32_e32 v56, v44, v45
	v_cndmask_b32_e64 v44, v46, v54, s[0:1]
	ds_bpermute_b32 v57, v125, v44
	v_pk_mul_f32 v[44:45], v[26:27], v[48:49]
	v_cndmask_b32_e64 v48, v52, v56, s[0:1]
	v_pk_fma_f32 v[44:45], v[50:51], v[28:29], v[44:45]
	ds_bpermute_b32 v48, v125, v48
	v_add_f32_e32 v44, v44, v45
	v_cndmask_b32_e64 v45, v54, v46, s[0:1]
	v_cndmask_b32_e64 v46, v47, v55, s[0:1]
	ds_bpermute_b32 v46, v125, v46
	v_cndmask_b32_e64 v49, v53, v44, s[0:1]
	ds_bpermute_b32 v49, v125, v49
	v_cndmask_b32_e64 v47, v55, v47, s[0:1]
	v_cndmask_b32_e64 v44, v44, v53, s[0:1]
	s_waitcnt lgkmcnt(1)
	v_add_f32_e32 v46, v47, v46
	v_cndmask_b32_e64 v47, v56, v52, s[0:1]
	v_add_f32_e32 v45, v45, v57
	v_add_f32_e32 v47, v47, v48
	s_waitcnt lgkmcnt(0)
	v_add_f32_e32 v44, v44, v49
	v_cndmask_b32_e64 v48, v45, v47, s[38:39]
	v_cndmask_b32_e64 v45, v47, v45, s[38:39]
	v_cndmask_b32_e64 v47, v46, v44, s[38:39]
	v_cndmask_b32_e64 v44, v44, v46, s[38:39]
	v_add_f32_dpp v45, v48, v45 row_ror:8 row_mask:0xf bank_mask:0xf bound_ctrl:1
	s_nop 0
	v_add_f32_dpp v44, v47, v44 row_ror:8 row_mask:0xf bank_mask:0xf bound_ctrl:1
	v_cndmask_b32_e64 v46, v45, v44, s[42:43]
	v_cndmask_b32_e64 v44, v44, v45, s[42:43]
	v_mov_b32_e32 v45, v35
	v_mov_b32_e32 v47, v35
	s_nop 0
	v_mov_b32_dpp v45, v46 row_ror:4 row_mask:0xf bank_mask:0xf
	v_mov_b32_dpp v47, v46 row_ror:12 row_mask:0xf bank_mask:0xf
	v_cndmask_b32_e64 v45, v45, v47, s[42:43]
	v_add_f32_e32 v44, v44, v45
	v_mov_b32_e32 v45, 0
	s_nop 0
	v_add_f32_dpp v44, v44, v44 quad_perm:[2,3,0,1] row_mask:0xf bank_mask:0xf bound_ctrl:1
	s_nop 1
	v_mov_b32_dpp v45, v44 quad_perm:[1,0,3,2] row_mask:0xf bank_mask:0xf
	s_and_saveexec_b64 s[2:3], s[44:45]
	s_cbranch_execz .LBB0_1163
	v_add_f32_e32 v44, v44, v45
	v_add_f32_e32 v44, v34, v44
	v_exp_f32_e32 v44, v44
	v_add_u32_e32 v46, 0x80, v126
	v_add_f32_e32 v45, 1.0, v44
	v_rcp_f32_e32 v45, v45
	s_nop 0
	v_mul_f32_e32 v44, v44, v45
	ds_write2st64_b32 v46, v45, v44 offset0:1 offset1:65
.LBB0_1163:
	s_or_b64 exec, exec, s[2:3]
	s_waitcnt vmcnt(33)
	v_pk_mul_f32 v[44:45], v[6:7], v[40:41]
	s_nop 0
	v_pk_fma_f32 v[44:45], v[42:43], v[8:9], v[44:45]
	s_nop 0
	v_add_f32_e32 v46, v44, v45
	s_waitcnt vmcnt(32)
	v_pk_mul_f32 v[44:45], v[2:3], v[36:37]
	s_nop 0
	v_pk_fma_f32 v[44:45], v[38:39], v[4:5], v[44:45]
	s_nop 0
	v_add_f32_e32 v47, v44, v45
	v_pk_mul_f32 v[44:45], v[14:15], v[40:41]
	s_nop 0
	v_pk_fma_f32 v[44:45], v[42:43], v[16:17], v[44:45]
	s_nop 0
	v_add_f32_e32 v48, v44, v45
	v_pk_mul_f32 v[44:45], v[10:11], v[36:37]
	s_nop 0
	v_pk_fma_f32 v[44:45], v[38:39], v[12:13], v[44:45]
	s_nop 0
	v_add_f32_e32 v49, v44, v45
	v_pk_mul_f32 v[44:45], v[22:23], v[40:41]
	v_pk_mul_f32 v[40:41], v[30:31], v[40:41]
	v_pk_fma_f32 v[44:45], v[42:43], v[24:25], v[44:45]
	v_pk_fma_f32 v[40:41], v[42:43], v[32:33], v[40:41]
	v_add_f32_e32 v50, v44, v45
	v_add_f32_e32 v40, v40, v41
	v_cndmask_b32_e64 v41, v46, v50, s[0:1]
	ds_bpermute_b32 v41, v125, v41
	v_pk_mul_f32 v[44:45], v[18:19], v[36:37]
	v_pk_mul_f32 v[36:37], v[26:27], v[36:37]
	v_pk_fma_f32 v[44:45], v[38:39], v[20:21], v[44:45]
	v_pk_fma_f32 v[36:37], v[38:39], v[28:29], v[36:37]
	v_add_f32_e32 v44, v44, v45
	v_add_f32_e32 v36, v36, v37
	v_cndmask_b32_e64 v37, v50, v46, s[0:1]
	v_cndmask_b32_e64 v38, v47, v44, s[0:1]
	s_waitcnt lgkmcnt(0)
	v_add_f32_e32 v37, v37, v41
	ds_bpermute_b32 v38, v125, v38
	v_cndmask_b32_e64 v41, v48, v40, s[0:1]
	v_cndmask_b32_e64 v42, v49, v36, s[0:1]
	ds_bpermute_b32 v41, v125, v41
	ds_bpermute_b32 v42, v125, v42
	v_cndmask_b32_e64 v39, v44, v47, s[0:1]
	s_waitcnt lgkmcnt(2)
	v_add_f32_e32 v38, v39, v38
	v_cndmask_b32_e64 v39, v40, v48, s[0:1]
	v_cndmask_b32_e64 v36, v36, v49, s[0:1]
	s_waitcnt lgkmcnt(1)
	v_add_f32_e32 v39, v39, v41
	s_waitcnt lgkmcnt(0)
	v_add_f32_e32 v36, v36, v42
	v_cndmask_b32_e64 v40, v37, v39, s[38:39]
	v_cndmask_b32_e64 v37, v39, v37, s[38:39]
	v_cndmask_b32_e64 v39, v38, v36, s[38:39]
	v_cndmask_b32_e64 v36, v36, v38, s[38:39]
	v_add_f32_dpp v37, v40, v37 row_ror:8 row_mask:0xf bank_mask:0xf bound_ctrl:1
	s_nop 0
	v_add_f32_dpp v36, v39, v36 row_ror:8 row_mask:0xf bank_mask:0xf bound_ctrl:1
	v_cndmask_b32_e64 v38, v37, v36, s[42:43]
	v_cndmask_b32_e64 v36, v36, v37, s[42:43]
	v_mov_b32_e32 v37, v35
	v_mov_b32_e32 v39, v35
	s_nop 0
	v_mov_b32_dpp v37, v38 row_ror:4 row_mask:0xf bank_mask:0xf
	v_mov_b32_dpp v39, v38 row_ror:12 row_mask:0xf bank_mask:0xf
	v_cndmask_b32_e64 v37, v37, v39, s[42:43]
	v_add_f32_e32 v36, v36, v37
	v_mov_b32_e32 v37, 0
	s_nop 0
	v_add_f32_dpp v36, v36, v36 quad_perm:[2,3,0,1] row_mask:0xf bank_mask:0xf bound_ctrl:1
	s_nop 1
	v_mov_b32_dpp v37, v36 quad_perm:[1,0,3,2] row_mask:0xf bank_mask:0xf
	s_and_saveexec_b64 s[2:3], s[44:45]
	s_cbranch_execz .LBB0_1165
	v_add_f32_e32 v36, v36, v37
	v_add_f32_e32 v36, v34, v36
	v_exp_f32_e32 v36, v36
	v_add_u32_e32 v38, 0xc0, v126
	v_add_f32_e32 v37, 1.0, v36
	v_rcp_f32_e32 v37, v37
	s_nop 0
	v_mul_f32_e32 v36, v36, v37
	ds_write2st64_b32 v38, v37, v36 offset0:1 offset1:65
; #define DEC_LOADK(dst, i0) do { asm volatile("" ::: "memory"); _Pragma("unroll") for (int u = 0; u < 4; ++u) { const float* kr = ck + rbase + (size_t)((i0) + u) * 512; dst[u][0] = __builtin_nontemporal_load((const f32x4*)(kr + 4 * lane)); dst[u][1] = __builtin_nontemporal_load((const f32x4*)(kr + 256 + 4 * lane)); } } while (0)
; __device__ __forceinline__ void decode_item(Frame& F, const Args& a, int l, int item, unsigned char* ws) {
;     ...
;         DEC_LOADK(ka, 0); DEC_LOADK(kb, 4); DEC_SCORE(ka, 0); DEC_LOADK(ka, 8); DEC_SCORE(kb, 4); DEC_LOADK(kb, 12); DEC_SCORE(ka, 8); DEC_LOADK(ka, 16); DEC_SCORE(kb, 12); DEC_LOADK(kb, 20); DEC_SCORE(ka, 16); DEC_LOADK(ka, 24); DEC_SCORE(kb, 20); DEC_LOADK(kb, 28); DEC_SCORE(ka, 24); DEC_SCORE(kb, 28);
.LBB0_1165:
	s_or_b64 exec, exec, s[2:3]
	v_add_co_u32_e32 v36, vcc, 0x6000, v120
	s_waitcnt vmcnt(15)
	v_pk_mul_f32 v[40:41], v[6:7], v[112:113]
	v_addc_co_u32_e32 v37, vcc, 0, v121, vcc
	global_load_dwordx4 v[108:111], v[36:37], off nt
	global_load_dwordx4 v[100:103], v[36:37], off offset:1024 nt
	global_load_dwordx4 v[92:95], v[36:37], off offset:2048 nt
	global_load_dwordx4 v[84:87], v[36:37], off offset:3072 nt
	v_add_co_u32_e32 v36, vcc, 0x7000, v120
	v_pk_fma_f32 v[40:41], v[114:115], v[8:9], v[40:41]
	s_nop 0
	v_addc_co_u32_e32 v37, vcc, 0, v121, vcc
	global_load_dwordx4 v[60:63], v[36:37], off nt
	global_load_dwordx4 v[52:55], v[36:37], off offset:1024 nt
	global_load_dwordx4 v[44:47], v[36:37], off offset:2048 nt
	s_nop 0
	global_load_dwordx4 v[36:39], v[36:37], off offset:3072 nt
	global_load_dwordx4 v[204:207], v[190:191], off offset:-4096
	global_load_dwordx4 v[204:207], v[190:191], off offset:-3072
	global_load_dwordx4 v[204:207], v[190:191], off offset:-2048
	global_load_dwordx4 v[204:207], v[190:191], off offset:-1024
	global_load_dwordx4 v[204:207], v[190:191], off
	global_load_dwordx4 v[204:207], v[190:191], off offset:1024
	global_load_dwordx4 v[204:207], v[190:191], off offset:2048
	global_load_dwordx4 v[204:207], v[190:191], off offset:3072
	v_add_f32_e32 v42, v40, v41
	s_waitcnt vmcnt(30)
	v_pk_mul_f32 v[40:41], v[2:3], v[104:105]
	s_nop 0
	v_pk_fma_f32 v[40:41], v[106:107], v[4:5], v[40:41]
	s_nop 0
	v_add_f32_e32 v43, v40, v41
	v_pk_mul_f32 v[40:41], v[14:15], v[112:113]
	s_nop 0
	v_pk_fma_f32 v[40:41], v[114:115], v[16:17], v[40:41]
	s_nop 0
	v_add_f32_e32 v48, v40, v41
	v_pk_mul_f32 v[40:41], v[10:11], v[104:105]
	s_nop 0
	v_pk_fma_f32 v[40:41], v[106:107], v[12:13], v[40:41]
	s_nop 0
	v_add_f32_e32 v49, v40, v41
	v_pk_mul_f32 v[40:41], v[22:23], v[112:113]
	s_nop 0
	v_pk_fma_f32 v[40:41], v[114:115], v[24:25], v[40:41]
	s_nop 0
	v_add_f32_e32 v50, v40, v41
	v_pk_mul_f32 v[40:41], v[18:19], v[104:105]
	s_nop 0
	v_pk_fma_f32 v[40:41], v[106:107], v[20:21], v[40:41]
	s_nop 0
	v_add_f32_e32 v51, v40, v41
	v_pk_mul_f32 v[40:41], v[30:31], v[112:113]
	s_nop 0
	v_pk_fma_f32 v[40:41], v[114:115], v[32:33], v[40:41]
	s_nop 0
	v_add_f32_e32 v56, v40, v41
	v_cndmask_b32_e64 v40, v42, v50, s[0:1]
	ds_bpermute_b32 v57, v125, v40
	v_pk_mul_f32 v[40:41], v[26:27], v[104:105]
	s_nop 0
	v_pk_fma_f32 v[40:41], v[106:107], v[28:29], v[40:41]
	s_nop 0
	v_add_f32_e32 v40, v40, v41
	v_cndmask_b32_e64 v41, v50, v42, s[0:1]
	v_cndmask_b32_e64 v42, v43, v51, s[0:1]
	v_cndmask_b32_e64 v43, v51, v43, s[0:1]
	ds_bpermute_b32 v42, v125, v42
	v_cndmask_b32_e64 v50, v48, v56, s[0:1]
	v_cndmask_b32_e64 v51, v49, v40, s[0:1]
	ds_bpermute_b32 v50, v125, v50
	ds_bpermute_b32 v51, v125, v51
	s_waitcnt lgkmcnt(2)
	v_add_f32_e32 v42, v43, v42
	v_cndmask_b32_e64 v43, v56, v48, s[0:1]
	v_cndmask_b32_e64 v40, v40, v49, s[0:1]
	v_add_f32_e32 v41, v41, v57
	s_waitcnt lgkmcnt(1)
	v_add_f32_e32 v43, v43, v50
	s_waitcnt lgkmcnt(0)
	v_add_f32_e32 v40, v40, v51
	v_cndmask_b32_e64 v48, v41, v43, s[38:39]
	v_cndmask_b32_e64 v41, v43, v41, s[38:39]
	v_cndmask_b32_e64 v43, v42, v40, s[38:39]
	v_cndmask_b32_e64 v40, v40, v42, s[38:39]
	v_add_f32_dpp v41, v48, v41 row_ror:8 row_mask:0xf bank_mask:0xf bound_ctrl:1
	s_nop 0
	v_add_f32_dpp v40, v43, v40 row_ror:8 row_mask:0xf bank_mask:0xf bound_ctrl:1
	v_cndmask_b32_e64 v42, v41, v40, s[42:43]
	v_cndmask_b32_e64 v40, v40, v41, s[42:43]
	v_mov_b32_e32 v41, v35
	v_mov_b32_e32 v43, v35
	s_nop 0
	v_mov_b32_dpp v41, v42 row_ror:4 row_mask:0xf bank_mask:0xf
	v_mov_b32_dpp v43, v42 row_ror:12 row_mask:0xf bank_mask:0xf
	v_cndmask_b32_e64 v41, v41, v43, s[42:43]
	v_add_f32_e32 v40, v40, v41
	v_mov_b32_e32 v41, 0
	s_nop 0
	v_add_f32_dpp v40, v40, v40 quad_perm:[2,3,0,1] row_mask:0xf bank_mask:0xf bound_ctrl:1
	s_nop 1
	v_mov_b32_dpp v41, v40 quad_perm:[1,0,3,2] row_mask:0xf bank_mask:0xf
	s_and_saveexec_b64 s[2:3], s[44:45]
	s_cbranch_execz .LBB0_1167
	v_add_f32_e32 v40, v40, v41
	v_add_f32_e32 v40, v34, v40
	v_exp_f32_e32 v40, v40
	s_nop 0
	v_add_f32_e32 v41, 1.0, v40
	v_rcp_f32_e32 v41, v41
	s_nop 0
	v_mul_f32_e32 v40, v40, v41
	ds_write2st64_b32 v126, v41, v40 offset0:2 offset1:66
.LBB0_1167:
	s_or_b64 exec, exec, s[2:3]
	s_waitcnt vmcnt(29)
	v_pk_mul_f32 v[40:41], v[6:7], v[96:97]
	s_nop 0
	v_pk_fma_f32 v[40:41], v[98:99], v[8:9], v[40:41]
	s_nop 0
	v_add_f32_e32 v42, v40, v41
	s_waitcnt vmcnt(28)
	v_pk_mul_f32 v[40:41], v[2:3], v[88:89]
	s_nop 0
	v_pk_fma_f32 v[40:41], v[90:91], v[4:5], v[40:41]
	s_nop 0
	v_add_f32_e32 v43, v40, v41
	v_pk_mul_f32 v[40:41], v[14:15], v[96:97]
	s_nop 0
	v_pk_fma_f32 v[40:41], v[98:99], v[16:17], v[40:41]
	s_nop 0
	v_add_f32_e32 v48, v40, v41
	v_pk_mul_f32 v[40:41], v[10:11], v[88:89]
	s_nop 0
	v_pk_fma_f32 v[40:41], v[90:91], v[12:13], v[40:41]
	s_nop 0
	v_add_f32_e32 v49, v40, v41
	v_pk_mul_f32 v[40:41], v[22:23], v[96:97]
	s_nop 0
	v_pk_fma_f32 v[40:41], v[98:99], v[24:25], v[40:41]
	s_nop 0
	v_add_f32_e32 v50, v40, v41
	v_pk_mul_f32 v[40:41], v[18:19], v[88:89]
	s_nop 0
	v_pk_fma_f32 v[40:41], v[90:91], v[20:21], v[40:41]
	s_nop 0
	v_add_f32_e32 v51, v40, v41
	v_pk_mul_f32 v[40:41], v[30:31], v[96:97]
	s_nop 0
	v_pk_fma_f32 v[40:41], v[98:99], v[32:33], v[40:41]
	s_nop 0
	v_add_f32_e32 v56, v40, v41
	v_cndmask_b32_e64 v40, v42, v50, s[0:1]
	ds_bpermute_b32 v57, v125, v40
	v_pk_mul_f32 v[40:41], v[26:27], v[88:89]
	s_nop 0
	v_pk_fma_f32 v[40:41], v[90:91], v[28:29], v[40:41]
	s_nop 0
	v_add_f32_e32 v40, v40, v41
	v_cndmask_b32_e64 v41, v50, v42, s[0:1]
	v_cndmask_b32_e64 v42, v43, v51, s[0:1]
	v_cndmask_b32_e64 v43, v51, v43, s[0:1]
	ds_bpermute_b32 v42, v125, v42
	v_cndmask_b32_e64 v50, v48, v56, s[0:1]
	v_cndmask_b32_e64 v51, v49, v40, s[0:1]
	ds_bpermute_b32 v50, v125, v50
	ds_bpermute_b32 v51, v125, v51
	s_waitcnt lgkmcnt(2)
	v_add_f32_e32 v42, v43, v42
	v_cndmask_b32_e64 v43, v56, v48, s[0:1]
	v_cndmask_b32_e64 v40, v40, v49, s[0:1]
	v_add_f32_e32 v41, v41, v57
	s_waitcnt lgkmcnt(1)
	v_add_f32_e32 v43, v43, v50
	s_waitcnt lgkmcnt(0)
	v_add_f32_e32 v40, v40, v51
	v_cndmask_b32_e64 v48, v41, v43, s[38:39]
	v_cndmask_b32_e64 v41, v43, v41, s[38:39]
	v_cndmask_b32_e64 v43, v42, v40, s[38:39]
	v_cndmask_b32_e64 v40, v40, v42, s[38:39]
	v_add_f32_dpp v41, v48, v41 row_ror:8 row_mask:0xf bank_mask:0xf bound_ctrl:1
	s_nop 0
	v_add_f32_dpp v40, v43, v40 row_ror:8 row_mask:0xf bank_mask:0xf bound_ctrl:1
	v_cndmask_b32_e64 v42, v41, v40, s[42:43]
	v_cndmask_b32_e64 v40, v40, v41, s[42:43]
	v_mov_b32_e32 v41, v35
	v_mov_b32_e32 v43, v35
	s_nop 0
	v_mov_b32_dpp v41, v42 row_ror:4 row_mask:0xf bank_mask:0xf
	v_mov_b32_dpp v43, v42 row_ror:12 row_mask:0xf bank_mask:0xf
	v_cndmask_b32_e64 v41, v41, v43, s[42:43]
	v_add_f32_e32 v40, v40, v41
	v_mov_b32_e32 v41, 0
	s_nop 0
	v_add_f32_dpp v40, v40, v40 quad_perm:[2,3,0,1] row_mask:0xf bank_mask:0xf bound_ctrl:1
	s_nop 1
	v_mov_b32_dpp v41, v40 quad_perm:[1,0,3,2] row_mask:0xf bank_mask:0xf
	s_and_saveexec_b64 s[2:3], s[44:45]
	s_cbranch_execz .LBB0_1169
; #define DEC_LOADK(dst, i0) do { asm volatile("" ::: "memory"); _Pragma("unroll") for (int u = 0; u < 4; ++u) { const float* kr = ck + rbase + (size_t)((i0) + u) * 512; dst[u][0] = __builtin_nontemporal_load((const f32x4*)(kr + 4 * lane)); dst[u][1] = __builtin_nontemporal_load((const f32x4*)(kr + 256 + 4 * lane)); } } while (0)
; __device__ __forceinline__ void decode_item(Frame& F, const Args& a, int l, int item, unsigned char* ws) {
;     ...
;         DEC_LOADK(ka, 0); DEC_LOADK(kb, 4); DEC_SCORE(ka, 0); DEC_LOADK(ka, 8); DEC_SCORE(kb, 4); DEC_LOADK(kb, 12); DEC_SCORE(ka, 8); DEC_LOADK(ka, 16); DEC_SCORE(kb, 12); DEC_LOADK(kb, 20); DEC_SCORE(ka, 16); DEC_LOADK(ka, 24); DEC_SCORE(kb, 20); DEC_LOADK(kb, 28); DEC_SCORE(ka, 24); DEC_SCORE(kb, 28);
	v_add_f32_e32 v40, v40, v41
	v_add_f32_e32 v40, v34, v40
	v_exp_f32_e32 v40, v40
	v_add_u32_e32 v42, 64, v126
	v_add_f32_e32 v41, 1.0, v40
	v_rcp_f32_e32 v41, v41
	s_nop 0
	v_mul_f32_e32 v40, v40, v41
	ds_write2st64_b32 v42, v41, v40 offset0:2 offset1:66
.LBB0_1169:
	s_or_b64 exec, exec, s[2:3]
	s_waitcnt vmcnt(27)
	v_pk_mul_f32 v[40:41], v[6:7], v[80:81]
	s_nop 0
	v_pk_fma_f32 v[40:41], v[82:83], v[8:9], v[40:41]
	s_nop 0
	v_add_f32_e32 v42, v40, v41
	s_waitcnt vmcnt(26)
	v_pk_mul_f32 v[40:41], v[2:3], v[76:77]
	s_nop 0
	v_pk_fma_f32 v[40:41], v[78:79], v[4:5], v[40:41]
	s_nop 0
	v_add_f32_e32 v43, v40, v41
	v_pk_mul_f32 v[40:41], v[14:15], v[80:81]
	s_nop 0
	v_pk_fma_f32 v[40:41], v[82:83], v[16:17], v[40:41]
	s_nop 0
	v_add_f32_e32 v48, v40, v41
	v_pk_mul_f32 v[40:41], v[10:11], v[76:77]
	s_nop 0
	v_pk_fma_f32 v[40:41], v[78:79], v[12:13], v[40:41]
	s_nop 0
	v_add_f32_e32 v49, v40, v41
	v_pk_mul_f32 v[40:41], v[22:23], v[80:81]
	s_nop 0
	v_pk_fma_f32 v[40:41], v[82:83], v[24:25], v[40:41]
	s_nop 0
	v_add_f32_e32 v50, v40, v41
	v_pk_mul_f32 v[40:41], v[18:19], v[76:77]
	s_nop 0
	v_pk_fma_f32 v[40:41], v[78:79], v[20:21], v[40:41]
	s_nop 0
	v_add_f32_e32 v51, v40, v41
	v_pk_mul_f32 v[40:41], v[30:31], v[80:81]
	s_nop 0
	v_pk_fma_f32 v[40:41], v[82:83], v[32:33], v[40:41]
	s_nop 0
	v_add_f32_e32 v56, v40, v41
	v_cndmask_b32_e64 v40, v42, v50, s[0:1]
	ds_bpermute_b32 v57, v125, v40
	v_pk_mul_f32 v[40:41], v[26:27], v[76:77]
	s_nop 0
	v_pk_fma_f32 v[40:41], v[78:79], v[28:29], v[40:41]
	s_nop 0
	v_add_f32_e32 v40, v40, v41
	v_cndmask_b32_e64 v41, v50, v42, s[0:1]
	v_cndmask_b32_e64 v42, v43, v51, s[0:1]
	v_cndmask_b32_e64 v43, v51, v43, s[0:1]
	ds_bpermute_b32 v42, v125, v42
	v_cndmask_b32_e64 v50, v48, v56, s[0:1]
	v_cndmask_b32_e64 v51, v49, v40, s[0:1]
	ds_bpermute_b32 v50, v125, v50
	ds_bpermute_b32 v51, v125, v51
	s_waitcnt lgkmcnt(2)
	v_add_f32_e32 v42, v43, v42
	v_cndmask_b32_e64 v43, v56, v48, s[0:1]
	v_cndmask_b32_e64 v40, v40, v49, s[0:1]
	v_add_f32_e32 v41, v41, v57
	s_waitcnt lgkmcnt(1)
	v_add_f32_e32 v43, v43, v50
	s_waitcnt lgkmcnt(0)
	v_add_f32_e32 v40, v40, v51
	v_cndmask_b32_e64 v48, v41, v43, s[38:39]
	v_cndmask_b32_e64 v41, v43, v41, s[38:39]
	v_cndmask_b32_e64 v43, v42, v40, s[38:39]
	v_cndmask_b32_e64 v40, v40, v42, s[38:39]
	v_add_f32_dpp v41, v48, v41 row_ror:8 row_mask:0xf bank_mask:0xf bound_ctrl:1
	s_nop 0
	v_add_f32_dpp v40, v43, v40 row_ror:8 row_mask:0xf bank_mask:0xf bound_ctrl:1
	v_cndmask_b32_e64 v42, v41, v40, s[42:43]
	v_cndmask_b32_e64 v40, v40, v41, s[42:43]
	v_mov_b32_e32 v41, v35
	v_mov_b32_e32 v43, v35
	s_nop 0
	v_mov_b32_dpp v41, v42 row_ror:4 row_mask:0xf bank_mask:0xf
	v_mov_b32_dpp v43, v42 row_ror:12 row_mask:0xf bank_mask:0xf
	v_cndmask_b32_e64 v41, v41, v43, s[42:43]
	v_add_f32_e32 v40, v40, v41
	v_mov_b32_e32 v41, 0
	s_nop 0
	v_add_f32_dpp v40, v40, v40 quad_perm:[2,3,0,1] row_mask:0xf bank_mask:0xf bound_ctrl:1
	s_nop 1
	v_mov_b32_dpp v41, v40 quad_perm:[1,0,3,2] row_mask:0xf bank_mask:0xf
	s_and_saveexec_b64 s[2:3], s[44:45]
	s_cbranch_execz .LBB0_1171
	v_add_f32_e32 v40, v40, v41
	v_add_f32_e32 v40, v34, v40
	v_exp_f32_e32 v40, v40
	v_add_u32_e32 v42, 0x80, v126
	v_add_f32_e32 v41, 1.0, v40
	v_rcp_f32_e32 v41, v41
	s_nop 0
	v_mul_f32_e32 v40, v40, v41
	ds_write2st64_b32 v42, v41, v40 offset0:2 offset1:66
.LBB0_1171:
	s_or_b64 exec, exec, s[2:3]
	s_waitcnt vmcnt(25)
	v_pk_mul_f32 v[40:41], v[6:7], v[72:73]
	s_nop 0
	v_pk_fma_f32 v[40:41], v[74:75], v[8:9], v[40:41]
	s_nop 0
	v_add_f32_e32 v42, v40, v41
	s_waitcnt vmcnt(24)
	v_pk_mul_f32 v[40:41], v[2:3], v[68:69]
	s_nop 0
	v_pk_fma_f32 v[40:41], v[70:71], v[4:5], v[40:41]
	s_nop 0
	v_add_f32_e32 v43, v40, v41
	v_pk_mul_f32 v[40:41], v[14:15], v[72:73]
	s_nop 0
	v_pk_fma_f32 v[40:41], v[74:75], v[16:17], v[40:41]
	s_nop 0
	v_add_f32_e32 v48, v40, v41
	v_pk_mul_f32 v[40:41], v[10:11], v[68:69]
	s_nop 0
	v_pk_fma_f32 v[40:41], v[70:71], v[12:13], v[40:41]
	s_nop 0
	v_add_f32_e32 v49, v40, v41
	v_pk_mul_f32 v[40:41], v[22:23], v[72:73]
	s_nop 0
	v_pk_fma_f32 v[40:41], v[74:75], v[24:25], v[40:41]
	s_nop 0
	v_add_f32_e32 v50, v40, v41
	v_pk_mul_f32 v[40:41], v[18:19], v[68:69]
	s_nop 0
	v_pk_fma_f32 v[40:41], v[70:71], v[20:21], v[40:41]
	s_nop 0
	v_add_f32_e32 v51, v40, v41
	v_pk_mul_f32 v[40:41], v[30:31], v[72:73]
	s_nop 0
	v_pk_fma_f32 v[40:41], v[74:75], v[32:33], v[40:41]
	s_nop 0
	v_add_f32_e32 v56, v40, v41
	v_cndmask_b32_e64 v40, v42, v50, s[0:1]
	ds_bpermute_b32 v57, v125, v40
	v_pk_mul_f32 v[40:41], v[26:27], v[68:69]
	s_nop 0
	v_pk_fma_f32 v[40:41], v[70:71], v[28:29], v[40:41]
	s_nop 0
	v_add_f32_e32 v40, v40, v41
	v_cndmask_b32_e64 v41, v50, v42, s[0:1]
	v_cndmask_b32_e64 v42, v43, v51, s[0:1]
	v_cndmask_b32_e64 v43, v51, v43, s[0:1]
	ds_bpermute_b32 v42, v125, v42
	v_cndmask_b32_e64 v50, v48, v56, s[0:1]
	v_cndmask_b32_e64 v51, v49, v40, s[0:1]
	ds_bpermute_b32 v50, v125, v50
	ds_bpermute_b32 v51, v125, v51
	s_waitcnt lgkmcnt(2)
	v_add_f32_e32 v42, v43, v42
	v_cndmask_b32_e64 v43, v56, v48, s[0:1]
	v_cndmask_b32_e64 v40, v40, v49, s[0:1]
	v_add_f32_e32 v41, v41, v57
	s_waitcnt lgkmcnt(1)
	v_add_f32_e32 v43, v43, v50
	s_waitcnt lgkmcnt(0)
	v_add_f32_e32 v40, v40, v51
	v_cndmask_b32_e64 v48, v41, v43, s[38:39]
	v_cndmask_b32_e64 v41, v43, v41, s[38:39]
	v_cndmask_b32_e64 v43, v42, v40, s[38:39]
	v_cndmask_b32_e64 v40, v40, v42, s[38:39]
	v_add_f32_dpp v41, v48, v41 row_ror:8 row_mask:0xf bank_mask:0xf bound_ctrl:1
	s_nop 0
	v_add_f32_dpp v40, v43, v40 row_ror:8 row_mask:0xf bank_mask:0xf bound_ctrl:1
	v_cndmask_b32_e64 v42, v41, v40, s[42:43]
	v_cndmask_b32_e64 v40, v40, v41, s[42:43]
	v_mov_b32_e32 v41, v35
	v_mov_b32_e32 v43, v35
	s_nop 0
	v_mov_b32_dpp v41, v42 row_ror:4 row_mask:0xf bank_mask:0xf
	v_mov_b32_dpp v43, v42 row_ror:12 row_mask:0xf bank_mask:0xf
	v_cndmask_b32_e64 v41, v41, v43, s[42:43]
	v_add_f32_e32 v40, v40, v41
	v_mov_b32_e32 v41, 0
	s_nop 0
	v_add_f32_dpp v40, v40, v40 quad_perm:[2,3,0,1] row_mask:0xf bank_mask:0xf bound_ctrl:1
	s_nop 1
	v_mov_b32_dpp v41, v40 quad_perm:[1,0,3,2] row_mask:0xf bank_mask:0xf
	s_and_saveexec_b64 s[2:3], s[44:45]
	s_cbranch_execz .LBB0_1173
	v_add_f32_e32 v40, v40, v41
	v_add_f32_e32 v40, v34, v40
	v_exp_f32_e32 v40, v40
	v_add_u32_e32 v42, 0xc0, v126
	v_add_f32_e32 v41, 1.0, v40
	v_rcp_f32_e32 v41, v41
	s_nop 0
	v_mul_f32_e32 v40, v40, v41
	ds_write2st64_b32 v42, v41, v40 offset0:2 offset1:66
; #define DEC_LOADK(dst, i0) do { asm volatile("" ::: "memory"); _Pragma("unroll") for (int u = 0; u < 4; ++u) { const float* kr = ck + rbase + (size_t)((i0) + u) * 512; dst[u][0] = __builtin_nontemporal_load((const f32x4*)(kr + 4 * lane)); dst[u][1] = __builtin_nontemporal_load((const f32x4*)(kr + 256 + 4 * lane)); } } while (0)
; __device__ __forceinline__ void decode_item(Frame& F, const Args& a, int l, int item, unsigned char* ws) {
;     ...
;         DEC_LOADK(ka, 0); DEC_LOADK(kb, 4); DEC_SCORE(ka, 0); DEC_LOADK(ka, 8); DEC_SCORE(kb, 4); DEC_LOADK(kb, 12); DEC_SCORE(ka, 8); DEC_LOADK(ka, 16); DEC_SCORE(kb, 12); DEC_LOADK(kb, 20); DEC_SCORE(ka, 16); DEC_LOADK(ka, 24); DEC_SCORE(kb, 20); DEC_LOADK(kb, 28); DEC_SCORE(ka, 24); DEC_SCORE(kb, 28);
.LBB0_1173:
	s_or_b64 exec, exec, s[2:3]
	v_add_co_u32_e32 v40, vcc, 0x8000, v120
	s_waitcnt vmcnt(15)
	v_pk_mul_f32 v[72:73], v[6:7], v[108:109]
	v_addc_co_u32_e32 v41, vcc, 0, v121, vcc
	global_load_dwordx4 v[96:99], v[40:41], off nt
	global_load_dwordx4 v[88:91], v[40:41], off offset:1024 nt
	global_load_dwordx4 v[76:79], v[40:41], off offset:2048 nt
	global_load_dwordx4 v[68:71], v[40:41], off offset:3072 nt
	v_add_co_u32_e32 v40, vcc, 0x9000, v120
	v_pk_fma_f32 v[72:73], v[110:111], v[8:9], v[72:73]
	s_nop 0
	v_addc_co_u32_e32 v41, vcc, 0, v121, vcc
	global_load_dwordx4 v[64:67], v[40:41], off nt
	global_load_dwordx4 v[56:59], v[40:41], off offset:1024 nt
	global_load_dwordx4 v[48:51], v[40:41], off offset:2048 nt
	s_nop 0
	global_load_dwordx4 v[40:43], v[40:41], off offset:3072 nt
	global_load_dwordx4 v[204:207], v[192:193], off offset:-4096
	global_load_dwordx4 v[204:207], v[192:193], off offset:-3072
	global_load_dwordx4 v[204:207], v[192:193], off offset:-2048
	global_load_dwordx4 v[204:207], v[192:193], off offset:-1024
	global_load_dwordx4 v[204:207], v[192:193], off
	global_load_dwordx4 v[204:207], v[192:193], off offset:1024
	global_load_dwordx4 v[204:207], v[192:193], off offset:2048
	global_load_dwordx4 v[204:207], v[192:193], off offset:3072
	v_add_f32_e32 v74, v72, v73
	s_waitcnt vmcnt(30)
	v_pk_mul_f32 v[72:73], v[2:3], v[100:101]
	s_nop 0
	v_pk_fma_f32 v[72:73], v[102:103], v[4:5], v[72:73]
	s_nop 0
	v_add_f32_e32 v75, v72, v73
	v_pk_mul_f32 v[72:73], v[14:15], v[108:109]
	s_nop 0
	v_pk_fma_f32 v[72:73], v[110:111], v[16:17], v[72:73]
	s_nop 0
	v_add_f32_e32 v80, v72, v73
	v_pk_mul_f32 v[72:73], v[10:11], v[100:101]
	s_nop 0
	v_pk_fma_f32 v[72:73], v[102:103], v[12:13], v[72:73]
	s_nop 0
	v_add_f32_e32 v81, v72, v73
	v_pk_mul_f32 v[72:73], v[22:23], v[108:109]
	s_nop 0
	v_pk_fma_f32 v[72:73], v[110:111], v[24:25], v[72:73]
	s_nop 0
	v_add_f32_e32 v82, v72, v73
	v_pk_mul_f32 v[72:73], v[18:19], v[100:101]
	s_nop 0
	v_pk_fma_f32 v[72:73], v[102:103], v[20:21], v[72:73]
	s_nop 0
	v_add_f32_e32 v83, v72, v73
	v_pk_mul_f32 v[72:73], v[30:31], v[108:109]
	s_nop 0
	v_pk_fma_f32 v[72:73], v[110:111], v[32:33], v[72:73]
	s_nop 0
	v_add_f32_e32 v104, v72, v73
	v_cndmask_b32_e64 v72, v74, v82, s[0:1]
	ds_bpermute_b32 v105, v125, v72
	v_pk_mul_f32 v[72:73], v[26:27], v[100:101]
	s_nop 0
	v_pk_fma_f32 v[72:73], v[102:103], v[28:29], v[72:73]
	s_nop 0
	v_add_f32_e32 v72, v72, v73
	v_cndmask_b32_e64 v73, v82, v74, s[0:1]
	v_cndmask_b32_e64 v74, v75, v83, s[0:1]
	v_cndmask_b32_e64 v75, v83, v75, s[0:1]
	ds_bpermute_b32 v74, v125, v74
	v_cndmask_b32_e64 v82, v80, v104, s[0:1]
	v_cndmask_b32_e64 v83, v81, v72, s[0:1]
	ds_bpermute_b32 v82, v125, v82
	ds_bpermute_b32 v83, v125, v83
	s_waitcnt lgkmcnt(2)
	v_add_f32_e32 v74, v75, v74
	v_cndmask_b32_e64 v75, v104, v80, s[0:1]
	v_cndmask_b32_e64 v72, v72, v81, s[0:1]
	v_add_f32_e32 v73, v73, v105
	s_waitcnt lgkmcnt(1)
	v_add_f32_e32 v75, v75, v82
	s_waitcnt lgkmcnt(0)
	v_add_f32_e32 v72, v72, v83
	v_cndmask_b32_e64 v80, v73, v75, s[38:39]
	v_cndmask_b32_e64 v73, v75, v73, s[38:39]
	v_cndmask_b32_e64 v75, v74, v72, s[38:39]
	v_cndmask_b32_e64 v72, v72, v74, s[38:39]
	v_add_f32_dpp v73, v80, v73 row_ror:8 row_mask:0xf bank_mask:0xf bound_ctrl:1
	s_nop 0
	v_add_f32_dpp v72, v75, v72 row_ror:8 row_mask:0xf bank_mask:0xf bound_ctrl:1
	v_cndmask_b32_e64 v74, v73, v72, s[42:43]
	v_cndmask_b32_e64 v72, v72, v73, s[42:43]
	v_mov_b32_e32 v73, v35
	v_mov_b32_e32 v75, v35
	s_nop 0
	v_mov_b32_dpp v73, v74 row_ror:4 row_mask:0xf bank_mask:0xf
	v_mov_b32_dpp v75, v74 row_ror:12 row_mask:0xf bank_mask:0xf
	v_cndmask_b32_e64 v73, v73, v75, s[42:43]
	v_add_f32_e32 v72, v72, v73
	v_mov_b32_e32 v73, 0
	s_nop 0
	v_add_f32_dpp v72, v72, v72 quad_perm:[2,3,0,1] row_mask:0xf bank_mask:0xf bound_ctrl:1
	s_nop 1
	v_mov_b32_dpp v73, v72 quad_perm:[1,0,3,2] row_mask:0xf bank_mask:0xf
	s_and_saveexec_b64 s[2:3], s[44:45]
	s_cbranch_execz .LBB0_1175
	v_add_f32_e32 v72, v72, v73
	v_add_f32_e32 v72, v34, v72
	v_exp_f32_e32 v72, v72
	s_nop 0
	v_add_f32_e32 v73, 1.0, v72
	v_rcp_f32_e32 v73, v73
	s_nop 0
	v_mul_f32_e32 v72, v72, v73
	ds_write2st64_b32 v126, v73, v72 offset0:3 offset1:67
.LBB0_1175:
	s_or_b64 exec, exec, s[2:3]
	s_waitcnt vmcnt(29)
	v_pk_mul_f32 v[72:73], v[6:7], v[92:93]
	s_nop 0
	v_pk_fma_f32 v[72:73], v[94:95], v[8:9], v[72:73]
	s_nop 0
	v_add_f32_e32 v74, v72, v73
	s_waitcnt vmcnt(28)
	v_pk_mul_f32 v[72:73], v[2:3], v[84:85]
	s_nop 0
	v_pk_fma_f32 v[72:73], v[86:87], v[4:5], v[72:73]
	s_nop 0
	v_add_f32_e32 v75, v72, v73
	v_pk_mul_f32 v[72:73], v[14:15], v[92:93]
	s_nop 0
	v_pk_fma_f32 v[72:73], v[94:95], v[16:17], v[72:73]
	s_nop 0
	v_add_f32_e32 v80, v72, v73
	v_pk_mul_f32 v[72:73], v[10:11], v[84:85]
	s_nop 0
	v_pk_fma_f32 v[72:73], v[86:87], v[12:13], v[72:73]
	s_nop 0
	v_add_f32_e32 v81, v72, v73
	v_pk_mul_f32 v[72:73], v[22:23], v[92:93]
	s_nop 0
	v_pk_fma_f32 v[72:73], v[94:95], v[24:25], v[72:73]
	s_nop 0
	v_add_f32_e32 v82, v72, v73
	v_pk_mul_f32 v[72:73], v[18:19], v[84:85]
	s_nop 0
	v_pk_fma_f32 v[72:73], v[86:87], v[20:21], v[72:73]
	s_nop 0
	v_add_f32_e32 v83, v72, v73
	v_pk_mul_f32 v[72:73], v[30:31], v[92:93]
	s_nop 0
	v_pk_fma_f32 v[72:73], v[94:95], v[32:33], v[72:73]
	s_nop 0
	v_add_f32_e32 v92, v72, v73
	v_cndmask_b32_e64 v72, v74, v82, s[0:1]
	ds_bpermute_b32 v93, v125, v72
	v_pk_mul_f32 v[72:73], v[26:27], v[84:85]
	s_nop 0
	v_pk_fma_f32 v[72:73], v[86:87], v[28:29], v[72:73]
	s_nop 0
	v_add_f32_e32 v72, v72, v73
	v_cndmask_b32_e64 v73, v82, v74, s[0:1]
	v_cndmask_b32_e64 v74, v75, v83, s[0:1]
	v_cndmask_b32_e64 v75, v83, v75, s[0:1]
	ds_bpermute_b32 v74, v125, v74
	v_cndmask_b32_e64 v82, v80, v92, s[0:1]
	v_cndmask_b32_e64 v83, v81, v72, s[0:1]
	ds_bpermute_b32 v82, v125, v82
	ds_bpermute_b32 v83, v125, v83
	s_waitcnt lgkmcnt(2)
	v_add_f32_e32 v74, v75, v74
	v_cndmask_b32_e64 v75, v92, v80, s[0:1]
	v_cndmask_b32_e64 v72, v72, v81, s[0:1]
	v_add_f32_e32 v73, v73, v93
	s_waitcnt lgkmcnt(1)
	v_add_f32_e32 v75, v75, v82
	s_waitcnt lgkmcnt(0)
	v_add_f32_e32 v72, v72, v83
	v_cndmask_b32_e64 v80, v73, v75, s[38:39]
	v_cndmask_b32_e64 v73, v75, v73, s[38:39]
	v_cndmask_b32_e64 v75, v74, v72, s[38:39]
	v_cndmask_b32_e64 v72, v72, v74, s[38:39]
	v_add_f32_dpp v73, v80, v73 row_ror:8 row_mask:0xf bank_mask:0xf bound_ctrl:1
	s_nop 0
	v_add_f32_dpp v72, v75, v72 row_ror:8 row_mask:0xf bank_mask:0xf bound_ctrl:1
	v_cndmask_b32_e64 v74, v73, v72, s[42:43]
	v_cndmask_b32_e64 v72, v72, v73, s[42:43]
	v_mov_b32_e32 v73, v35
	v_mov_b32_e32 v75, v35
	s_nop 0
	v_mov_b32_dpp v73, v74 row_ror:4 row_mask:0xf bank_mask:0xf
	v_mov_b32_dpp v75, v74 row_ror:12 row_mask:0xf bank_mask:0xf
	v_cndmask_b32_e64 v73, v73, v75, s[42:43]
	v_add_f32_e32 v72, v72, v73
	v_mov_b32_e32 v73, 0
	s_nop 0
	v_add_f32_dpp v72, v72, v72 quad_perm:[2,3,0,1] row_mask:0xf bank_mask:0xf bound_ctrl:1
	s_nop 1
	v_mov_b32_dpp v73, v72 quad_perm:[1,0,3,2] row_mask:0xf bank_mask:0xf
	s_and_saveexec_b64 s[2:3], s[44:45]
	s_cbranch_execz .LBB0_1177
; #define DEC_LOADK(dst, i0) do { asm volatile("" ::: "memory"); _Pragma("unroll") for (int u = 0; u < 4; ++u) { const float* kr = ck + rbase + (size_t)((i0) + u) * 512; dst[u][0] = __builtin_nontemporal_load((const f32x4*)(kr + 4 * lane)); dst[u][1] = __builtin_nontemporal_load((const f32x4*)(kr + 256 + 4 * lane)); } } while (0)
; __device__ __forceinline__ void decode_item(Frame& F, const Args& a, int l, int item, unsigned char* ws) {
;     ...
;         DEC_LOADK(ka, 0); DEC_LOADK(kb, 4); DEC_SCORE(ka, 0); DEC_LOADK(ka, 8); DEC_SCORE(kb, 4); DEC_LOADK(kb, 12); DEC_SCORE(ka, 8); DEC_LOADK(ka, 16); DEC_SCORE(kb, 12); DEC_LOADK(kb, 20); DEC_SCORE(ka, 16); DEC_LOADK(ka, 24); DEC_SCORE(kb, 20); DEC_LOADK(kb, 28); DEC_SCORE(ka, 24); DEC_SCORE(kb, 28);
	v_add_f32_e32 v72, v72, v73
	v_add_f32_e32 v72, v34, v72
	v_exp_f32_e32 v72, v72
	v_add_u32_e32 v74, 64, v126
	v_add_f32_e32 v73, 1.0, v72
	v_rcp_f32_e32 v73, v73
	s_nop 0
	v_mul_f32_e32 v72, v72, v73
	ds_write2st64_b32 v74, v73, v72 offset0:3 offset1:67
.LBB0_1177:
	s_or_b64 exec, exec, s[2:3]
	s_waitcnt vmcnt(27)
	v_pk_mul_f32 v[72:73], v[6:7], v[60:61]
	s_nop 0
	v_pk_fma_f32 v[72:73], v[62:63], v[8:9], v[72:73]
	s_nop 0
	v_add_f32_e32 v74, v72, v73
	s_waitcnt vmcnt(26)
	v_pk_mul_f32 v[72:73], v[2:3], v[52:53]
	s_nop 0
	v_pk_fma_f32 v[72:73], v[54:55], v[4:5], v[72:73]
	s_nop 0
	v_add_f32_e32 v75, v72, v73
	v_pk_mul_f32 v[72:73], v[14:15], v[60:61]
	s_nop 0
	v_pk_fma_f32 v[72:73], v[62:63], v[16:17], v[72:73]
	s_nop 0
	v_add_f32_e32 v80, v72, v73
	v_pk_mul_f32 v[72:73], v[10:11], v[52:53]
	s_nop 0
	v_pk_fma_f32 v[72:73], v[54:55], v[12:13], v[72:73]
	s_nop 0
	v_add_f32_e32 v81, v72, v73
	v_pk_mul_f32 v[72:73], v[22:23], v[60:61]
	v_pk_mul_f32 v[60:61], v[30:31], v[60:61]
	v_pk_fma_f32 v[72:73], v[62:63], v[24:25], v[72:73]
	v_pk_fma_f32 v[60:61], v[62:63], v[32:33], v[60:61]
	v_add_f32_e32 v82, v72, v73
	v_add_f32_e32 v60, v60, v61
	v_cndmask_b32_e64 v61, v74, v82, s[0:1]
	ds_bpermute_b32 v61, v125, v61
	v_pk_mul_f32 v[72:73], v[18:19], v[52:53]
	v_pk_mul_f32 v[52:53], v[26:27], v[52:53]
	v_pk_fma_f32 v[72:73], v[54:55], v[20:21], v[72:73]
	v_pk_fma_f32 v[52:53], v[54:55], v[28:29], v[52:53]
	v_add_f32_e32 v72, v72, v73
	v_add_f32_e32 v52, v52, v53
	v_cndmask_b32_e64 v53, v82, v74, s[0:1]
	v_cndmask_b32_e64 v54, v75, v72, s[0:1]
	s_waitcnt lgkmcnt(0)
	v_add_f32_e32 v53, v53, v61
	ds_bpermute_b32 v54, v125, v54
	v_cndmask_b32_e64 v61, v80, v60, s[0:1]
	v_cndmask_b32_e64 v62, v81, v52, s[0:1]
	ds_bpermute_b32 v61, v125, v61
	ds_bpermute_b32 v62, v125, v62
	v_cndmask_b32_e64 v55, v72, v75, s[0:1]
	s_waitcnt lgkmcnt(2)
	v_add_f32_e32 v54, v55, v54
	v_cndmask_b32_e64 v55, v60, v80, s[0:1]
	v_cndmask_b32_e64 v52, v52, v81, s[0:1]
	s_waitcnt lgkmcnt(1)
	v_add_f32_e32 v55, v55, v61
	s_waitcnt lgkmcnt(0)
	v_add_f32_e32 v52, v52, v62
	v_cndmask_b32_e64 v60, v53, v55, s[38:39]
	v_cndmask_b32_e64 v53, v55, v53, s[38:39]
	v_cndmask_b32_e64 v55, v54, v52, s[38:39]
	v_cndmask_b32_e64 v52, v52, v54, s[38:39]
	v_add_f32_dpp v53, v60, v53 row_ror:8 row_mask:0xf bank_mask:0xf bound_ctrl:1
	s_nop 0
	v_add_f32_dpp v52, v55, v52 row_ror:8 row_mask:0xf bank_mask:0xf bound_ctrl:1
	v_cndmask_b32_e64 v54, v53, v52, s[42:43]
	v_cndmask_b32_e64 v52, v52, v53, s[42:43]
	v_mov_b32_e32 v53, v35
	v_mov_b32_e32 v55, v35
	s_nop 0
	v_mov_b32_dpp v53, v54 row_ror:4 row_mask:0xf bank_mask:0xf
	v_mov_b32_dpp v55, v54 row_ror:12 row_mask:0xf bank_mask:0xf
	v_cndmask_b32_e64 v53, v53, v55, s[42:43]
	v_add_f32_e32 v52, v52, v53
	v_mov_b32_e32 v53, 0
	s_nop 0
	v_add_f32_dpp v52, v52, v52 quad_perm:[2,3,0,1] row_mask:0xf bank_mask:0xf bound_ctrl:1
	s_nop 1
	v_mov_b32_dpp v53, v52 quad_perm:[1,0,3,2] row_mask:0xf bank_mask:0xf
	s_and_saveexec_b64 s[2:3], s[44:45]
	s_cbranch_execz .LBB0_1179
	v_add_f32_e32 v52, v52, v53
	v_add_f32_e32 v52, v34, v52
	v_exp_f32_e32 v52, v52
	v_add_u32_e32 v54, 0x80, v126
	v_add_f32_e32 v53, 1.0, v52
	v_rcp_f32_e32 v53, v53
	s_nop 0
	v_mul_f32_e32 v52, v52, v53
	ds_write2st64_b32 v54, v53, v52 offset0:3 offset1:67
.LBB0_1179:
	s_or_b64 exec, exec, s[2:3]
	s_waitcnt vmcnt(25)
	v_pk_mul_f32 v[52:53], v[6:7], v[44:45]
	s_nop 0
	v_pk_fma_f32 v[52:53], v[46:47], v[8:9], v[52:53]
	s_nop 0
	v_add_f32_e32 v54, v52, v53
	s_waitcnt vmcnt(24)
	v_pk_mul_f32 v[52:53], v[2:3], v[36:37]
	s_nop 0
	v_pk_fma_f32 v[52:53], v[38:39], v[4:5], v[52:53]
	s_nop 0
	v_add_f32_e32 v55, v52, v53
	v_pk_mul_f32 v[52:53], v[14:15], v[44:45]
	s_nop 0
	v_pk_fma_f32 v[52:53], v[46:47], v[16:17], v[52:53]
	s_nop 0
	v_add_f32_e32 v60, v52, v53
	v_pk_mul_f32 v[52:53], v[10:11], v[36:37]
	s_nop 0
	v_pk_fma_f32 v[52:53], v[38:39], v[12:13], v[52:53]
	s_nop 0
	v_add_f32_e32 v61, v52, v53
	v_pk_mul_f32 v[52:53], v[22:23], v[44:45]
	v_pk_mul_f32 v[44:45], v[30:31], v[44:45]
	v_pk_fma_f32 v[52:53], v[46:47], v[24:25], v[52:53]
	v_pk_fma_f32 v[44:45], v[46:47], v[32:33], v[44:45]
	v_add_f32_e32 v62, v52, v53
	v_add_f32_e32 v44, v44, v45
	v_cndmask_b32_e64 v45, v54, v62, s[0:1]
	ds_bpermute_b32 v45, v125, v45
	v_pk_mul_f32 v[52:53], v[18:19], v[36:37]
	v_pk_mul_f32 v[36:37], v[26:27], v[36:37]
	v_pk_fma_f32 v[52:53], v[38:39], v[20:21], v[52:53]
	v_pk_fma_f32 v[36:37], v[38:39], v[28:29], v[36:37]
	v_add_f32_e32 v52, v52, v53
	v_add_f32_e32 v36, v36, v37
	v_cndmask_b32_e64 v37, v62, v54, s[0:1]
	v_cndmask_b32_e64 v38, v55, v52, s[0:1]
	s_waitcnt lgkmcnt(0)
	v_add_f32_e32 v37, v37, v45
	ds_bpermute_b32 v38, v125, v38
	v_cndmask_b32_e64 v45, v60, v44, s[0:1]
	v_cndmask_b32_e64 v46, v61, v36, s[0:1]
	ds_bpermute_b32 v45, v125, v45
	ds_bpermute_b32 v46, v125, v46
	v_cndmask_b32_e64 v39, v52, v55, s[0:1]
	s_waitcnt lgkmcnt(2)
	v_add_f32_e32 v38, v39, v38
	v_cndmask_b32_e64 v39, v44, v60, s[0:1]
	v_cndmask_b32_e64 v36, v36, v61, s[0:1]
	s_waitcnt lgkmcnt(1)
	v_add_f32_e32 v39, v39, v45
	s_waitcnt lgkmcnt(0)
	v_add_f32_e32 v36, v36, v46
	v_cndmask_b32_e64 v44, v37, v39, s[38:39]
	v_cndmask_b32_e64 v37, v39, v37, s[38:39]
	v_cndmask_b32_e64 v39, v38, v36, s[38:39]
	v_cndmask_b32_e64 v36, v36, v38, s[38:39]
	v_add_f32_dpp v37, v44, v37 row_ror:8 row_mask:0xf bank_mask:0xf bound_ctrl:1
	s_nop 0
	v_add_f32_dpp v36, v39, v36 row_ror:8 row_mask:0xf bank_mask:0xf bound_ctrl:1
	v_cndmask_b32_e64 v38, v37, v36, s[42:43]
	v_cndmask_b32_e64 v36, v36, v37, s[42:43]
	v_mov_b32_e32 v37, v35
	v_mov_b32_e32 v39, v35
	s_nop 0
	v_mov_b32_dpp v37, v38 row_ror:4 row_mask:0xf bank_mask:0xf
	v_mov_b32_dpp v39, v38 row_ror:12 row_mask:0xf bank_mask:0xf
	v_cndmask_b32_e64 v37, v37, v39, s[42:43]
	v_add_f32_e32 v36, v36, v37
	v_mov_b32_e32 v37, 0
	s_nop 0
	v_add_f32_dpp v36, v36, v36 quad_perm:[2,3,0,1] row_mask:0xf bank_mask:0xf bound_ctrl:1
	s_nop 1
	v_mov_b32_dpp v37, v36 quad_perm:[1,0,3,2] row_mask:0xf bank_mask:0xf
	s_and_saveexec_b64 s[2:3], s[44:45]
	s_cbranch_execz .LBB0_1181
	v_add_f32_e32 v36, v36, v37
	v_add_f32_e32 v36, v34, v36
	v_exp_f32_e32 v36, v36
	v_add_u32_e32 v38, 0xc0, v126
	v_add_f32_e32 v37, 1.0, v36
	v_rcp_f32_e32 v37, v37
	s_nop 0
	v_mul_f32_e32 v36, v36, v37
	ds_write2st64_b32 v38, v37, v36 offset0:3 offset1:67
; #define DEC_LOADK(dst, i0) do { asm volatile("" ::: "memory"); _Pragma("unroll") for (int u = 0; u < 4; ++u) { const float* kr = ck + rbase + (size_t)((i0) + u) * 512; dst[u][0] = __builtin_nontemporal_load((const f32x4*)(kr + 4 * lane)); dst[u][1] = __builtin_nontemporal_load((const f32x4*)(kr + 256 + 4 * lane)); } } while (0)
; __device__ __forceinline__ void decode_item(Frame& F, const Args& a, int l, int item, unsigned char* ws) {
;     ...
;         DEC_LOADK(ka, 0); DEC_LOADK(kb, 4); DEC_SCORE(ka, 0); DEC_LOADK(ka, 8); DEC_SCORE(kb, 4); DEC_LOADK(kb, 12); DEC_SCORE(ka, 8); DEC_LOADK(ka, 16); DEC_SCORE(kb, 12); DEC_LOADK(kb, 20); DEC_SCORE(ka, 16); DEC_LOADK(ka, 24); DEC_SCORE(kb, 20); DEC_LOADK(kb, 28); DEC_SCORE(ka, 24); DEC_SCORE(kb, 28);
.LBB0_1181:
	s_or_b64 exec, exec, s[2:3]
	v_add_co_u32_e32 v36, vcc, 0xa000, v120
	s_waitcnt vmcnt(15)
	v_pk_mul_f32 v[100:101], v[6:7], v[96:97]
	v_addc_co_u32_e32 v37, vcc, 0, v121, vcc
	global_load_dwordx4 v[92:95], v[36:37], off nt
	global_load_dwordx4 v[84:87], v[36:37], off offset:1024 nt
	global_load_dwordx4 v[80:83], v[36:37], off offset:2048 nt
	global_load_dwordx4 v[72:75], v[36:37], off offset:3072 nt
	v_add_co_u32_e32 v36, vcc, 0xb000, v120
	v_pk_fma_f32 v[100:101], v[98:99], v[8:9], v[100:101]
	s_nop 0
	v_addc_co_u32_e32 v37, vcc, 0, v121, vcc
	global_load_dwordx4 v[60:63], v[36:37], off nt
	global_load_dwordx4 v[52:55], v[36:37], off offset:1024 nt
	global_load_dwordx4 v[44:47], v[36:37], off offset:2048 nt
	s_nop 0
	global_load_dwordx4 v[36:39], v[36:37], off offset:3072 nt
	global_load_dwordx4 v[204:207], v[194:195], off offset:-4096
	global_load_dwordx4 v[204:207], v[194:195], off offset:-3072
	global_load_dwordx4 v[204:207], v[194:195], off offset:-2048
	global_load_dwordx4 v[204:207], v[194:195], off offset:-1024
	global_load_dwordx4 v[204:207], v[194:195], off
	global_load_dwordx4 v[204:207], v[194:195], off offset:1024
	global_load_dwordx4 v[204:207], v[194:195], off offset:2048
	global_load_dwordx4 v[204:207], v[194:195], off offset:3072
	v_add_f32_e32 v102, v100, v101
	s_waitcnt vmcnt(30)
	v_pk_mul_f32 v[100:101], v[2:3], v[88:89]
	s_nop 0
	v_pk_fma_f32 v[100:101], v[90:91], v[4:5], v[100:101]
	s_nop 0
	v_add_f32_e32 v103, v100, v101
	v_pk_mul_f32 v[100:101], v[14:15], v[96:97]
	s_nop 0
	v_pk_fma_f32 v[100:101], v[98:99], v[16:17], v[100:101]
	s_nop 0
	v_add_f32_e32 v104, v100, v101
	v_pk_mul_f32 v[100:101], v[10:11], v[88:89]
	s_nop 0
	v_pk_fma_f32 v[100:101], v[90:91], v[12:13], v[100:101]
	s_nop 0
	v_add_f32_e32 v105, v100, v101
	v_pk_mul_f32 v[100:101], v[22:23], v[96:97]
	v_pk_mul_f32 v[96:97], v[30:31], v[96:97]
	v_pk_fma_f32 v[100:101], v[98:99], v[24:25], v[100:101]
	v_pk_fma_f32 v[96:97], v[98:99], v[32:33], v[96:97]
	v_add_f32_e32 v106, v100, v101
	v_add_f32_e32 v96, v96, v97
	v_cndmask_b32_e64 v97, v102, v106, s[0:1]
	ds_bpermute_b32 v97, v125, v97
	v_pk_mul_f32 v[100:101], v[18:19], v[88:89]
	v_pk_mul_f32 v[88:89], v[26:27], v[88:89]
	v_pk_fma_f32 v[100:101], v[90:91], v[20:21], v[100:101]
	v_pk_fma_f32 v[88:89], v[90:91], v[28:29], v[88:89]
	v_add_f32_e32 v100, v100, v101
	v_add_f32_e32 v88, v88, v89
	v_cndmask_b32_e64 v89, v106, v102, s[0:1]
	v_cndmask_b32_e64 v90, v103, v100, s[0:1]
	s_waitcnt lgkmcnt(0)
	v_add_f32_e32 v89, v89, v97
	ds_bpermute_b32 v90, v125, v90
	v_cndmask_b32_e64 v97, v104, v96, s[0:1]
	v_cndmask_b32_e64 v98, v105, v88, s[0:1]
	ds_bpermute_b32 v97, v125, v97
	ds_bpermute_b32 v98, v125, v98
	v_cndmask_b32_e64 v91, v100, v103, s[0:1]
	s_waitcnt lgkmcnt(2)
	v_add_f32_e32 v90, v91, v90
	v_cndmask_b32_e64 v91, v96, v104, s[0:1]
	v_cndmask_b32_e64 v88, v88, v105, s[0:1]
	s_waitcnt lgkmcnt(1)
	v_add_f32_e32 v91, v91, v97
	s_waitcnt lgkmcnt(0)
	v_add_f32_e32 v88, v88, v98
	v_cndmask_b32_e64 v96, v89, v91, s[38:39]
	v_cndmask_b32_e64 v89, v91, v89, s[38:39]
	v_cndmask_b32_e64 v91, v90, v88, s[38:39]
	v_cndmask_b32_e64 v88, v88, v90, s[38:39]
	v_add_f32_dpp v89, v96, v89 row_ror:8 row_mask:0xf bank_mask:0xf bound_ctrl:1
	s_nop 0
	v_add_f32_dpp v88, v91, v88 row_ror:8 row_mask:0xf bank_mask:0xf bound_ctrl:1
	v_cndmask_b32_e64 v90, v89, v88, s[42:43]
	v_cndmask_b32_e64 v88, v88, v89, s[42:43]
	v_mov_b32_e32 v89, v35
	v_mov_b32_e32 v91, v35
	s_nop 0
	v_mov_b32_dpp v89, v90 row_ror:4 row_mask:0xf bank_mask:0xf
	v_mov_b32_dpp v91, v90 row_ror:12 row_mask:0xf bank_mask:0xf
	v_cndmask_b32_e64 v89, v89, v91, s[42:43]
	v_add_f32_e32 v88, v88, v89
	v_mov_b32_e32 v89, 0
	s_nop 0
	v_add_f32_dpp v88, v88, v88 quad_perm:[2,3,0,1] row_mask:0xf bank_mask:0xf bound_ctrl:1
	s_nop 1
	v_mov_b32_dpp v89, v88 quad_perm:[1,0,3,2] row_mask:0xf bank_mask:0xf
	s_and_saveexec_b64 s[2:3], s[44:45]
	s_cbranch_execz .LBB0_1183
	v_add_f32_e32 v88, v88, v89
	v_add_f32_e32 v88, v34, v88
	v_exp_f32_e32 v88, v88
	s_nop 0
	v_add_f32_e32 v89, 1.0, v88
	v_rcp_f32_e32 v89, v89
	s_nop 0
	v_mul_f32_e32 v88, v88, v89
	ds_write2st64_b32 v126, v89, v88 offset0:4 offset1:68
.LBB0_1183:
	s_or_b64 exec, exec, s[2:3]
	s_waitcnt vmcnt(29)
	v_pk_mul_f32 v[88:89], v[6:7], v[76:77]
	s_nop 0
	v_pk_fma_f32 v[88:89], v[78:79], v[8:9], v[88:89]
	s_nop 0
	v_add_f32_e32 v90, v88, v89
	s_waitcnt vmcnt(28)
	v_pk_mul_f32 v[88:89], v[2:3], v[68:69]
	s_nop 0
	v_pk_fma_f32 v[88:89], v[70:71], v[4:5], v[88:89]
	s_nop 0
	v_add_f32_e32 v91, v88, v89
	v_pk_mul_f32 v[88:89], v[14:15], v[76:77]
	s_nop 0
	v_pk_fma_f32 v[88:89], v[78:79], v[16:17], v[88:89]
	s_nop 0
	v_add_f32_e32 v96, v88, v89
	v_pk_mul_f32 v[88:89], v[10:11], v[68:69]
	s_nop 0
	v_pk_fma_f32 v[88:89], v[70:71], v[12:13], v[88:89]
	s_nop 0
	v_add_f32_e32 v97, v88, v89
	v_pk_mul_f32 v[88:89], v[22:23], v[76:77]
	v_pk_mul_f32 v[76:77], v[30:31], v[76:77]
	v_pk_fma_f32 v[88:89], v[78:79], v[24:25], v[88:89]
	v_pk_fma_f32 v[76:77], v[78:79], v[32:33], v[76:77]
	v_add_f32_e32 v98, v88, v89
	v_add_f32_e32 v76, v76, v77
	v_cndmask_b32_e64 v77, v90, v98, s[0:1]
	ds_bpermute_b32 v77, v125, v77
	v_pk_mul_f32 v[88:89], v[18:19], v[68:69]
	v_pk_mul_f32 v[68:69], v[26:27], v[68:69]
	v_pk_fma_f32 v[88:89], v[70:71], v[20:21], v[88:89]
	v_pk_fma_f32 v[68:69], v[70:71], v[28:29], v[68:69]
	v_add_f32_e32 v88, v88, v89
	v_add_f32_e32 v68, v68, v69
	v_cndmask_b32_e64 v69, v98, v90, s[0:1]
	v_cndmask_b32_e64 v70, v91, v88, s[0:1]
	s_waitcnt lgkmcnt(0)
	v_add_f32_e32 v69, v69, v77
	ds_bpermute_b32 v70, v125, v70
	v_cndmask_b32_e64 v77, v96, v76, s[0:1]
	v_cndmask_b32_e64 v78, v97, v68, s[0:1]
	ds_bpermute_b32 v77, v125, v77
	ds_bpermute_b32 v78, v125, v78
	v_cndmask_b32_e64 v71, v88, v91, s[0:1]
	s_waitcnt lgkmcnt(2)
	v_add_f32_e32 v70, v71, v70
	v_cndmask_b32_e64 v71, v76, v96, s[0:1]
	v_cndmask_b32_e64 v68, v68, v97, s[0:1]
	s_waitcnt lgkmcnt(1)
	v_add_f32_e32 v71, v71, v77
	s_waitcnt lgkmcnt(0)
	v_add_f32_e32 v68, v68, v78
	v_cndmask_b32_e64 v76, v69, v71, s[38:39]
	v_cndmask_b32_e64 v69, v71, v69, s[38:39]
	v_cndmask_b32_e64 v71, v70, v68, s[38:39]
	v_cndmask_b32_e64 v68, v68, v70, s[38:39]
	v_add_f32_dpp v69, v76, v69 row_ror:8 row_mask:0xf bank_mask:0xf bound_ctrl:1
	s_nop 0
	v_add_f32_dpp v68, v71, v68 row_ror:8 row_mask:0xf bank_mask:0xf bound_ctrl:1
	v_cndmask_b32_e64 v70, v69, v68, s[42:43]
	v_cndmask_b32_e64 v68, v68, v69, s[42:43]
	v_mov_b32_e32 v69, v35
	v_mov_b32_e32 v71, v35
	s_nop 0
	v_mov_b32_dpp v69, v70 row_ror:4 row_mask:0xf bank_mask:0xf
	v_mov_b32_dpp v71, v70 row_ror:12 row_mask:0xf bank_mask:0xf
	v_cndmask_b32_e64 v69, v69, v71, s[42:43]
	v_add_f32_e32 v68, v68, v69
	v_mov_b32_e32 v69, 0
	s_nop 0
	v_add_f32_dpp v68, v68, v68 quad_perm:[2,3,0,1] row_mask:0xf bank_mask:0xf bound_ctrl:1
	s_nop 1
	v_mov_b32_dpp v69, v68 quad_perm:[1,0,3,2] row_mask:0xf bank_mask:0xf
	s_and_saveexec_b64 s[2:3], s[44:45]
	s_cbranch_execz .LBB0_1185
; #define DEC_LOADK(dst, i0) do { asm volatile("" ::: "memory"); _Pragma("unroll") for (int u = 0; u < 4; ++u) { const float* kr = ck + rbase + (size_t)((i0) + u) * 512; dst[u][0] = __builtin_nontemporal_load((const f32x4*)(kr + 4 * lane)); dst[u][1] = __builtin_nontemporal_load((const f32x4*)(kr + 256 + 4 * lane)); } } while (0)
; __device__ __forceinline__ void decode_item(Frame& F, const Args& a, int l, int item, unsigned char* ws) {
;     ...
;         DEC_LOADK(ka, 0); DEC_LOADK(kb, 4); DEC_SCORE(ka, 0); DEC_LOADK(ka, 8); DEC_SCORE(kb, 4); DEC_LOADK(kb, 12); DEC_SCORE(ka, 8); DEC_LOADK(ka, 16); DEC_SCORE(kb, 12); DEC_LOADK(kb, 20); DEC_SCORE(ka, 16); DEC_LOADK(ka, 24); DEC_SCORE(kb, 20); DEC_LOADK(kb, 28); DEC_SCORE(ka, 24); DEC_SCORE(kb, 28);
	v_add_f32_e32 v68, v68, v69
	v_add_f32_e32 v68, v34, v68
	v_exp_f32_e32 v68, v68
	v_add_u32_e32 v70, 64, v126
	v_add_f32_e32 v69, 1.0, v68
	v_rcp_f32_e32 v69, v69
	s_nop 0
	v_mul_f32_e32 v68, v68, v69
	ds_write2st64_b32 v70, v69, v68 offset0:4 offset1:68
.LBB0_1185:
	s_or_b64 exec, exec, s[2:3]
	s_waitcnt vmcnt(27)
	v_pk_mul_f32 v[68:69], v[6:7], v[64:65]
	s_nop 0
	v_pk_fma_f32 v[68:69], v[66:67], v[8:9], v[68:69]
	s_nop 0
	v_add_f32_e32 v70, v68, v69
	s_waitcnt vmcnt(26)
	v_pk_mul_f32 v[68:69], v[2:3], v[56:57]
	s_nop 0
	v_pk_fma_f32 v[68:69], v[58:59], v[4:5], v[68:69]
	s_nop 0
	v_add_f32_e32 v71, v68, v69
	v_pk_mul_f32 v[68:69], v[14:15], v[64:65]
	s_nop 0
	v_pk_fma_f32 v[68:69], v[66:67], v[16:17], v[68:69]
	s_nop 0
	v_add_f32_e32 v76, v68, v69
	v_pk_mul_f32 v[68:69], v[10:11], v[56:57]
	s_nop 0
	v_pk_fma_f32 v[68:69], v[58:59], v[12:13], v[68:69]
	s_nop 0
	v_add_f32_e32 v77, v68, v69
	v_pk_mul_f32 v[68:69], v[22:23], v[64:65]
	v_pk_mul_f32 v[64:65], v[30:31], v[64:65]
	v_pk_fma_f32 v[68:69], v[66:67], v[24:25], v[68:69]
	v_pk_fma_f32 v[64:65], v[66:67], v[32:33], v[64:65]
	v_add_f32_e32 v78, v68, v69
	v_add_f32_e32 v64, v64, v65
	v_cndmask_b32_e64 v65, v70, v78, s[0:1]
	ds_bpermute_b32 v65, v125, v65
	v_pk_mul_f32 v[68:69], v[18:19], v[56:57]
	v_pk_mul_f32 v[56:57], v[26:27], v[56:57]
	v_pk_fma_f32 v[68:69], v[58:59], v[20:21], v[68:69]
	v_pk_fma_f32 v[56:57], v[58:59], v[28:29], v[56:57]
	v_add_f32_e32 v68, v68, v69
	v_add_f32_e32 v56, v56, v57
	v_cndmask_b32_e64 v57, v78, v70, s[0:1]
	v_cndmask_b32_e64 v58, v71, v68, s[0:1]
	s_waitcnt lgkmcnt(0)
	v_add_f32_e32 v57, v57, v65
	ds_bpermute_b32 v58, v125, v58
	v_cndmask_b32_e64 v65, v76, v64, s[0:1]
	v_cndmask_b32_e64 v66, v77, v56, s[0:1]
	ds_bpermute_b32 v65, v125, v65
	ds_bpermute_b32 v66, v125, v66
	v_cndmask_b32_e64 v59, v68, v71, s[0:1]
	s_waitcnt lgkmcnt(2)
	v_add_f32_e32 v58, v59, v58
	v_cndmask_b32_e64 v59, v64, v76, s[0:1]
	v_cndmask_b32_e64 v56, v56, v77, s[0:1]
	s_waitcnt lgkmcnt(1)
	v_add_f32_e32 v59, v59, v65
	s_waitcnt lgkmcnt(0)
	v_add_f32_e32 v56, v56, v66
	v_cndmask_b32_e64 v64, v57, v59, s[38:39]
	v_cndmask_b32_e64 v57, v59, v57, s[38:39]
	v_cndmask_b32_e64 v59, v58, v56, s[38:39]
	v_cndmask_b32_e64 v56, v56, v58, s[38:39]
	v_add_f32_dpp v57, v64, v57 row_ror:8 row_mask:0xf bank_mask:0xf bound_ctrl:1
	s_nop 0
	v_add_f32_dpp v56, v59, v56 row_ror:8 row_mask:0xf bank_mask:0xf bound_ctrl:1
	v_cndmask_b32_e64 v58, v57, v56, s[42:43]
	v_cndmask_b32_e64 v56, v56, v57, s[42:43]
	v_mov_b32_e32 v57, v35
	v_mov_b32_e32 v59, v35
	s_nop 0
	v_mov_b32_dpp v57, v58 row_ror:4 row_mask:0xf bank_mask:0xf
	v_mov_b32_dpp v59, v58 row_ror:12 row_mask:0xf bank_mask:0xf
	v_cndmask_b32_e64 v57, v57, v59, s[42:43]
	v_add_f32_e32 v56, v56, v57
	v_mov_b32_e32 v57, 0
	s_nop 0
	v_add_f32_dpp v56, v56, v56 quad_perm:[2,3,0,1] row_mask:0xf bank_mask:0xf bound_ctrl:1
	s_nop 1
	v_mov_b32_dpp v57, v56 quad_perm:[1,0,3,2] row_mask:0xf bank_mask:0xf
	s_and_saveexec_b64 s[2:3], s[44:45]
	s_cbranch_execz .LBB0_1187
	v_add_f32_e32 v56, v56, v57
	v_add_f32_e32 v56, v34, v56
	v_exp_f32_e32 v56, v56
	v_add_u32_e32 v58, 0x80, v126
	v_add_f32_e32 v57, 1.0, v56
	v_rcp_f32_e32 v57, v57
	s_nop 0
	v_mul_f32_e32 v56, v56, v57
	ds_write2st64_b32 v58, v57, v56 offset0:4 offset1:68
.LBB0_1187:
	s_or_b64 exec, exec, s[2:3]
	s_waitcnt vmcnt(25)
	v_pk_mul_f32 v[56:57], v[6:7], v[48:49]
	s_nop 0
	v_pk_fma_f32 v[56:57], v[50:51], v[8:9], v[56:57]
	s_nop 0
	v_add_f32_e32 v58, v56, v57
	s_waitcnt vmcnt(24)
	v_pk_mul_f32 v[56:57], v[2:3], v[40:41]
	s_nop 0
	v_pk_fma_f32 v[56:57], v[42:43], v[4:5], v[56:57]
	s_nop 0
	v_add_f32_e32 v59, v56, v57
	v_pk_mul_f32 v[56:57], v[14:15], v[48:49]
	s_nop 0
	v_pk_fma_f32 v[56:57], v[50:51], v[16:17], v[56:57]
	s_nop 0
	v_add_f32_e32 v64, v56, v57
	v_pk_mul_f32 v[56:57], v[10:11], v[40:41]
	s_nop 0
	v_pk_fma_f32 v[56:57], v[42:43], v[12:13], v[56:57]
	s_nop 0
	v_add_f32_e32 v65, v56, v57
	v_pk_mul_f32 v[56:57], v[22:23], v[48:49]
	v_pk_mul_f32 v[48:49], v[30:31], v[48:49]
	v_pk_fma_f32 v[56:57], v[50:51], v[24:25], v[56:57]
	v_pk_fma_f32 v[48:49], v[50:51], v[32:33], v[48:49]
	v_add_f32_e32 v66, v56, v57
	v_add_f32_e32 v48, v48, v49
	v_cndmask_b32_e64 v49, v58, v66, s[0:1]
	ds_bpermute_b32 v49, v125, v49
	v_pk_mul_f32 v[56:57], v[18:19], v[40:41]
	v_pk_mul_f32 v[40:41], v[26:27], v[40:41]
	v_pk_fma_f32 v[56:57], v[42:43], v[20:21], v[56:57]
	v_pk_fma_f32 v[40:41], v[42:43], v[28:29], v[40:41]
	v_add_f32_e32 v56, v56, v57
	v_add_f32_e32 v40, v40, v41
	v_cndmask_b32_e64 v41, v66, v58, s[0:1]
	v_cndmask_b32_e64 v42, v59, v56, s[0:1]
	s_waitcnt lgkmcnt(0)
	v_add_f32_e32 v41, v41, v49
	ds_bpermute_b32 v42, v125, v42
	v_cndmask_b32_e64 v49, v64, v48, s[0:1]
	v_cndmask_b32_e64 v50, v65, v40, s[0:1]
	ds_bpermute_b32 v49, v125, v49
	ds_bpermute_b32 v50, v125, v50
	v_cndmask_b32_e64 v43, v56, v59, s[0:1]
	s_waitcnt lgkmcnt(2)
	v_add_f32_e32 v42, v43, v42
	v_cndmask_b32_e64 v43, v48, v64, s[0:1]
	v_cndmask_b32_e64 v40, v40, v65, s[0:1]
	s_waitcnt lgkmcnt(1)
	v_add_f32_e32 v43, v43, v49
	s_waitcnt lgkmcnt(0)
	v_add_f32_e32 v40, v40, v50
	v_cndmask_b32_e64 v48, v41, v43, s[38:39]
	v_cndmask_b32_e64 v41, v43, v41, s[38:39]
	v_cndmask_b32_e64 v43, v42, v40, s[38:39]
	v_cndmask_b32_e64 v40, v40, v42, s[38:39]
	v_add_f32_dpp v41, v48, v41 row_ror:8 row_mask:0xf bank_mask:0xf bound_ctrl:1
	s_nop 0
	v_add_f32_dpp v40, v43, v40 row_ror:8 row_mask:0xf bank_mask:0xf bound_ctrl:1
	v_cndmask_b32_e64 v42, v41, v40, s[42:43]
	v_cndmask_b32_e64 v40, v40, v41, s[42:43]
	v_mov_b32_e32 v41, v35
	v_mov_b32_e32 v43, v35
	s_nop 0
	v_mov_b32_dpp v41, v42 row_ror:4 row_mask:0xf bank_mask:0xf
	v_mov_b32_dpp v43, v42 row_ror:12 row_mask:0xf bank_mask:0xf
	v_cndmask_b32_e64 v41, v41, v43, s[42:43]
	v_add_f32_e32 v40, v40, v41
	v_mov_b32_e32 v41, 0
	s_nop 0
	v_add_f32_dpp v40, v40, v40 quad_perm:[2,3,0,1] row_mask:0xf bank_mask:0xf bound_ctrl:1
	s_nop 1
	v_mov_b32_dpp v41, v40 quad_perm:[1,0,3,2] row_mask:0xf bank_mask:0xf
	s_and_saveexec_b64 s[2:3], s[44:45]
	s_cbranch_execz .LBB0_1189
	v_add_f32_e32 v40, v40, v41
	v_add_f32_e32 v40, v34, v40
	v_exp_f32_e32 v40, v40
	v_add_u32_e32 v42, 0xc0, v126
	v_add_f32_e32 v41, 1.0, v40
	v_rcp_f32_e32 v41, v41
	s_nop 0
	v_mul_f32_e32 v40, v40, v41
	ds_write2st64_b32 v42, v41, v40 offset0:4 offset1:68
; #define DEC_LOADK(dst, i0) do { asm volatile("" ::: "memory"); _Pragma("unroll") for (int u = 0; u < 4; ++u) { const float* kr = ck + rbase + (size_t)((i0) + u) * 512; dst[u][0] = __builtin_nontemporal_load((const f32x4*)(kr + 4 * lane)); dst[u][1] = __builtin_nontemporal_load((const f32x4*)(kr + 256 + 4 * lane)); } } while (0)
; __device__ __forceinline__ void decode_item(Frame& F, const Args& a, int l, int item, unsigned char* ws) {
;     ...
;         DEC_LOADK(ka, 0); DEC_LOADK(kb, 4); DEC_SCORE(ka, 0); DEC_LOADK(ka, 8); DEC_SCORE(kb, 4); DEC_LOADK(kb, 12); DEC_SCORE(ka, 8); DEC_LOADK(ka, 16); DEC_SCORE(kb, 12); DEC_LOADK(kb, 20); DEC_SCORE(ka, 16); DEC_LOADK(ka, 24); DEC_SCORE(kb, 20); DEC_LOADK(kb, 28); DEC_SCORE(ka, 24); DEC_SCORE(kb, 28);
.LBB0_1189:
	s_or_b64 exec, exec, s[2:3]
	v_add_co_u32_e32 v40, vcc, 0xc000, v120
	s_waitcnt vmcnt(15)
	v_pk_mul_f32 v[100:101], v[6:7], v[92:93]
	v_addc_co_u32_e32 v41, vcc, 0, v121, vcc
	global_load_dwordx4 v[96:99], v[40:41], off nt
	global_load_dwordx4 v[88:91], v[40:41], off offset:1024 nt
	global_load_dwordx4 v[76:79], v[40:41], off offset:2048 nt
	global_load_dwordx4 v[68:71], v[40:41], off offset:3072 nt
	v_add_co_u32_e32 v40, vcc, 0xd000, v120
	v_pk_fma_f32 v[100:101], v[94:95], v[8:9], v[100:101]
	s_nop 0
	v_addc_co_u32_e32 v41, vcc, 0, v121, vcc
	global_load_dwordx4 v[64:67], v[40:41], off nt
	global_load_dwordx4 v[56:59], v[40:41], off offset:1024 nt
	global_load_dwordx4 v[48:51], v[40:41], off offset:2048 nt
	s_nop 0
	global_load_dwordx4 v[40:43], v[40:41], off offset:3072 nt
	v_add_f32_e32 v102, v100, v101
	s_waitcnt vmcnt(22)
	v_pk_mul_f32 v[100:101], v[2:3], v[84:85]
	s_nop 0
	v_pk_fma_f32 v[100:101], v[86:87], v[4:5], v[100:101]
	s_nop 0
	v_add_f32_e32 v103, v100, v101
	v_pk_mul_f32 v[100:101], v[14:15], v[92:93]
	s_nop 0
	v_pk_fma_f32 v[100:101], v[94:95], v[16:17], v[100:101]
	s_nop 0
	v_add_f32_e32 v104, v100, v101
	v_pk_mul_f32 v[100:101], v[10:11], v[84:85]
	s_nop 0
	v_pk_fma_f32 v[100:101], v[86:87], v[12:13], v[100:101]
	s_nop 0
	v_add_f32_e32 v105, v100, v101
	v_pk_mul_f32 v[100:101], v[22:23], v[92:93]
	v_pk_mul_f32 v[92:93], v[30:31], v[92:93]
	v_pk_fma_f32 v[100:101], v[94:95], v[24:25], v[100:101]
	v_pk_fma_f32 v[92:93], v[94:95], v[32:33], v[92:93]
	v_add_f32_e32 v106, v100, v101
	v_add_f32_e32 v92, v92, v93
	v_cndmask_b32_e64 v93, v102, v106, s[0:1]
	ds_bpermute_b32 v93, v125, v93
	v_pk_mul_f32 v[100:101], v[18:19], v[84:85]
	v_pk_mul_f32 v[84:85], v[26:27], v[84:85]
	v_pk_fma_f32 v[100:101], v[86:87], v[20:21], v[100:101]
	v_pk_fma_f32 v[84:85], v[86:87], v[28:29], v[84:85]
	v_add_f32_e32 v100, v100, v101
	v_add_f32_e32 v84, v84, v85
	v_cndmask_b32_e64 v85, v106, v102, s[0:1]
	v_cndmask_b32_e64 v86, v103, v100, s[0:1]
	s_waitcnt lgkmcnt(0)
	v_add_f32_e32 v85, v85, v93
	ds_bpermute_b32 v86, v125, v86
	v_cndmask_b32_e64 v93, v104, v92, s[0:1]
	v_cndmask_b32_e64 v94, v105, v84, s[0:1]
	ds_bpermute_b32 v93, v125, v93
	ds_bpermute_b32 v94, v125, v94
	v_cndmask_b32_e64 v87, v100, v103, s[0:1]
	s_waitcnt lgkmcnt(2)
	v_add_f32_e32 v86, v87, v86
	v_cndmask_b32_e64 v87, v92, v104, s[0:1]
	v_cndmask_b32_e64 v84, v84, v105, s[0:1]
	s_waitcnt lgkmcnt(1)
	v_add_f32_e32 v87, v87, v93
	s_waitcnt lgkmcnt(0)
	v_add_f32_e32 v84, v84, v94
	v_cndmask_b32_e64 v92, v85, v87, s[38:39]
	v_cndmask_b32_e64 v85, v87, v85, s[38:39]
	v_cndmask_b32_e64 v87, v86, v84, s[38:39]
	v_cndmask_b32_e64 v84, v84, v86, s[38:39]
	v_add_f32_dpp v85, v92, v85 row_ror:8 row_mask:0xf bank_mask:0xf bound_ctrl:1
	s_nop 0
	v_add_f32_dpp v84, v87, v84 row_ror:8 row_mask:0xf bank_mask:0xf bound_ctrl:1
	v_cndmask_b32_e64 v86, v85, v84, s[42:43]
	v_cndmask_b32_e64 v84, v84, v85, s[42:43]
	v_mov_b32_e32 v85, v35
	v_mov_b32_e32 v87, v35
	s_nop 0
	v_mov_b32_dpp v85, v86 row_ror:4 row_mask:0xf bank_mask:0xf
	v_mov_b32_dpp v87, v86 row_ror:12 row_mask:0xf bank_mask:0xf
	v_cndmask_b32_e64 v85, v85, v87, s[42:43]
	v_add_f32_e32 v84, v84, v85
	v_mov_b32_e32 v85, 0
	s_nop 0
	v_add_f32_dpp v84, v84, v84 quad_perm:[2,3,0,1] row_mask:0xf bank_mask:0xf bound_ctrl:1
	s_nop 1
	v_mov_b32_dpp v85, v84 quad_perm:[1,0,3,2] row_mask:0xf bank_mask:0xf
	s_and_saveexec_b64 s[2:3], s[44:45]
	s_cbranch_execz .LBB0_1191
	v_add_f32_e32 v84, v84, v85
	v_add_f32_e32 v84, v34, v84
	v_exp_f32_e32 v84, v84
	s_nop 0
	v_add_f32_e32 v85, 1.0, v84
	v_rcp_f32_e32 v85, v85
	s_nop 0
	v_mul_f32_e32 v84, v84, v85
	ds_write2st64_b32 v126, v85, v84 offset0:5 offset1:69
.LBB0_1191:
	s_or_b64 exec, exec, s[2:3]
	s_waitcnt vmcnt(21)
	v_pk_mul_f32 v[84:85], v[6:7], v[80:81]
	s_nop 0
	v_pk_fma_f32 v[84:85], v[82:83], v[8:9], v[84:85]
	s_nop 0
	v_add_f32_e32 v86, v84, v85
	s_waitcnt vmcnt(20)
	v_pk_mul_f32 v[84:85], v[2:3], v[72:73]
	s_nop 0
	v_pk_fma_f32 v[84:85], v[74:75], v[4:5], v[84:85]
	s_nop 0
	v_add_f32_e32 v87, v84, v85
	v_pk_mul_f32 v[84:85], v[14:15], v[80:81]
	s_nop 0
	v_pk_fma_f32 v[84:85], v[82:83], v[16:17], v[84:85]
	s_nop 0
	v_add_f32_e32 v92, v84, v85
	v_pk_mul_f32 v[84:85], v[10:11], v[72:73]
	s_nop 0
	v_pk_fma_f32 v[84:85], v[74:75], v[12:13], v[84:85]
	s_nop 0
	v_add_f32_e32 v93, v84, v85
	v_pk_mul_f32 v[84:85], v[22:23], v[80:81]
	v_pk_mul_f32 v[80:81], v[30:31], v[80:81]
	v_pk_fma_f32 v[84:85], v[82:83], v[24:25], v[84:85]
	v_pk_fma_f32 v[80:81], v[82:83], v[32:33], v[80:81]
	v_add_f32_e32 v94, v84, v85
	v_add_f32_e32 v80, v80, v81
	v_cndmask_b32_e64 v81, v86, v94, s[0:1]
	ds_bpermute_b32 v81, v125, v81
	v_pk_mul_f32 v[84:85], v[18:19], v[72:73]
	v_pk_mul_f32 v[72:73], v[26:27], v[72:73]
	v_pk_fma_f32 v[84:85], v[74:75], v[20:21], v[84:85]
	v_pk_fma_f32 v[72:73], v[74:75], v[28:29], v[72:73]
	v_add_f32_e32 v84, v84, v85
	v_add_f32_e32 v72, v72, v73
	v_cndmask_b32_e64 v73, v94, v86, s[0:1]
	v_cndmask_b32_e64 v74, v87, v84, s[0:1]
	s_waitcnt lgkmcnt(0)
	v_add_f32_e32 v73, v73, v81
	ds_bpermute_b32 v74, v125, v74
	v_cndmask_b32_e64 v81, v92, v80, s[0:1]
	v_cndmask_b32_e64 v82, v93, v72, s[0:1]
	ds_bpermute_b32 v81, v125, v81
	ds_bpermute_b32 v82, v125, v82
	v_cndmask_b32_e64 v75, v84, v87, s[0:1]
	s_waitcnt lgkmcnt(2)
	v_add_f32_e32 v74, v75, v74
	v_cndmask_b32_e64 v75, v80, v92, s[0:1]
	v_cndmask_b32_e64 v72, v72, v93, s[0:1]
	s_waitcnt lgkmcnt(1)
	v_add_f32_e32 v75, v75, v81
	s_waitcnt lgkmcnt(0)
	v_add_f32_e32 v72, v72, v82
	v_cndmask_b32_e64 v80, v73, v75, s[38:39]
	v_cndmask_b32_e64 v73, v75, v73, s[38:39]
	v_cndmask_b32_e64 v75, v74, v72, s[38:39]
	v_cndmask_b32_e64 v72, v72, v74, s[38:39]
	v_add_f32_dpp v73, v80, v73 row_ror:8 row_mask:0xf bank_mask:0xf bound_ctrl:1
	s_nop 0
	v_add_f32_dpp v72, v75, v72 row_ror:8 row_mask:0xf bank_mask:0xf bound_ctrl:1
	v_cndmask_b32_e64 v74, v73, v72, s[42:43]
	v_cndmask_b32_e64 v72, v72, v73, s[42:43]
	v_mov_b32_e32 v73, v35
	v_mov_b32_e32 v75, v35
	s_nop 0
	v_mov_b32_dpp v73, v74 row_ror:4 row_mask:0xf bank_mask:0xf
	v_mov_b32_dpp v75, v74 row_ror:12 row_mask:0xf bank_mask:0xf
	v_cndmask_b32_e64 v73, v73, v75, s[42:43]
	v_add_f32_e32 v72, v72, v73
	v_mov_b32_e32 v73, 0
	s_nop 0
	v_add_f32_dpp v72, v72, v72 quad_perm:[2,3,0,1] row_mask:0xf bank_mask:0xf bound_ctrl:1
	s_nop 1
	v_mov_b32_dpp v73, v72 quad_perm:[1,0,3,2] row_mask:0xf bank_mask:0xf
	s_and_saveexec_b64 s[2:3], s[44:45]
	s_cbranch_execz .LBB0_1193
	v_add_f32_e32 v72, v72, v73
	v_add_f32_e32 v72, v34, v72
	v_exp_f32_e32 v72, v72
	v_add_u32_e32 v74, 64, v126
	v_add_f32_e32 v73, 1.0, v72
	v_rcp_f32_e32 v73, v73
	s_nop 0
	v_mul_f32_e32 v72, v72, v73
	ds_write2st64_b32 v74, v73, v72 offset0:5 offset1:69
; #define DEC_LOADK(dst, i0) do { asm volatile("" ::: "memory"); _Pragma("unroll") for (int u = 0; u < 4; ++u) { const float* kr = ck + rbase + (size_t)((i0) + u) * 512; dst[u][0] = __builtin_nontemporal_load((const f32x4*)(kr + 4 * lane)); dst[u][1] = __builtin_nontemporal_load((const f32x4*)(kr + 256 + 4 * lane)); } } while (0)
; __device__ __forceinline__ void decode_item(Frame& F, const Args& a, int l, int item, unsigned char* ws) {
;     ...
;         DEC_LOADK(ka, 0); DEC_LOADK(kb, 4); DEC_SCORE(ka, 0); DEC_LOADK(ka, 8); DEC_SCORE(kb, 4); DEC_LOADK(kb, 12); DEC_SCORE(ka, 8); DEC_LOADK(ka, 16); DEC_SCORE(kb, 12); DEC_LOADK(kb, 20); DEC_SCORE(ka, 16); DEC_LOADK(ka, 24); DEC_SCORE(kb, 20); DEC_LOADK(kb, 28); DEC_SCORE(ka, 24); DEC_SCORE(kb, 28);
.LBB0_1193:
	s_or_b64 exec, exec, s[2:3]
	s_waitcnt vmcnt(19)
	v_pk_mul_f32 v[72:73], v[6:7], v[60:61]
	s_nop 0
	v_pk_fma_f32 v[72:73], v[62:63], v[8:9], v[72:73]
	s_nop 0
	v_add_f32_e32 v74, v72, v73
	s_waitcnt vmcnt(18)
	v_pk_mul_f32 v[72:73], v[2:3], v[52:53]
	s_nop 0
	v_pk_fma_f32 v[72:73], v[54:55], v[4:5], v[72:73]
	s_nop 0
	v_add_f32_e32 v75, v72, v73
	v_pk_mul_f32 v[72:73], v[14:15], v[60:61]
	s_nop 0
	v_pk_fma_f32 v[72:73], v[62:63], v[16:17], v[72:73]
	s_nop 0
	v_add_f32_e32 v80, v72, v73
	v_pk_mul_f32 v[72:73], v[10:11], v[52:53]
	s_nop 0
	v_pk_fma_f32 v[72:73], v[54:55], v[12:13], v[72:73]
	s_nop 0
	v_add_f32_e32 v81, v72, v73
	v_pk_mul_f32 v[72:73], v[22:23], v[60:61]
	v_pk_mul_f32 v[60:61], v[30:31], v[60:61]
	v_pk_fma_f32 v[72:73], v[62:63], v[24:25], v[72:73]
	v_pk_fma_f32 v[60:61], v[62:63], v[32:33], v[60:61]
	v_add_f32_e32 v82, v72, v73
	v_add_f32_e32 v60, v60, v61
	v_cndmask_b32_e64 v61, v74, v82, s[0:1]
	ds_bpermute_b32 v61, v125, v61
	v_pk_mul_f32 v[72:73], v[18:19], v[52:53]
	v_pk_mul_f32 v[52:53], v[26:27], v[52:53]
	v_pk_fma_f32 v[72:73], v[54:55], v[20:21], v[72:73]
	v_pk_fma_f32 v[52:53], v[54:55], v[28:29], v[52:53]
	v_add_f32_e32 v72, v72, v73
	v_add_f32_e32 v52, v52, v53
	v_cndmask_b32_e64 v53, v82, v74, s[0:1]
	v_cndmask_b32_e64 v54, v75, v72, s[0:1]
	s_waitcnt lgkmcnt(0)
	v_add_f32_e32 v53, v53, v61
	ds_bpermute_b32 v54, v125, v54
	v_cndmask_b32_e64 v61, v80, v60, s[0:1]
	v_cndmask_b32_e64 v62, v81, v52, s[0:1]
	ds_bpermute_b32 v61, v125, v61
	ds_bpermute_b32 v62, v125, v62
	v_cndmask_b32_e64 v55, v72, v75, s[0:1]
	s_waitcnt lgkmcnt(2)
	v_add_f32_e32 v54, v55, v54
	v_cndmask_b32_e64 v55, v60, v80, s[0:1]
	v_cndmask_b32_e64 v52, v52, v81, s[0:1]
	s_waitcnt lgkmcnt(1)
	v_add_f32_e32 v55, v55, v61
	s_waitcnt lgkmcnt(0)
	v_add_f32_e32 v52, v52, v62
	v_cndmask_b32_e64 v60, v53, v55, s[38:39]
	v_cndmask_b32_e64 v53, v55, v53, s[38:39]
	v_cndmask_b32_e64 v55, v54, v52, s[38:39]
	v_cndmask_b32_e64 v52, v52, v54, s[38:39]
	v_add_f32_dpp v53, v60, v53 row_ror:8 row_mask:0xf bank_mask:0xf bound_ctrl:1
	s_nop 0
	v_add_f32_dpp v52, v55, v52 row_ror:8 row_mask:0xf bank_mask:0xf bound_ctrl:1
	v_cndmask_b32_e64 v54, v53, v52, s[42:43]
	v_cndmask_b32_e64 v52, v52, v53, s[42:43]
	v_mov_b32_e32 v53, v35
	v_mov_b32_e32 v55, v35
	s_nop 0
	v_mov_b32_dpp v53, v54 row_ror:4 row_mask:0xf bank_mask:0xf
	v_mov_b32_dpp v55, v54 row_ror:12 row_mask:0xf bank_mask:0xf
	v_cndmask_b32_e64 v53, v53, v55, s[42:43]
	v_add_f32_e32 v52, v52, v53
	v_mov_b32_e32 v53, 0
	s_nop 0
	v_add_f32_dpp v52, v52, v52 quad_perm:[2,3,0,1] row_mask:0xf bank_mask:0xf bound_ctrl:1
	s_nop 1
	v_mov_b32_dpp v53, v52 quad_perm:[1,0,3,2] row_mask:0xf bank_mask:0xf
	s_and_saveexec_b64 s[2:3], s[44:45]
	s_cbranch_execz .LBB0_1195
	v_add_f32_e32 v52, v52, v53
	v_add_f32_e32 v52, v34, v52
	v_exp_f32_e32 v52, v52
	v_add_u32_e32 v54, 0x80, v126
	v_add_f32_e32 v53, 1.0, v52
	v_rcp_f32_e32 v53, v53
	s_nop 0
	v_mul_f32_e32 v52, v52, v53
	ds_write2st64_b32 v54, v53, v52 offset0:5 offset1:69
.LBB0_1195:
	s_or_b64 exec, exec, s[2:3]
	s_waitcnt vmcnt(17)
	v_pk_mul_f32 v[52:53], v[6:7], v[44:45]
	s_nop 0
	v_pk_fma_f32 v[52:53], v[46:47], v[8:9], v[52:53]
	s_nop 0
	v_add_f32_e32 v54, v52, v53
	s_waitcnt vmcnt(16)
	v_pk_mul_f32 v[52:53], v[2:3], v[36:37]
	s_nop 0
	v_pk_fma_f32 v[52:53], v[38:39], v[4:5], v[52:53]
	s_nop 0
	v_add_f32_e32 v55, v52, v53
	v_pk_mul_f32 v[52:53], v[14:15], v[44:45]
	s_nop 0
	v_pk_fma_f32 v[52:53], v[46:47], v[16:17], v[52:53]
	s_nop 0
	v_add_f32_e32 v60, v52, v53
	v_pk_mul_f32 v[52:53], v[10:11], v[36:37]
	s_nop 0
	v_pk_fma_f32 v[52:53], v[38:39], v[12:13], v[52:53]
	s_nop 0
	v_add_f32_e32 v61, v52, v53
	v_pk_mul_f32 v[52:53], v[22:23], v[44:45]
	v_pk_mul_f32 v[44:45], v[30:31], v[44:45]
	v_pk_fma_f32 v[52:53], v[46:47], v[24:25], v[52:53]
	v_pk_fma_f32 v[44:45], v[46:47], v[32:33], v[44:45]
	v_add_f32_e32 v62, v52, v53
	v_add_f32_e32 v44, v44, v45
	v_cndmask_b32_e64 v45, v54, v62, s[0:1]
	ds_bpermute_b32 v45, v125, v45
	v_pk_mul_f32 v[52:53], v[18:19], v[36:37]
	v_pk_mul_f32 v[36:37], v[26:27], v[36:37]
	v_pk_fma_f32 v[52:53], v[38:39], v[20:21], v[52:53]
	v_pk_fma_f32 v[36:37], v[38:39], v[28:29], v[36:37]
	v_add_f32_e32 v52, v52, v53
	v_add_f32_e32 v36, v36, v37
	v_cndmask_b32_e64 v37, v62, v54, s[0:1]
	v_cndmask_b32_e64 v38, v55, v52, s[0:1]
	s_waitcnt lgkmcnt(0)
	v_add_f32_e32 v37, v37, v45
	ds_bpermute_b32 v38, v125, v38
	v_cndmask_b32_e64 v45, v60, v44, s[0:1]
	v_cndmask_b32_e64 v46, v61, v36, s[0:1]
	ds_bpermute_b32 v45, v125, v45
	ds_bpermute_b32 v46, v125, v46
	v_cndmask_b32_e64 v39, v52, v55, s[0:1]
	s_waitcnt lgkmcnt(2)
	v_add_f32_e32 v38, v39, v38
	v_cndmask_b32_e64 v39, v44, v60, s[0:1]
	v_cndmask_b32_e64 v36, v36, v61, s[0:1]
	s_waitcnt lgkmcnt(1)
	v_add_f32_e32 v39, v39, v45
	s_waitcnt lgkmcnt(0)
	v_add_f32_e32 v36, v36, v46
	v_cndmask_b32_e64 v44, v37, v39, s[38:39]
	v_cndmask_b32_e64 v37, v39, v37, s[38:39]
	v_cndmask_b32_e64 v39, v38, v36, s[38:39]
	v_cndmask_b32_e64 v36, v36, v38, s[38:39]
	v_add_f32_dpp v37, v44, v37 row_ror:8 row_mask:0xf bank_mask:0xf bound_ctrl:1
	s_nop 0
	v_add_f32_dpp v36, v39, v36 row_ror:8 row_mask:0xf bank_mask:0xf bound_ctrl:1
	v_cndmask_b32_e64 v38, v37, v36, s[42:43]
	v_cndmask_b32_e64 v36, v36, v37, s[42:43]
	v_mov_b32_e32 v37, v35
	v_mov_b32_e32 v39, v35
	s_nop 0
	v_mov_b32_dpp v37, v38 row_ror:4 row_mask:0xf bank_mask:0xf
	v_mov_b32_dpp v39, v38 row_ror:12 row_mask:0xf bank_mask:0xf
	v_cndmask_b32_e64 v37, v37, v39, s[42:43]
	v_add_f32_e32 v36, v36, v37
	v_mov_b32_e32 v37, 0
	s_nop 0
	v_add_f32_dpp v36, v36, v36 quad_perm:[2,3,0,1] row_mask:0xf bank_mask:0xf bound_ctrl:1
	s_nop 1
	v_mov_b32_dpp v37, v36 quad_perm:[1,0,3,2] row_mask:0xf bank_mask:0xf
	s_and_saveexec_b64 s[2:3], s[44:45]
	s_cbranch_execz .LBB0_1197
	v_add_f32_e32 v36, v36, v37
	v_add_f32_e32 v36, v34, v36
	v_exp_f32_e32 v36, v36
	v_add_u32_e32 v38, 0xc0, v126
	v_add_f32_e32 v37, 1.0, v36
	v_rcp_f32_e32 v37, v37
	s_nop 0
	v_mul_f32_e32 v36, v36, v37
	ds_write2st64_b32 v38, v37, v36 offset0:5 offset1:69

; #define DEC_LOADV(dst, i0) do { asm volatile("" ::: "memory"); _Pragma("unroll") for (int u = 0; u < 4; ++u) { const float* vr = cv + rbase + (size_t)((i0) + u) * 512; dst[u][0] = __builtin_nontemporal_load((const f32x4*)(vr + 4 * lane)); dst[u][1] = __builtin_nontemporal_load((const f32x4*)(vr + 256 + 4 * lane)); } } while (0)
; __device__ __forceinline__ void decode_item(Frame& F, const Args& a, int l, int item, unsigned char* ws) {
;     ...
;         DEC_LOADV(va, 0); DEC_LOADV(vb, 4); DEC_ACC(va, 0); DEC_LOADV(va, 8); DEC_ACC(vb, 4); DEC_LOADV(vb, 12); DEC_ACC(va, 8); DEC_LOADV(va, 16); DEC_ACC(vb, 12); DEC_LOADV(vb, 20); DEC_ACC(va, 16); DEC_LOADV(va, 24); DEC_ACC(vb, 20); DEC_LOADV(vb, 28); DEC_ACC(va, 24); DEC_ACC(vb, 28);
.LBB0_1221:
	s_or_b64 exec, exec, s[0:1]
	v_readlane_b32 s36, v252, 21
	v_readlane_b32 s42, v252, 27
	v_readlane_b32 s43, v252, 28
	s_add_u32 s0, s42, s6
	s_addc_u32 s1, s43, s7
	v_lshl_add_u64 v[2:3], v[118:119], 2, s[0:1]
	s_waitcnt lgkmcnt(0)
	s_waitcnt lgkmcnt(0)
	s_barrier
	v_lshl_add_u64 v[86:87], v[116:117], 2, v[2:3]
	global_load_dwordx4 v[60:63], v[86:87], off nt
	global_load_dwordx4 v[66:69], v[86:87], off offset:1024 nt
	global_load_dwordx4 v[56:59], v[86:87], off offset:2048 nt
	global_load_dwordx4 v[52:55], v[86:87], off offset:3072 nt
	v_add_co_u32_e32 v184, vcc, 0x5000, v86
	s_nop 1
	v_addc_co_u32_e32 v185, vcc, 0, v87, vcc
	v_add_co_u32_e32 v186, vcc, 0x7000, v86
	s_nop 1
	v_addc_co_u32_e32 v187, vcc, 0, v87, vcc
	v_add_co_u32_e32 v188, vcc, 0x9000, v86
	s_nop 1
	v_addc_co_u32_e32 v189, vcc, 0, v87, vcc
	v_add_co_u32_e32 v190, vcc, 0xb000, v86
	s_nop 1
	v_addc_co_u32_e32 v191, vcc, 0, v87, vcc
	v_add_co_u32_e32 v192, vcc, 0xd000, v86
	s_nop 1
	v_addc_co_u32_e32 v193, vcc, 0, v87, vcc
	v_add_co_u32_e32 v194, vcc, 0xf000, v86
	s_nop 1
	v_addc_co_u32_e32 v195, vcc, 0, v87, vcc
	v_add_co_u32_e32 v2, vcc, s69, v86
	s_movk_i32 s0, 0x2000
	s_nop 0
	v_addc_co_u32_e32 v3, vcc, 0, v87, vcc
	v_add_co_u32_e32 v4, vcc, s0, v86
	s_movk_i32 s0, 0x3000
	s_nop 0
	v_addc_co_u32_e32 v5, vcc, 0, v87, vcc
	global_load_dwordx4 v[44:47], v[4:5], off offset:-4096 nt
	global_load_dwordx4 v[48:51], v[2:3], off offset:1024 nt
	global_load_dwordx4 v[40:43], v[2:3], off offset:2048 nt
	global_load_dwordx4 v[36:39], v[2:3], off offset:3072 nt
	global_load_dwordx4 v[30:33], v[4:5], off nt
	global_load_dwordx4 v[26:29], v[4:5], off offset:1024 nt
	global_load_dwordx4 v[22:25], v[4:5], off offset:2048 nt
	global_load_dwordx4 v[18:21], v[4:5], off offset:3072 nt
	v_add_co_u32_e32 v2, vcc, s0, v86
	v_lshlrev_b32_e64 v34, 11, s18
	s_nop 0
	v_addc_co_u32_e32 v3, vcc, 0, v87, vcc
	v_add_co_u32_e32 v64, vcc, s95, v86
	v_and_b32_e32 v70, 0xffffffe0, v122
	s_nop 0
	v_addc_co_u32_e32 v65, vcc, 0, v87, vcc
	global_load_dwordx4 v[14:17], v[64:65], off offset:-4096 nt
	global_load_dwordx4 v[10:13], v[2:3], off offset:1024 nt
	global_load_dwordx4 v[6:9], v[2:3], off offset:2048 nt
	s_nop 0
	global_load_dwordx4 v[2:5], v[2:3], off offset:3072 nt
	global_load_dwordx4 v[204:207], v[184:185], off offset:-4096
	global_load_dwordx4 v[204:207], v[184:185], off offset:-3072
	global_load_dwordx4 v[204:207], v[184:185], off offset:-2048
	global_load_dwordx4 v[204:207], v[184:185], off offset:-1024
	global_load_dwordx4 v[204:207], v[184:185], off
	global_load_dwordx4 v[204:207], v[184:185], off offset:1024
	global_load_dwordx4 v[204:207], v[184:185], off offset:2048
	global_load_dwordx4 v[204:207], v[184:185], off offset:3072
	global_load_dwordx4 v[204:207], v[186:187], off offset:-4096
	global_load_dwordx4 v[204:207], v[186:187], off offset:-3072
	global_load_dwordx4 v[204:207], v[186:187], off offset:-2048
	global_load_dwordx4 v[204:207], v[186:187], off offset:-1024
	global_load_dwordx4 v[204:207], v[186:187], off
	global_load_dwordx4 v[204:207], v[186:187], off offset:1024
	global_load_dwordx4 v[204:207], v[186:187], off offset:2048
	global_load_dwordx4 v[204:207], v[186:187], off offset:3072
	global_load_dwordx4 v[204:207], v[188:189], off offset:-4096
	global_load_dwordx4 v[204:207], v[188:189], off offset:-3072
	global_load_dwordx4 v[204:207], v[188:189], off offset:-2048
	global_load_dwordx4 v[204:207], v[188:189], off offset:-1024
	global_load_dwordx4 v[204:207], v[188:189], off
	global_load_dwordx4 v[204:207], v[188:189], off offset:1024
	global_load_dwordx4 v[204:207], v[188:189], off offset:2048
	global_load_dwordx4 v[204:207], v[188:189], off offset:3072
	v_add3_u32 v34, 0, v34, v70
	ds_read_b128 v[70:73], v34 offset:16384
	ds_read_b128 v[74:77], v34 offset:16400
	s_movk_i32 s0, 0x5000
	v_readlane_b32 s37, v252, 22
	v_readlane_b32 s38, v252, 23
	v_readlane_b32 s39, v252, 24
	v_readlane_b32 s40, v252, 25
	v_readlane_b32 s41, v252, 26
	v_readlane_b32 s44, v252, 29
	v_readlane_b32 s45, v252, 30
	v_readlane_b32 s46, v252, 31
	v_readlane_b32 s47, v252, 32
	v_readlane_b32 s48, v252, 33
	v_readlane_b32 s49, v252, 34
	v_readlane_b32 s50, v252, 35
	v_readlane_b32 s51, v252, 36
	s_waitcnt vmcnt(39) lgkmcnt(1)
	v_pk_fma_f32 v[78:79], v[62:63], v[70:71], 0 op_sel_hi:[1,0,0]
	v_pk_fma_f32 v[80:81], v[60:61], v[70:71], 0 op_sel_hi:[1,0,0]
	s_waitcnt vmcnt(38)
	v_pk_fma_f32 v[82:83], v[68:69], v[70:71], 0 op_sel:[0,1,0] op_sel_hi:[1,1,0]
	v_pk_fma_f32 v[88:89], v[66:67], v[70:71], 0 op_sel:[0,1,0] op_sel_hi:[1,1,0]
	v_pk_fma_f32 v[92:93], v[60:61], v[72:73], 0 op_sel_hi:[1,0,0]
	v_mov_b32_e32 v70, v73
	s_waitcnt lgkmcnt(0)
	v_pk_fma_f32 v[98:99], v[60:61], v[74:75], 0 op_sel_hi:[1,0,0]
	v_pk_fma_f32 v[104:105], v[60:61], v[76:77], 0 op_sel_hi:[1,0,0]
	v_mov_b32_e32 v60, v77
	v_pk_fma_f32 v[90:91], v[62:63], v[72:73], 0 op_sel_hi:[1,0,0]
	v_pk_fma_f32 v[72:73], v[68:69], v[70:71], 0 op_sel_hi:[1,0,0]
	v_pk_fma_f32 v[94:95], v[66:67], v[70:71], 0 op_sel_hi:[1,0,0]
	v_pk_fma_f32 v[96:97], v[62:63], v[74:75], 0 op_sel_hi:[1,0,0]
	v_pk_fma_f32 v[100:101], v[68:69], v[74:75], 0 op_sel:[0,1,0] op_sel_hi:[1,1,0]
	v_pk_fma_f32 v[102:103], v[62:63], v[76:77], 0 op_sel_hi:[1,0,0]
	v_pk_fma_f32 v[76:77], v[68:69], v[60:61], 0 op_sel_hi:[1,0,0]
	v_pk_fma_f32 v[106:107], v[66:67], v[60:61], 0 op_sel_hi:[1,0,0]
	ds_read_b128 v[60:63], v34 offset:16448
	ds_read_b128 v[68:71], v34 offset:16464
	v_pk_fma_f32 v[74:75], v[66:67], v[74:75], 0 op_sel:[0,1,0] op_sel_hi:[1,1,0]
	s_waitcnt vmcnt(37) lgkmcnt(1)
; #define DEC_LOADV(dst, i0) do { asm volatile("" ::: "memory"); _Pragma("unroll") for (int u = 0; u < 4; ++u) { const float* vr = cv + rbase + (size_t)((i0) + u) * 512; dst[u][0] = __builtin_nontemporal_load((const f32x4*)(vr + 4 * lane)); dst[u][1] = __builtin_nontemporal_load((const f32x4*)(vr + 256 + 4 * lane)); } } while (0)
; __device__ __forceinline__ void decode_item(Frame& F, const Args& a, int l, int item, unsigned char* ws) {
;     ...
;         DEC_LOADV(va, 0); DEC_LOADV(vb, 4); DEC_ACC(va, 0); DEC_LOADV(va, 8); DEC_ACC(vb, 4); DEC_LOADV(vb, 12); DEC_ACC(va, 8); DEC_LOADV(va, 16); DEC_ACC(vb, 12); DEC_LOADV(vb, 20); DEC_ACC(va, 16); DEC_LOADV(va, 24); DEC_ACC(vb, 20); DEC_LOADV(vb, 28); DEC_ACC(va, 24); DEC_ACC(vb, 28);
	v_pk_fma_f32 v[92:93], v[56:57], v[62:63], v[92:93] op_sel_hi:[1,0,1]
	v_pk_fma_f32 v[90:91], v[58:59], v[62:63], v[90:91] op_sel_hi:[1,0,1]
	v_mov_b32_e32 v62, v63
	v_pk_fma_f32 v[80:81], v[56:57], v[60:61], v[80:81] op_sel_hi:[1,0,1]
	v_pk_fma_f32 v[78:79], v[58:59], v[60:61], v[78:79] op_sel_hi:[1,0,1]
	s_waitcnt vmcnt(36)
	v_pk_fma_f32 v[88:89], v[52:53], v[60:61], v[88:89] op_sel:[0,1,0]
	v_pk_fma_f32 v[82:83], v[54:55], v[60:61], v[82:83] op_sel:[0,1,0]
	v_pk_fma_f32 v[60:61], v[52:53], v[62:63], v[94:95] op_sel_hi:[1,0,1]
	v_pk_fma_f32 v[94:95], v[54:55], v[62:63], v[72:73] op_sel_hi:[1,0,1]
	s_waitcnt lgkmcnt(0)
	v_pk_fma_f32 v[62:63], v[56:57], v[68:69], v[98:99] op_sel_hi:[1,0,1]
	v_pk_fma_f32 v[96:97], v[58:59], v[68:69], v[96:97] op_sel_hi:[1,0,1]
	v_pk_fma_f32 v[66:67], v[52:53], v[68:69], v[74:75] op_sel:[0,1,0]
	v_pk_fma_f32 v[98:99], v[54:55], v[68:69], v[100:101] op_sel:[0,1,0]
	v_mov_b32_e32 v68, v71
	v_pk_fma_f32 v[56:57], v[56:57], v[70:71], v[104:105] op_sel_hi:[1,0,1]
	v_pk_fma_f32 v[58:59], v[58:59], v[70:71], v[102:103] op_sel_hi:[1,0,1]
	v_pk_fma_f32 v[52:53], v[52:53], v[68:69], v[106:107] op_sel_hi:[1,0,1]
	v_pk_fma_f32 v[54:55], v[54:55], v[68:69], v[76:77] op_sel_hi:[1,0,1]
	ds_read_b128 v[68:71], v34 offset:16512
	ds_read_b128 v[72:75], v34 offset:16528
	s_waitcnt vmcnt(35) lgkmcnt(1)
	v_pk_fma_f32 v[76:77], v[46:47], v[68:69], v[78:79] op_sel_hi:[1,0,1]
	v_pk_fma_f32 v[78:79], v[44:45], v[68:69], v[80:81] op_sel_hi:[1,0,1]
	s_waitcnt vmcnt(34)
	v_pk_fma_f32 v[80:81], v[50:51], v[68:69], v[82:83] op_sel:[0,1,0]
	v_pk_fma_f32 v[68:69], v[48:49], v[68:69], v[88:89] op_sel:[0,1,0]
	v_pk_fma_f32 v[82:83], v[46:47], v[70:71], v[90:91] op_sel_hi:[1,0,1]
	v_pk_fma_f32 v[88:89], v[44:45], v[70:71], v[92:93] op_sel_hi:[1,0,1]
	v_mov_b32_e32 v70, v71
	s_waitcnt lgkmcnt(0)
	v_pk_fma_f32 v[62:63], v[44:45], v[72:73], v[62:63] op_sel_hi:[1,0,1]
	v_pk_fma_f32 v[56:57], v[44:45], v[74:75], v[56:57] op_sel_hi:[1,0,1]
	v_mov_b32_e32 v44, v75
	v_pk_fma_f32 v[90:91], v[50:51], v[70:71], v[94:95] op_sel_hi:[1,0,1]
	v_pk_fma_f32 v[60:61], v[48:49], v[70:71], v[60:61] op_sel_hi:[1,0,1]
	v_pk_fma_f32 v[70:71], v[46:47], v[72:73], v[96:97] op_sel_hi:[1,0,1]
	v_pk_fma_f32 v[92:93], v[50:51], v[72:73], v[98:99] op_sel:[0,1,0]
	v_pk_fma_f32 v[66:67], v[48:49], v[72:73], v[66:67] op_sel:[0,1,0]
	v_pk_fma_f32 v[58:59], v[46:47], v[74:75], v[58:59] op_sel_hi:[1,0,1]
	v_pk_fma_f32 v[54:55], v[50:51], v[44:45], v[54:55] op_sel_hi:[1,0,1]
	v_pk_fma_f32 v[52:53], v[48:49], v[44:45], v[52:53] op_sel_hi:[1,0,1]
	ds_read_b128 v[44:47], v34 offset:16576
	ds_read_b128 v[48:51], v34 offset:16592
	s_waitcnt vmcnt(33) lgkmcnt(1)
	v_pk_fma_f32 v[72:73], v[42:43], v[44:45], v[76:77] op_sel_hi:[1,0,1]
	v_pk_fma_f32 v[74:75], v[40:41], v[44:45], v[78:79] op_sel_hi:[1,0,1]
	s_waitcnt vmcnt(32)
	v_pk_fma_f32 v[80:81], v[38:39], v[44:45], v[80:81] op_sel:[0,1,0]
	v_pk_fma_f32 v[94:95], v[36:37], v[44:45], v[68:69] op_sel:[0,1,0]
	v_pk_fma_f32 v[88:89], v[40:41], v[46:47], v[88:89] op_sel_hi:[1,0,1]
	v_mov_b32_e32 v44, v47
	s_waitcnt lgkmcnt(0)
	v_pk_fma_f32 v[100:101], v[40:41], v[48:49], v[62:63] op_sel_hi:[1,0,1]
	v_pk_fma_f32 v[106:107], v[40:41], v[50:51], v[56:57] op_sel_hi:[1,0,1]
	v_mov_b32_e32 v40, v51
	v_pk_fma_f32 v[96:97], v[36:37], v[44:45], v[60:61] op_sel_hi:[1,0,1]
	v_pk_fma_f32 v[98:99], v[42:43], v[48:49], v[70:71] op_sel_hi:[1,0,1]
	v_pk_fma_f32 v[108:109], v[38:39], v[40:41], v[54:55] op_sel_hi:[1,0,1]
	v_pk_fma_f32 v[110:111], v[36:37], v[40:41], v[52:53] op_sel_hi:[1,0,1]
	global_load_dwordx4 v[68:71], v[64:65], off nt
	global_load_dwordx4 v[76:79], v[64:65], off offset:1024 nt
	global_load_dwordx4 v[60:63], v[64:65], off offset:2048 nt
	global_load_dwordx4 v[52:55], v[64:65], off offset:3072 nt
	v_pk_fma_f32 v[102:103], v[36:37], v[48:49], v[66:67] op_sel:[0,1,0]
	v_add_co_u32_e32 v36, vcc, s0, v86
	s_movk_i32 s0, 0x6000
	s_nop 0
	v_addc_co_u32_e32 v37, vcc, 0, v87, vcc
	v_add_co_u32_e32 v112, vcc, s0, v86
	v_pk_fma_f32 v[82:83], v[42:43], v[46:47], v[82:83] op_sel_hi:[1,0,1]
	s_nop 0
	v_addc_co_u32_e32 v113, vcc, 0, v87, vcc
	v_pk_fma_f32 v[90:91], v[38:39], v[44:45], v[90:91] op_sel_hi:[1,0,1]
	v_pk_fma_f32 v[92:93], v[38:39], v[48:49], v[92:93] op_sel:[0,1,0]
	v_pk_fma_f32 v[104:105], v[42:43], v[50:51], v[58:59] op_sel_hi:[1,0,1]
	global_load_dwordx4 v[48:51], v[112:113], off offset:-4096 nt
	global_load_dwordx4 v[44:47], v[36:37], off offset:1024 nt
	global_load_dwordx4 v[40:43], v[36:37], off offset:2048 nt
	s_nop 0
	global_load_dwordx4 v[36:39], v[36:37], off offset:3072 nt
	global_load_dwordx4 v[204:207], v[190:191], off offset:-4096
	global_load_dwordx4 v[204:207], v[190:191], off offset:-3072
	global_load_dwordx4 v[204:207], v[190:191], off offset:-2048
	global_load_dwordx4 v[204:207], v[190:191], off offset:-1024
	global_load_dwordx4 v[204:207], v[190:191], off
	global_load_dwordx4 v[204:207], v[190:191], off offset:1024
	global_load_dwordx4 v[204:207], v[190:191], off offset:2048
	global_load_dwordx4 v[204:207], v[190:191], off offset:3072
	ds_read_b128 v[56:59], v34 offset:16640
	ds_read_b128 v[64:67], v34 offset:16656
	s_movk_i32 s0, 0x7000
	s_waitcnt vmcnt(47) lgkmcnt(1)
	v_pk_fma_f32 v[82:83], v[32:33], v[58:59], v[82:83] op_sel_hi:[1,0,1]
	v_pk_fma_f32 v[88:89], v[30:31], v[58:59], v[88:89] op_sel_hi:[1,0,1]
	v_mov_b32_e32 v58, v59
	v_pk_fma_f32 v[74:75], v[30:31], v[56:57], v[74:75] op_sel_hi:[1,0,1]
	s_waitcnt vmcnt(46)
	v_pk_fma_f32 v[90:91], v[28:29], v[58:59], v[90:91] op_sel_hi:[1,0,1]
	v_pk_fma_f32 v[58:59], v[26:27], v[58:59], v[96:97] op_sel_hi:[1,0,1]
	s_waitcnt lgkmcnt(0)
; #define DEC_LOADV(dst, i0) do { asm volatile("" ::: "memory"); _Pragma("unroll") for (int u = 0; u < 4; ++u) { const float* vr = cv + rbase + (size_t)((i0) + u) * 512; dst[u][0] = __builtin_nontemporal_load((const f32x4*)(vr + 4 * lane)); dst[u][1] = __builtin_nontemporal_load((const f32x4*)(vr + 256 + 4 * lane)); } } while (0)
; __device__ __forceinline__ void decode_item(Frame& F, const Args& a, int l, int item, unsigned char* ws) {
;     ...
;         DEC_LOADV(va, 0); DEC_LOADV(vb, 4); DEC_ACC(va, 0); DEC_LOADV(va, 8); DEC_ACC(vb, 4); DEC_LOADV(vb, 12); DEC_ACC(va, 8); DEC_LOADV(va, 16); DEC_ACC(vb, 12); DEC_LOADV(vb, 20); DEC_ACC(va, 16); DEC_LOADV(va, 24); DEC_ACC(vb, 20); DEC_LOADV(vb, 28); DEC_ACC(va, 24); DEC_ACC(vb, 28);
	v_pk_fma_f32 v[96:97], v[30:31], v[64:65], v[100:101] op_sel_hi:[1,0,1]
	v_pk_fma_f32 v[100:101], v[30:31], v[66:67], v[106:107] op_sel_hi:[1,0,1]
	v_mov_b32_e32 v30, v67
	v_pk_fma_f32 v[72:73], v[32:33], v[56:57], v[72:73] op_sel_hi:[1,0,1]
	v_pk_fma_f32 v[80:81], v[28:29], v[56:57], v[80:81] op_sel:[0,1,0]
	v_pk_fma_f32 v[56:57], v[26:27], v[56:57], v[94:95] op_sel:[0,1,0]
	v_pk_fma_f32 v[94:95], v[32:33], v[64:65], v[98:99] op_sel_hi:[1,0,1]
	v_pk_fma_f32 v[92:93], v[28:29], v[64:65], v[92:93] op_sel:[0,1,0]
	v_pk_fma_f32 v[64:65], v[26:27], v[64:65], v[102:103] op_sel:[0,1,0]
	v_pk_fma_f32 v[98:99], v[32:33], v[66:67], v[104:105] op_sel_hi:[1,0,1]
	v_pk_fma_f32 v[66:67], v[28:29], v[30:31], v[108:109] op_sel_hi:[1,0,1]
	v_pk_fma_f32 v[102:103], v[26:27], v[30:31], v[110:111] op_sel_hi:[1,0,1]
	ds_read_b128 v[26:29], v34 offset:16704
	ds_read_b128 v[30:33], v34 offset:16720
	s_waitcnt vmcnt(45) lgkmcnt(1)
	v_pk_fma_f32 v[72:73], v[24:25], v[26:27], v[72:73] op_sel_hi:[1,0,1]
	v_pk_fma_f32 v[74:75], v[22:23], v[26:27], v[74:75] op_sel_hi:[1,0,1]
	s_waitcnt vmcnt(44)
	v_pk_fma_f32 v[80:81], v[20:21], v[26:27], v[80:81] op_sel:[0,1,0]
	v_pk_fma_f32 v[26:27], v[18:19], v[26:27], v[56:57] op_sel:[0,1,0]
	v_pk_fma_f32 v[56:57], v[24:25], v[28:29], v[82:83] op_sel_hi:[1,0,1]
	v_pk_fma_f32 v[82:83], v[22:23], v[28:29], v[88:89] op_sel_hi:[1,0,1]
	v_mov_b32_e32 v28, v29
	v_pk_fma_f32 v[88:89], v[20:21], v[28:29], v[90:91] op_sel_hi:[1,0,1]
	v_pk_fma_f32 v[28:29], v[18:19], v[28:29], v[58:59] op_sel_hi:[1,0,1]
	s_waitcnt lgkmcnt(0)
	v_pk_fma_f32 v[58:59], v[24:25], v[30:31], v[94:95] op_sel_hi:[1,0,1]
	v_pk_fma_f32 v[90:91], v[22:23], v[30:31], v[96:97] op_sel_hi:[1,0,1]
	v_pk_fma_f32 v[94:95], v[22:23], v[32:33], v[100:101] op_sel_hi:[1,0,1]
	v_mov_b32_e32 v22, v33
	v_pk_fma_f32 v[92:93], v[20:21], v[30:31], v[92:93] op_sel:[0,1,0]
	v_pk_fma_f32 v[30:31], v[18:19], v[30:31], v[64:65] op_sel:[0,1,0]
	v_pk_fma_f32 v[64:65], v[24:25], v[32:33], v[98:99] op_sel_hi:[1,0,1]
	v_pk_fma_f32 v[32:33], v[20:21], v[22:23], v[66:67] op_sel_hi:[1,0,1]
	v_pk_fma_f32 v[66:67], v[18:19], v[22:23], v[102:103] op_sel_hi:[1,0,1]
	ds_read_b128 v[18:21], v34 offset:16768
	ds_read_b128 v[22:25], v34 offset:16784
	s_waitcnt vmcnt(43) lgkmcnt(1)
	v_pk_fma_f32 v[72:73], v[16:17], v[18:19], v[72:73] op_sel_hi:[1,0,1]
	v_pk_fma_f32 v[74:75], v[14:15], v[18:19], v[74:75] op_sel_hi:[1,0,1]
	s_waitcnt vmcnt(42)
	v_pk_fma_f32 v[80:81], v[12:13], v[18:19], v[80:81] op_sel:[0,1,0]
	v_pk_fma_f32 v[18:19], v[10:11], v[18:19], v[26:27] op_sel:[0,1,0]
	v_pk_fma_f32 v[26:27], v[16:17], v[20:21], v[56:57] op_sel_hi:[1,0,1]
	v_pk_fma_f32 v[56:57], v[14:15], v[20:21], v[82:83] op_sel_hi:[1,0,1]
	v_mov_b32_e32 v20, v21
	v_pk_fma_f32 v[82:83], v[12:13], v[20:21], v[88:89] op_sel_hi:[1,0,1]
	v_pk_fma_f32 v[20:21], v[10:11], v[20:21], v[28:29] op_sel_hi:[1,0,1]
	s_waitcnt lgkmcnt(0)
	v_pk_fma_f32 v[28:29], v[16:17], v[22:23], v[58:59] op_sel_hi:[1,0,1]
	v_pk_fma_f32 v[58:59], v[14:15], v[22:23], v[90:91] op_sel_hi:[1,0,1]
	v_pk_fma_f32 v[88:89], v[12:13], v[22:23], v[92:93] op_sel:[0,1,0]
	v_pk_fma_f32 v[22:23], v[10:11], v[22:23], v[30:31] op_sel:[0,1,0]
	v_pk_fma_f32 v[30:31], v[16:17], v[24:25], v[64:65] op_sel_hi:[1,0,1]
	v_pk_fma_f32 v[64:65], v[14:15], v[24:25], v[94:95] op_sel_hi:[1,0,1]
	v_mov_b32_e32 v14, v25
	v_pk_fma_f32 v[24:25], v[12:13], v[14:15], v[32:33] op_sel_hi:[1,0,1]
	v_pk_fma_f32 v[32:33], v[10:11], v[14:15], v[66:67] op_sel_hi:[1,0,1]
	ds_read_b128 v[10:13], v34 offset:16832
	ds_read_b128 v[14:17], v34 offset:16848
	s_waitcnt vmcnt(41) lgkmcnt(1)
	v_pk_fma_f32 v[90:91], v[8:9], v[10:11], v[72:73] op_sel_hi:[1,0,1]
	v_pk_fma_f32 v[92:93], v[6:7], v[10:11], v[74:75] op_sel_hi:[1,0,1]
	s_waitcnt vmcnt(40)
	v_pk_fma_f32 v[94:95], v[4:5], v[10:11], v[80:81] op_sel:[0,1,0]
	v_pk_fma_f32 v[96:97], v[2:3], v[10:11], v[18:19] op_sel:[0,1,0]
	v_mov_b32_e32 v10, v13
	v_pk_fma_f32 v[100:101], v[6:7], v[12:13], v[56:57] op_sel_hi:[1,0,1]
	v_pk_fma_f32 v[102:103], v[4:5], v[10:11], v[82:83] op_sel_hi:[1,0,1]
	s_waitcnt lgkmcnt(0)
	v_pk_fma_f32 v[108:109], v[6:7], v[14:15], v[58:59] op_sel_hi:[1,0,1]
	v_pk_fma_f32 v[110:111], v[6:7], v[16:17], v[64:65] op_sel_hi:[1,0,1]
	global_load_dwordx4 v[72:75], v[112:113], off nt
	global_load_dwordx4 v[80:83], v[112:113], off offset:1024 nt
	global_load_dwordx4 v[64:67], v[112:113], off offset:2048 nt
	global_load_dwordx4 v[56:59], v[112:113], off offset:3072 nt
	v_mov_b32_e32 v6, v17
	v_pk_fma_f32 v[104:105], v[2:3], v[10:11], v[20:21] op_sel_hi:[1,0,1]
	v_pk_fma_f32 v[22:23], v[2:3], v[14:15], v[22:23] op_sel:[0,1,0]
	v_pk_fma_f32 v[32:33], v[2:3], v[6:7], v[32:33] op_sel_hi:[1,0,1]
	v_add_co_u32_e32 v2, vcc, s0, v86
	s_mov_b32 s0, 0x8000
	s_nop 0
	v_addc_co_u32_e32 v3, vcc, 0, v87, vcc
	v_add_co_u32_e32 v112, vcc, s0, v86
	v_pk_fma_f32 v[98:99], v[8:9], v[12:13], v[26:27] op_sel_hi:[1,0,1]
	s_nop 0
	v_addc_co_u32_e32 v113, vcc, 0, v87, vcc
	v_pk_fma_f32 v[106:107], v[8:9], v[14:15], v[28:29] op_sel_hi:[1,0,1]
	v_pk_fma_f32 v[88:89], v[4:5], v[14:15], v[88:89] op_sel:[0,1,0]
	v_pk_fma_f32 v[24:25], v[4:5], v[6:7], v[24:25] op_sel_hi:[1,0,1]
	global_load_dwordx4 v[26:29], v[112:113], off offset:-4096 nt
	global_load_dwordx4 v[18:21], v[2:3], off offset:1024 nt
	global_load_dwordx4 v[10:13], v[2:3], off offset:2048 nt
	s_nop 0
	global_load_dwordx4 v[2:5], v[2:3], off offset:3072 nt
	global_load_dwordx4 v[204:207], v[192:193], off offset:-4096
	global_load_dwordx4 v[204:207], v[192:193], off offset:-3072
	global_load_dwordx4 v[204:207], v[192:193], off offset:-2048
	global_load_dwordx4 v[204:207], v[192:193], off offset:-1024
	global_load_dwordx4 v[204:207], v[192:193], off
	global_load_dwordx4 v[204:207], v[192:193], off offset:1024
	global_load_dwordx4 v[204:207], v[192:193], off offset:2048
	global_load_dwordx4 v[204:207], v[192:193], off offset:3072
	v_pk_fma_f32 v[30:31], v[8:9], v[16:17], v[30:31] op_sel_hi:[1,0,1]
	ds_read_b128 v[6:9], v34 offset:16896
	ds_read_b128 v[14:17], v34 offset:16912
	s_mov_b32 s0, 0x9000
	s_waitcnt vmcnt(31) lgkmcnt(1)
; #define DEC_LOADV(dst, i0) do { asm volatile("" ::: "memory"); _Pragma("unroll") for (int u = 0; u < 4; ++u) { const float* vr = cv + rbase + (size_t)((i0) + u) * 512; dst[u][0] = __builtin_nontemporal_load((const f32x4*)(vr + 4 * lane)); dst[u][1] = __builtin_nontemporal_load((const f32x4*)(vr + 256 + 4 * lane)); } } while (0)
; __device__ __forceinline__ void decode_item(Frame& F, const Args& a, int l, int item, unsigned char* ws) {
;     ...
;         DEC_LOADV(va, 0); DEC_LOADV(vb, 4); DEC_ACC(va, 0); DEC_LOADV(va, 8); DEC_ACC(vb, 4); DEC_LOADV(vb, 12); DEC_ACC(va, 8); DEC_LOADV(va, 16); DEC_ACC(vb, 12); DEC_LOADV(vb, 20); DEC_ACC(va, 16); DEC_LOADV(va, 24); DEC_ACC(vb, 20); DEC_LOADV(vb, 28); DEC_ACC(va, 24); DEC_ACC(vb, 28);
	v_pk_fma_f32 v[90:91], v[70:71], v[6:7], v[90:91] op_sel_hi:[1,0,1]
	v_pk_fma_f32 v[92:93], v[68:69], v[6:7], v[92:93] op_sel_hi:[1,0,1]
	s_waitcnt vmcnt(30)
	v_pk_fma_f32 v[94:95], v[78:79], v[6:7], v[94:95] op_sel:[0,1,0]
	v_pk_fma_f32 v[96:97], v[76:77], v[6:7], v[96:97] op_sel:[0,1,0]
	v_mov_b32_e32 v6, v9
	v_pk_fma_f32 v[102:103], v[78:79], v[6:7], v[102:103] op_sel_hi:[1,0,1]
	v_pk_fma_f32 v[104:105], v[76:77], v[6:7], v[104:105] op_sel_hi:[1,0,1]
	s_waitcnt lgkmcnt(0)
	v_mov_b32_e32 v6, v17
	v_pk_fma_f32 v[98:99], v[70:71], v[8:9], v[98:99] op_sel_hi:[1,0,1]
	v_pk_fma_f32 v[100:101], v[68:69], v[8:9], v[100:101] op_sel_hi:[1,0,1]
	v_pk_fma_f32 v[106:107], v[70:71], v[14:15], v[106:107] op_sel_hi:[1,0,1]
	v_pk_fma_f32 v[108:109], v[68:69], v[14:15], v[108:109] op_sel_hi:[1,0,1]
	v_pk_fma_f32 v[88:89], v[78:79], v[14:15], v[88:89] op_sel:[0,1,0]
	v_pk_fma_f32 v[22:23], v[76:77], v[14:15], v[22:23] op_sel:[0,1,0]
	v_pk_fma_f32 v[30:31], v[70:71], v[16:17], v[30:31] op_sel_hi:[1,0,1]
	v_pk_fma_f32 v[68:69], v[68:69], v[16:17], v[110:111] op_sel_hi:[1,0,1]
	v_pk_fma_f32 v[24:25], v[78:79], v[6:7], v[24:25] op_sel_hi:[1,0,1]
	v_pk_fma_f32 v[32:33], v[76:77], v[6:7], v[32:33] op_sel_hi:[1,0,1]
	ds_read_b128 v[6:9], v34 offset:16960
	ds_read_b128 v[14:17], v34 offset:16976
	s_waitcnt vmcnt(29) lgkmcnt(1)
	v_pk_fma_f32 v[70:71], v[62:63], v[6:7], v[90:91] op_sel_hi:[1,0,1]
	v_pk_fma_f32 v[76:77], v[60:61], v[6:7], v[92:93] op_sel_hi:[1,0,1]
	s_waitcnt vmcnt(28)
	v_pk_fma_f32 v[78:79], v[54:55], v[6:7], v[94:95] op_sel:[0,1,0]
	v_pk_fma_f32 v[90:91], v[52:53], v[6:7], v[96:97] op_sel:[0,1,0]
	v_mov_b32_e32 v6, v9
	v_pk_fma_f32 v[92:93], v[62:63], v[8:9], v[98:99] op_sel_hi:[1,0,1]
	v_pk_fma_f32 v[96:97], v[54:55], v[6:7], v[102:103] op_sel_hi:[1,0,1]
	v_pk_fma_f32 v[98:99], v[52:53], v[6:7], v[104:105] op_sel_hi:[1,0,1]
	s_waitcnt lgkmcnt(0)
	v_mov_b32_e32 v6, v17
	v_pk_fma_f32 v[94:95], v[60:61], v[8:9], v[100:101] op_sel_hi:[1,0,1]
	v_pk_fma_f32 v[100:101], v[62:63], v[14:15], v[106:107] op_sel_hi:[1,0,1]
	v_pk_fma_f32 v[102:103], v[60:61], v[14:15], v[108:109] op_sel_hi:[1,0,1]
	v_pk_fma_f32 v[88:89], v[54:55], v[14:15], v[88:89] op_sel:[0,1,0]
	v_pk_fma_f32 v[22:23], v[52:53], v[14:15], v[22:23] op_sel:[0,1,0]
	v_pk_fma_f32 v[30:31], v[62:63], v[16:17], v[30:31] op_sel_hi:[1,0,1]
	v_pk_fma_f32 v[60:61], v[60:61], v[16:17], v[68:69] op_sel_hi:[1,0,1]
	v_pk_fma_f32 v[24:25], v[54:55], v[6:7], v[24:25] op_sel_hi:[1,0,1]
	v_pk_fma_f32 v[32:33], v[52:53], v[6:7], v[32:33] op_sel_hi:[1,0,1]
	ds_read_b128 v[6:9], v34 offset:17024
	ds_read_b128 v[14:17], v34 offset:17040
	s_waitcnt vmcnt(27) lgkmcnt(1)
	v_pk_fma_f32 v[52:53], v[50:51], v[6:7], v[70:71] op_sel_hi:[1,0,1]
	v_pk_fma_f32 v[54:55], v[48:49], v[6:7], v[76:77] op_sel_hi:[1,0,1]
	s_waitcnt vmcnt(26)
	v_pk_fma_f32 v[62:63], v[46:47], v[6:7], v[78:79] op_sel:[0,1,0]
	v_pk_fma_f32 v[68:69], v[44:45], v[6:7], v[90:91] op_sel:[0,1,0]
	v_mov_b32_e32 v6, v9
	v_pk_fma_f32 v[78:79], v[46:47], v[6:7], v[96:97] op_sel_hi:[1,0,1]
	v_pk_fma_f32 v[90:91], v[44:45], v[6:7], v[98:99] op_sel_hi:[1,0,1]
	s_waitcnt lgkmcnt(0)
	v_mov_b32_e32 v6, v17
	v_pk_fma_f32 v[70:71], v[50:51], v[8:9], v[92:93] op_sel_hi:[1,0,1]
	v_pk_fma_f32 v[76:77], v[48:49], v[8:9], v[94:95] op_sel_hi:[1,0,1]
	v_pk_fma_f32 v[92:93], v[50:51], v[14:15], v[100:101] op_sel_hi:[1,0,1]
	v_pk_fma_f32 v[94:95], v[48:49], v[14:15], v[102:103] op_sel_hi:[1,0,1]
	v_pk_fma_f32 v[88:89], v[46:47], v[14:15], v[88:89] op_sel:[0,1,0]
	v_pk_fma_f32 v[22:23], v[44:45], v[14:15], v[22:23] op_sel:[0,1,0]
	v_pk_fma_f32 v[30:31], v[50:51], v[16:17], v[30:31] op_sel_hi:[1,0,1]
	v_pk_fma_f32 v[48:49], v[48:49], v[16:17], v[60:61] op_sel_hi:[1,0,1]
	v_pk_fma_f32 v[24:25], v[46:47], v[6:7], v[24:25] op_sel_hi:[1,0,1]
	v_pk_fma_f32 v[32:33], v[44:45], v[6:7], v[32:33] op_sel_hi:[1,0,1]
	ds_read_b128 v[6:9], v34 offset:17088
	ds_read_b128 v[14:17], v34 offset:17104
	s_waitcnt vmcnt(25) lgkmcnt(1)
	v_pk_fma_f32 v[96:97], v[42:43], v[6:7], v[52:53] op_sel_hi:[1,0,1]
	v_pk_fma_f32 v[98:99], v[40:41], v[6:7], v[54:55] op_sel_hi:[1,0,1]
	s_waitcnt vmcnt(24)
	v_pk_fma_f32 v[100:101], v[38:39], v[6:7], v[62:63] op_sel:[0,1,0]
	v_pk_fma_f32 v[68:69], v[36:37], v[6:7], v[68:69] op_sel:[0,1,0]
	v_mov_b32_e32 v6, v9
	v_pk_fma_f32 v[78:79], v[38:39], v[6:7], v[78:79] op_sel_hi:[1,0,1]
	v_pk_fma_f32 v[90:91], v[36:37], v[6:7], v[90:91] op_sel_hi:[1,0,1]
	s_waitcnt lgkmcnt(0)
	v_mov_b32_e32 v6, v17
	v_pk_fma_f32 v[88:89], v[38:39], v[14:15], v[88:89] op_sel:[0,1,0]
	v_pk_fma_f32 v[102:103], v[36:37], v[14:15], v[22:23] op_sel:[0,1,0]
	v_pk_fma_f32 v[108:109], v[38:39], v[6:7], v[24:25] op_sel_hi:[1,0,1]
	v_pk_fma_f32 v[110:111], v[36:37], v[6:7], v[32:33] op_sel_hi:[1,0,1]
	global_load_dwordx4 v[52:55], v[112:113], off nt
	global_load_dwordx4 v[60:63], v[112:113], off offset:1024 nt
	global_load_dwordx4 v[44:47], v[112:113], off offset:2048 nt
	global_load_dwordx4 v[36:39], v[112:113], off offset:3072 nt
	v_add_co_u32_e32 v6, vcc, s0, v86
	s_mov_b32 s0, 0xa000
	s_nop 0
	v_addc_co_u32_e32 v7, vcc, 0, v87, vcc
	v_add_co_u32_e32 v112, vcc, s0, v86
	v_pk_fma_f32 v[70:71], v[42:43], v[8:9], v[70:71] op_sel_hi:[1,0,1]
	s_nop 0
	v_addc_co_u32_e32 v113, vcc, 0, v87, vcc
	v_pk_fma_f32 v[76:77], v[40:41], v[8:9], v[76:77] op_sel_hi:[1,0,1]
	v_pk_fma_f32 v[92:93], v[42:43], v[14:15], v[92:93] op_sel_hi:[1,0,1]
	v_pk_fma_f32 v[94:95], v[40:41], v[14:15], v[94:95] op_sel_hi:[1,0,1]
	v_pk_fma_f32 v[104:105], v[42:43], v[16:17], v[30:31] op_sel_hi:[1,0,1]
	v_pk_fma_f32 v[106:107], v[40:41], v[16:17], v[48:49] op_sel_hi:[1,0,1]
	global_load_dwordx4 v[30:33], v[112:113], off offset:-4096 nt
	global_load_dwordx4 v[22:25], v[6:7], off offset:1024 nt
	global_load_dwordx4 v[14:17], v[6:7], off offset:2048 nt
	s_nop 0
	global_load_dwordx4 v[6:9], v[6:7], off offset:3072 nt
	global_load_dwordx4 v[204:207], v[194:195], off offset:-4096
	global_load_dwordx4 v[204:207], v[194:195], off offset:-3072
	global_load_dwordx4 v[204:207], v[194:195], off offset:-2048
	global_load_dwordx4 v[204:207], v[194:195], off offset:-1024
	global_load_dwordx4 v[204:207], v[194:195], off
	global_load_dwordx4 v[204:207], v[194:195], off offset:1024
	global_load_dwordx4 v[204:207], v[194:195], off offset:2048
	global_load_dwordx4 v[204:207], v[194:195], off offset:3072
	ds_read_b128 v[40:43], v34 offset:17152
	ds_read_b128 v[48:51], v34 offset:17168
	s_mov_b32 s0, 0xb000
	s_waitcnt vmcnt(31) lgkmcnt(1)
; #define DEC_LOADV(dst, i0) do { asm volatile("" ::: "memory"); _Pragma("unroll") for (int u = 0; u < 4; ++u) { const float* vr = cv + rbase + (size_t)((i0) + u) * 512; dst[u][0] = __builtin_nontemporal_load((const f32x4*)(vr + 4 * lane)); dst[u][1] = __builtin_nontemporal_load((const f32x4*)(vr + 256 + 4 * lane)); } } while (0)
; __device__ __forceinline__ void decode_item(Frame& F, const Args& a, int l, int item, unsigned char* ws) {
;     ...
;         DEC_LOADV(va, 0); DEC_LOADV(vb, 4); DEC_ACC(va, 0); DEC_LOADV(va, 8); DEC_ACC(vb, 4); DEC_LOADV(vb, 12); DEC_ACC(va, 8); DEC_LOADV(va, 16); DEC_ACC(vb, 12); DEC_LOADV(vb, 20); DEC_ACC(va, 16); DEC_LOADV(va, 24); DEC_ACC(vb, 20); DEC_LOADV(vb, 28); DEC_ACC(va, 24); DEC_ACC(vb, 28);
	v_pk_fma_f32 v[96:97], v[74:75], v[40:41], v[96:97] op_sel_hi:[1,0,1]
	v_pk_fma_f32 v[98:99], v[72:73], v[40:41], v[98:99] op_sel_hi:[1,0,1]
	s_waitcnt vmcnt(30)
	v_pk_fma_f32 v[100:101], v[82:83], v[40:41], v[100:101] op_sel:[0,1,0]
	v_pk_fma_f32 v[68:69], v[80:81], v[40:41], v[68:69] op_sel:[0,1,0]
	v_mov_b32_e32 v40, v43
	v_pk_fma_f32 v[78:79], v[82:83], v[40:41], v[78:79] op_sel_hi:[1,0,1]
	v_pk_fma_f32 v[90:91], v[80:81], v[40:41], v[90:91] op_sel_hi:[1,0,1]
	s_waitcnt lgkmcnt(0)
	v_mov_b32_e32 v40, v51
	v_pk_fma_f32 v[70:71], v[74:75], v[42:43], v[70:71] op_sel_hi:[1,0,1]
	v_pk_fma_f32 v[76:77], v[72:73], v[42:43], v[76:77] op_sel_hi:[1,0,1]
	v_pk_fma_f32 v[92:93], v[74:75], v[48:49], v[92:93] op_sel_hi:[1,0,1]
	v_pk_fma_f32 v[94:95], v[72:73], v[48:49], v[94:95] op_sel_hi:[1,0,1]
	v_pk_fma_f32 v[88:89], v[82:83], v[48:49], v[88:89] op_sel:[0,1,0]
	v_pk_fma_f32 v[102:103], v[80:81], v[48:49], v[102:103] op_sel:[0,1,0]
	v_pk_fma_f32 v[74:75], v[74:75], v[50:51], v[104:105] op_sel_hi:[1,0,1]
	v_pk_fma_f32 v[72:73], v[72:73], v[50:51], v[106:107] op_sel_hi:[1,0,1]
	v_pk_fma_f32 v[82:83], v[82:83], v[40:41], v[108:109] op_sel_hi:[1,0,1]
	v_pk_fma_f32 v[80:81], v[80:81], v[40:41], v[110:111] op_sel_hi:[1,0,1]
	ds_read_b128 v[40:43], v34 offset:17216
	ds_read_b128 v[48:51], v34 offset:17232
	s_waitcnt vmcnt(29) lgkmcnt(1)
	v_pk_fma_f32 v[96:97], v[66:67], v[40:41], v[96:97] op_sel_hi:[1,0,1]
	v_pk_fma_f32 v[98:99], v[64:65], v[40:41], v[98:99] op_sel_hi:[1,0,1]
	s_waitcnt vmcnt(28)
	v_pk_fma_f32 v[100:101], v[58:59], v[40:41], v[100:101] op_sel:[0,1,0]
	v_pk_fma_f32 v[68:69], v[56:57], v[40:41], v[68:69] op_sel:[0,1,0]
	v_mov_b32_e32 v40, v43
	v_pk_fma_f32 v[78:79], v[58:59], v[40:41], v[78:79] op_sel_hi:[1,0,1]
	v_pk_fma_f32 v[90:91], v[56:57], v[40:41], v[90:91] op_sel_hi:[1,0,1]
	s_waitcnt lgkmcnt(0)
	v_mov_b32_e32 v40, v51
	v_pk_fma_f32 v[70:71], v[66:67], v[42:43], v[70:71] op_sel_hi:[1,0,1]
	v_pk_fma_f32 v[76:77], v[64:65], v[42:43], v[76:77] op_sel_hi:[1,0,1]
	v_pk_fma_f32 v[92:93], v[66:67], v[48:49], v[92:93] op_sel_hi:[1,0,1]
	v_pk_fma_f32 v[94:95], v[64:65], v[48:49], v[94:95] op_sel_hi:[1,0,1]
	v_pk_fma_f32 v[88:89], v[58:59], v[48:49], v[88:89] op_sel:[0,1,0]
	v_pk_fma_f32 v[102:103], v[56:57], v[48:49], v[102:103] op_sel:[0,1,0]
	v_pk_fma_f32 v[66:67], v[66:67], v[50:51], v[74:75] op_sel_hi:[1,0,1]
	v_pk_fma_f32 v[64:65], v[64:65], v[50:51], v[72:73] op_sel_hi:[1,0,1]
	v_pk_fma_f32 v[58:59], v[58:59], v[40:41], v[82:83] op_sel_hi:[1,0,1]
	v_pk_fma_f32 v[56:57], v[56:57], v[40:41], v[80:81] op_sel_hi:[1,0,1]
	ds_read_b128 v[40:43], v34 offset:17280
	ds_read_b128 v[48:51], v34 offset:17296
	s_waitcnt vmcnt(27) lgkmcnt(1)
	v_pk_fma_f32 v[72:73], v[28:29], v[40:41], v[96:97] op_sel_hi:[1,0,1]
	v_pk_fma_f32 v[74:75], v[26:27], v[40:41], v[98:99] op_sel_hi:[1,0,1]
	s_waitcnt vmcnt(26)
	v_pk_fma_f32 v[80:81], v[20:21], v[40:41], v[100:101] op_sel:[0,1,0]
	v_pk_fma_f32 v[40:41], v[18:19], v[40:41], v[68:69] op_sel:[0,1,0]
	v_pk_fma_f32 v[68:69], v[28:29], v[42:43], v[70:71] op_sel_hi:[1,0,1]
	v_pk_fma_f32 v[70:71], v[26:27], v[42:43], v[76:77] op_sel_hi:[1,0,1]
	v_mov_b32_e32 v42, v43
	s_waitcnt lgkmcnt(0)
	v_pk_fma_f32 v[82:83], v[26:27], v[48:49], v[94:95] op_sel_hi:[1,0,1]
	v_pk_fma_f32 v[64:65], v[26:27], v[50:51], v[64:65] op_sel_hi:[1,0,1]
	v_mov_b32_e32 v26, v51
	v_pk_fma_f32 v[76:77], v[20:21], v[42:43], v[78:79] op_sel_hi:[1,0,1]
	v_pk_fma_f32 v[42:43], v[18:19], v[42:43], v[90:91] op_sel_hi:[1,0,1]
	v_pk_fma_f32 v[78:79], v[28:29], v[48:49], v[92:93] op_sel_hi:[1,0,1]
	v_pk_fma_f32 v[88:89], v[20:21], v[48:49], v[88:89] op_sel:[0,1,0]
	v_pk_fma_f32 v[48:49], v[18:19], v[48:49], v[102:103] op_sel:[0,1,0]
	v_pk_fma_f32 v[66:67], v[28:29], v[50:51], v[66:67] op_sel_hi:[1,0,1]
	v_pk_fma_f32 v[50:51], v[20:21], v[26:27], v[58:59] op_sel_hi:[1,0,1]
	v_pk_fma_f32 v[56:57], v[18:19], v[26:27], v[56:57] op_sel_hi:[1,0,1]
	ds_read_b128 v[18:21], v34 offset:17344
	ds_read_b128 v[26:29], v34 offset:17360
	s_waitcnt vmcnt(25) lgkmcnt(1)
	v_pk_fma_f32 v[90:91], v[12:13], v[18:19], v[72:73] op_sel_hi:[1,0,1]
	v_pk_fma_f32 v[92:93], v[10:11], v[18:19], v[74:75] op_sel_hi:[1,0,1]
	s_waitcnt vmcnt(24)
	v_pk_fma_f32 v[80:81], v[4:5], v[18:19], v[80:81] op_sel:[0,1,0]
	v_pk_fma_f32 v[94:95], v[2:3], v[18:19], v[40:41] op_sel:[0,1,0]
	v_pk_fma_f32 v[98:99], v[10:11], v[20:21], v[70:71] op_sel_hi:[1,0,1]
	v_mov_b32_e32 v18, v21
	s_waitcnt lgkmcnt(0)
	v_pk_fma_f32 v[82:83], v[10:11], v[26:27], v[82:83] op_sel_hi:[1,0,1]
	v_pk_fma_f32 v[106:107], v[10:11], v[28:29], v[64:65] op_sel_hi:[1,0,1]
	v_mov_b32_e32 v10, v29
	v_pk_fma_f32 v[100:101], v[2:3], v[18:19], v[42:43] op_sel_hi:[1,0,1]
	v_pk_fma_f32 v[102:103], v[2:3], v[26:27], v[48:49] op_sel:[0,1,0]
	v_pk_fma_f32 v[104:105], v[12:13], v[28:29], v[66:67] op_sel_hi:[1,0,1]
	v_pk_fma_f32 v[108:109], v[4:5], v[10:11], v[50:51] op_sel_hi:[1,0,1]
	v_pk_fma_f32 v[110:111], v[2:3], v[10:11], v[56:57] op_sel_hi:[1,0,1]
	global_load_dwordx4 v[56:59], v[112:113], off nt
	global_load_dwordx4 v[64:67], v[112:113], off offset:1024 nt
	global_load_dwordx4 v[48:51], v[112:113], off offset:2048 nt
	global_load_dwordx4 v[40:43], v[112:113], off offset:3072 nt
	v_add_co_u32_e32 v2, vcc, s0, v86
	s_mov_b32 s0, 0xc000
	s_nop 0
	v_addc_co_u32_e32 v3, vcc, 0, v87, vcc
	v_add_co_u32_e32 v112, vcc, s0, v86
	v_pk_fma_f32 v[96:97], v[12:13], v[20:21], v[68:69] op_sel_hi:[1,0,1]
	s_nop 0
	v_addc_co_u32_e32 v113, vcc, 0, v87, vcc
	v_pk_fma_f32 v[76:77], v[4:5], v[18:19], v[76:77] op_sel_hi:[1,0,1]
	v_pk_fma_f32 v[78:79], v[12:13], v[26:27], v[78:79] op_sel_hi:[1,0,1]
	v_pk_fma_f32 v[88:89], v[4:5], v[26:27], v[88:89] op_sel:[0,1,0]
	global_load_dwordx4 v[26:29], v[112:113], off offset:-4096 nt
	global_load_dwordx4 v[18:21], v[2:3], off offset:1024 nt
	global_load_dwordx4 v[10:13], v[2:3], off offset:2048 nt
	s_nop 0
	global_load_dwordx4 v[2:5], v[2:3], off offset:3072 nt
	ds_read_b128 v[68:71], v34 offset:17408
	ds_read_b128 v[72:75], v34 offset:17424
	s_mov_b32 s0, 0xd000
	s_waitcnt vmcnt(23) lgkmcnt(1)
; #define DEC_LOADV(dst, i0) do { asm volatile("" ::: "memory"); _Pragma("unroll") for (int u = 0; u < 4; ++u) { const float* vr = cv + rbase + (size_t)((i0) + u) * 512; dst[u][0] = __builtin_nontemporal_load((const f32x4*)(vr + 4 * lane)); dst[u][1] = __builtin_nontemporal_load((const f32x4*)(vr + 256 + 4 * lane)); } } while (0)
; __device__ __forceinline__ void decode_item(Frame& F, const Args& a, int l, int item, unsigned char* ws) {
;     ...
;         DEC_LOADV(va, 0); DEC_LOADV(vb, 4); DEC_ACC(va, 0); DEC_LOADV(va, 8); DEC_ACC(vb, 4); DEC_LOADV(vb, 12); DEC_ACC(va, 8); DEC_LOADV(va, 16); DEC_ACC(vb, 12); DEC_LOADV(vb, 20); DEC_ACC(va, 16); DEC_LOADV(va, 24); DEC_ACC(vb, 20); DEC_LOADV(vb, 28); DEC_ACC(va, 24); DEC_ACC(vb, 28);
	v_pk_fma_f32 v[90:91], v[54:55], v[68:69], v[90:91] op_sel_hi:[1,0,1]
	v_pk_fma_f32 v[92:93], v[52:53], v[68:69], v[92:93] op_sel_hi:[1,0,1]
	s_waitcnt vmcnt(22)
	v_pk_fma_f32 v[80:81], v[62:63], v[68:69], v[80:81] op_sel:[0,1,0]
	v_pk_fma_f32 v[68:69], v[60:61], v[68:69], v[94:95] op_sel:[0,1,0]
	v_pk_fma_f32 v[94:95], v[54:55], v[70:71], v[96:97] op_sel_hi:[1,0,1]
	v_pk_fma_f32 v[96:97], v[52:53], v[70:71], v[98:99] op_sel_hi:[1,0,1]
	v_mov_b32_e32 v70, v71
	v_pk_fma_f32 v[76:77], v[62:63], v[70:71], v[76:77] op_sel_hi:[1,0,1]
	v_pk_fma_f32 v[70:71], v[60:61], v[70:71], v[100:101] op_sel_hi:[1,0,1]
	s_waitcnt lgkmcnt(0)
	v_pk_fma_f32 v[82:83], v[52:53], v[72:73], v[82:83] op_sel_hi:[1,0,1]
	v_pk_fma_f32 v[100:101], v[52:53], v[74:75], v[106:107] op_sel_hi:[1,0,1]
	v_mov_b32_e32 v52, v75
	v_pk_fma_f32 v[78:79], v[54:55], v[72:73], v[78:79] op_sel_hi:[1,0,1]
	v_pk_fma_f32 v[88:89], v[62:63], v[72:73], v[88:89] op_sel:[0,1,0]
	v_pk_fma_f32 v[72:73], v[60:61], v[72:73], v[102:103] op_sel:[0,1,0]
	v_pk_fma_f32 v[98:99], v[54:55], v[74:75], v[104:105] op_sel_hi:[1,0,1]
	v_pk_fma_f32 v[74:75], v[62:63], v[52:53], v[108:109] op_sel_hi:[1,0,1]
	v_pk_fma_f32 v[102:103], v[60:61], v[52:53], v[110:111] op_sel_hi:[1,0,1]
	ds_read_b128 v[52:55], v34 offset:17472
	ds_read_b128 v[60:63], v34 offset:17488
	s_waitcnt vmcnt(21) lgkmcnt(1)
	v_pk_fma_f32 v[90:91], v[46:47], v[52:53], v[90:91] op_sel_hi:[1,0,1]
	v_pk_fma_f32 v[92:93], v[44:45], v[52:53], v[92:93] op_sel_hi:[1,0,1]
	s_waitcnt vmcnt(20)
	v_pk_fma_f32 v[80:81], v[38:39], v[52:53], v[80:81] op_sel:[0,1,0]
	v_pk_fma_f32 v[52:53], v[36:37], v[52:53], v[68:69] op_sel:[0,1,0]
	v_pk_fma_f32 v[68:69], v[46:47], v[54:55], v[94:95] op_sel_hi:[1,0,1]
	v_pk_fma_f32 v[94:95], v[44:45], v[54:55], v[96:97] op_sel_hi:[1,0,1]
	v_mov_b32_e32 v54, v55
	v_pk_fma_f32 v[76:77], v[38:39], v[54:55], v[76:77] op_sel_hi:[1,0,1]
	v_pk_fma_f32 v[54:55], v[36:37], v[54:55], v[70:71] op_sel_hi:[1,0,1]
	s_waitcnt lgkmcnt(0)
	v_pk_fma_f32 v[70:71], v[46:47], v[60:61], v[78:79] op_sel_hi:[1,0,1]
	v_pk_fma_f32 v[78:79], v[44:45], v[60:61], v[82:83] op_sel_hi:[1,0,1]
	v_pk_fma_f32 v[82:83], v[38:39], v[60:61], v[88:89] op_sel:[0,1,0]
	v_pk_fma_f32 v[88:89], v[44:45], v[62:63], v[100:101] op_sel_hi:[1,0,1]
	v_mov_b32_e32 v44, v63
	v_pk_fma_f32 v[60:61], v[36:37], v[60:61], v[72:73] op_sel:[0,1,0]
	v_pk_fma_f32 v[72:73], v[46:47], v[62:63], v[98:99] op_sel_hi:[1,0,1]
	v_pk_fma_f32 v[62:63], v[38:39], v[44:45], v[74:75] op_sel_hi:[1,0,1]
	v_pk_fma_f32 v[74:75], v[36:37], v[44:45], v[102:103] op_sel_hi:[1,0,1]
	ds_read_b128 v[36:39], v34 offset:17536
	ds_read_b128 v[44:47], v34 offset:17552
	s_waitcnt vmcnt(19) lgkmcnt(1)
	v_pk_fma_f32 v[90:91], v[32:33], v[36:37], v[90:91] op_sel_hi:[1,0,1]
	v_pk_fma_f32 v[92:93], v[30:31], v[36:37], v[92:93] op_sel_hi:[1,0,1]
	s_waitcnt vmcnt(18)
	v_pk_fma_f32 v[80:81], v[24:25], v[36:37], v[80:81] op_sel:[0,1,0]
	v_pk_fma_f32 v[36:37], v[22:23], v[36:37], v[52:53] op_sel:[0,1,0]
	v_pk_fma_f32 v[52:53], v[32:33], v[38:39], v[68:69] op_sel_hi:[1,0,1]
	v_pk_fma_f32 v[68:69], v[30:31], v[38:39], v[94:95] op_sel_hi:[1,0,1]
	v_mov_b32_e32 v38, v39
	v_pk_fma_f32 v[76:77], v[24:25], v[38:39], v[76:77] op_sel_hi:[1,0,1]
	v_pk_fma_f32 v[38:39], v[22:23], v[38:39], v[54:55] op_sel_hi:[1,0,1]
	s_waitcnt lgkmcnt(0)
	v_pk_fma_f32 v[54:55], v[32:33], v[44:45], v[70:71] op_sel_hi:[1,0,1]
	v_pk_fma_f32 v[70:71], v[30:31], v[44:45], v[78:79] op_sel_hi:[1,0,1]
	v_pk_fma_f32 v[78:79], v[24:25], v[44:45], v[82:83] op_sel:[0,1,0]
	v_pk_fma_f32 v[44:45], v[22:23], v[44:45], v[60:61] op_sel:[0,1,0]
	v_pk_fma_f32 v[60:61], v[32:33], v[46:47], v[72:73] op_sel_hi:[1,0,1]
	v_pk_fma_f32 v[72:73], v[30:31], v[46:47], v[88:89] op_sel_hi:[1,0,1]
	v_mov_b32_e32 v30, v47
	v_pk_fma_f32 v[46:47], v[24:25], v[30:31], v[62:63] op_sel_hi:[1,0,1]
	v_pk_fma_f32 v[62:63], v[22:23], v[30:31], v[74:75] op_sel_hi:[1,0,1]
	ds_read_b128 v[22:25], v34 offset:17600
	ds_read_b128 v[30:33], v34 offset:17616
	s_waitcnt vmcnt(17) lgkmcnt(1)
	v_pk_fma_f32 v[82:83], v[16:17], v[22:23], v[90:91] op_sel_hi:[1,0,1]
	v_pk_fma_f32 v[88:89], v[14:15], v[22:23], v[92:93] op_sel_hi:[1,0,1]
	s_waitcnt vmcnt(16)
	v_pk_fma_f32 v[80:81], v[8:9], v[22:23], v[80:81] op_sel:[0,1,0]
	v_pk_fma_f32 v[90:91], v[6:7], v[22:23], v[36:37] op_sel:[0,1,0]
	v_pk_fma_f32 v[94:95], v[14:15], v[24:25], v[68:69] op_sel_hi:[1,0,1]
	v_mov_b32_e32 v22, v25
	s_waitcnt lgkmcnt(0)
	v_pk_fma_f32 v[100:101], v[14:15], v[30:31], v[70:71] op_sel_hi:[1,0,1]
	v_pk_fma_f32 v[106:107], v[14:15], v[32:33], v[72:73] op_sel_hi:[1,0,1]
	v_mov_b32_e32 v14, v33
	v_pk_fma_f32 v[96:97], v[6:7], v[22:23], v[38:39] op_sel_hi:[1,0,1]
	v_pk_fma_f32 v[102:103], v[6:7], v[30:31], v[44:45] op_sel:[0,1,0]
	v_pk_fma_f32 v[110:111], v[6:7], v[14:15], v[62:63] op_sel_hi:[1,0,1]
	v_add_co_u32_e32 v6, vcc, s0, v86
	s_mov_b32 s0, 0xe000
	s_nop 0
	v_addc_co_u32_e32 v7, vcc, 0, v87, vcc
	v_pk_fma_f32 v[92:93], v[16:17], v[24:25], v[52:53] op_sel_hi:[1,0,1]
	v_pk_fma_f32 v[98:99], v[16:17], v[30:31], v[54:55] op_sel_hi:[1,0,1]
	v_pk_fma_f32 v[104:105], v[16:17], v[32:33], v[60:61] op_sel_hi:[1,0,1]
	v_pk_fma_f32 v[108:109], v[8:9], v[14:15], v[46:47] op_sel_hi:[1,0,1]
	global_load_dwordx4 v[52:55], v[112:113], off nt
	global_load_dwordx4 v[60:63], v[112:113], off offset:1024 nt
	global_load_dwordx4 v[44:47], v[112:113], off offset:2048 nt
	global_load_dwordx4 v[36:39], v[112:113], off offset:3072 nt
	v_add_co_u32_e32 v112, vcc, s0, v86
	v_pk_fma_f32 v[76:77], v[8:9], v[22:23], v[76:77] op_sel_hi:[1,0,1]
	s_nop 0
	v_addc_co_u32_e32 v113, vcc, 0, v87, vcc
	v_pk_fma_f32 v[78:79], v[8:9], v[30:31], v[78:79] op_sel:[0,1,0]
	global_load_dwordx4 v[30:33], v[112:113], off offset:-4096 nt
	global_load_dwordx4 v[22:25], v[6:7], off offset:1024 nt
	global_load_dwordx4 v[14:17], v[6:7], off offset:2048 nt
	s_nop 0
	global_load_dwordx4 v[6:9], v[6:7], off offset:3072 nt
	ds_read_b128 v[68:71], v34 offset:17664
	ds_read_b128 v[72:75], v34 offset:17680
	s_mov_b32 s0, 0xf000
	s_waitcnt vmcnt(15) lgkmcnt(1)
; #define DEC_LOADV(dst, i0) do { asm volatile("" ::: "memory"); _Pragma("unroll") for (int u = 0; u < 4; ++u) { const float* vr = cv + rbase + (size_t)((i0) + u) * 512; dst[u][0] = __builtin_nontemporal_load((const f32x4*)(vr + 4 * lane)); dst[u][1] = __builtin_nontemporal_load((const f32x4*)(vr + 256 + 4 * lane)); } } while (0)
; __device__ __forceinline__ void decode_item(Frame& F, const Args& a, int l, int item, unsigned char* ws) {
;     ...
;         DEC_LOADV(va, 0); DEC_LOADV(vb, 4); DEC_ACC(va, 0); DEC_LOADV(va, 8); DEC_ACC(vb, 4); DEC_LOADV(vb, 12); DEC_ACC(va, 8); DEC_LOADV(va, 16); DEC_ACC(vb, 12); DEC_LOADV(vb, 20); DEC_ACC(va, 16); DEC_LOADV(va, 24); DEC_ACC(vb, 20); DEC_LOADV(vb, 28); DEC_ACC(va, 24); DEC_ACC(vb, 28);
	v_pk_fma_f32 v[82:83], v[58:59], v[68:69], v[82:83] op_sel_hi:[1,0,1]
	v_pk_fma_f32 v[88:89], v[56:57], v[68:69], v[88:89] op_sel_hi:[1,0,1]
	s_waitcnt vmcnt(14)
	v_pk_fma_f32 v[80:81], v[66:67], v[68:69], v[80:81] op_sel:[0,1,0]
	v_pk_fma_f32 v[68:69], v[64:65], v[68:69], v[90:91] op_sel:[0,1,0]
	v_pk_fma_f32 v[90:91], v[58:59], v[70:71], v[92:93] op_sel_hi:[1,0,1]
	v_pk_fma_f32 v[92:93], v[56:57], v[70:71], v[94:95] op_sel_hi:[1,0,1]
	v_mov_b32_e32 v70, v71
	v_pk_fma_f32 v[76:77], v[66:67], v[70:71], v[76:77] op_sel_hi:[1,0,1]
	v_pk_fma_f32 v[70:71], v[64:65], v[70:71], v[96:97] op_sel_hi:[1,0,1]
	s_waitcnt lgkmcnt(0)
	v_pk_fma_f32 v[96:97], v[56:57], v[72:73], v[100:101] op_sel_hi:[1,0,1]
	v_pk_fma_f32 v[100:101], v[56:57], v[74:75], v[106:107] op_sel_hi:[1,0,1]
	v_mov_b32_e32 v56, v75
	v_pk_fma_f32 v[94:95], v[58:59], v[72:73], v[98:99] op_sel_hi:[1,0,1]
	v_pk_fma_f32 v[78:79], v[66:67], v[72:73], v[78:79] op_sel:[0,1,0]
	v_pk_fma_f32 v[72:73], v[64:65], v[72:73], v[102:103] op_sel:[0,1,0]
	v_pk_fma_f32 v[98:99], v[58:59], v[74:75], v[104:105] op_sel_hi:[1,0,1]
	v_pk_fma_f32 v[74:75], v[66:67], v[56:57], v[108:109] op_sel_hi:[1,0,1]
	v_pk_fma_f32 v[102:103], v[64:65], v[56:57], v[110:111] op_sel_hi:[1,0,1]
	ds_read_b128 v[56:59], v34 offset:17728
	ds_read_b128 v[64:67], v34 offset:17744
	s_waitcnt vmcnt(13) lgkmcnt(1)
	v_pk_fma_f32 v[82:83], v[50:51], v[56:57], v[82:83] op_sel_hi:[1,0,1]
	v_pk_fma_f32 v[88:89], v[48:49], v[56:57], v[88:89] op_sel_hi:[1,0,1]
	s_waitcnt vmcnt(12)
	v_pk_fma_f32 v[80:81], v[42:43], v[56:57], v[80:81] op_sel:[0,1,0]
	v_pk_fma_f32 v[56:57], v[40:41], v[56:57], v[68:69] op_sel:[0,1,0]
	v_pk_fma_f32 v[68:69], v[50:51], v[58:59], v[90:91] op_sel_hi:[1,0,1]
	v_pk_fma_f32 v[90:91], v[48:49], v[58:59], v[92:93] op_sel_hi:[1,0,1]
	v_mov_b32_e32 v58, v59
	v_pk_fma_f32 v[76:77], v[42:43], v[58:59], v[76:77] op_sel_hi:[1,0,1]
	v_pk_fma_f32 v[58:59], v[40:41], v[58:59], v[70:71] op_sel_hi:[1,0,1]
	s_waitcnt lgkmcnt(0)
	v_pk_fma_f32 v[70:71], v[50:51], v[64:65], v[94:95] op_sel_hi:[1,0,1]
	v_pk_fma_f32 v[92:93], v[48:49], v[64:65], v[96:97] op_sel_hi:[1,0,1]
	v_pk_fma_f32 v[94:95], v[48:49], v[66:67], v[100:101] op_sel_hi:[1,0,1]
	v_mov_b32_e32 v48, v67
	v_pk_fma_f32 v[78:79], v[42:43], v[64:65], v[78:79] op_sel:[0,1,0]
	v_pk_fma_f32 v[64:65], v[40:41], v[64:65], v[72:73] op_sel:[0,1,0]
	v_pk_fma_f32 v[72:73], v[50:51], v[66:67], v[98:99] op_sel_hi:[1,0,1]
	v_pk_fma_f32 v[66:67], v[42:43], v[48:49], v[74:75] op_sel_hi:[1,0,1]
	v_pk_fma_f32 v[74:75], v[40:41], v[48:49], v[102:103] op_sel_hi:[1,0,1]
	ds_read_b128 v[40:43], v34 offset:17792
	ds_read_b128 v[48:51], v34 offset:17808
	s_waitcnt vmcnt(11) lgkmcnt(1)
	v_pk_fma_f32 v[82:83], v[28:29], v[40:41], v[82:83] op_sel_hi:[1,0,1]
	v_pk_fma_f32 v[88:89], v[26:27], v[40:41], v[88:89] op_sel_hi:[1,0,1]
	s_waitcnt vmcnt(10)
	v_pk_fma_f32 v[80:81], v[20:21], v[40:41], v[80:81] op_sel:[0,1,0]
	v_pk_fma_f32 v[40:41], v[18:19], v[40:41], v[56:57] op_sel:[0,1,0]
	v_pk_fma_f32 v[56:57], v[28:29], v[42:43], v[68:69] op_sel_hi:[1,0,1]
	v_pk_fma_f32 v[68:69], v[26:27], v[42:43], v[90:91] op_sel_hi:[1,0,1]
	v_mov_b32_e32 v42, v43
	v_pk_fma_f32 v[76:77], v[20:21], v[42:43], v[76:77] op_sel_hi:[1,0,1]
	v_pk_fma_f32 v[42:43], v[18:19], v[42:43], v[58:59] op_sel_hi:[1,0,1]
	s_waitcnt lgkmcnt(0)
	v_pk_fma_f32 v[58:59], v[28:29], v[48:49], v[70:71] op_sel_hi:[1,0,1]
	v_pk_fma_f32 v[70:71], v[26:27], v[48:49], v[92:93] op_sel_hi:[1,0,1]
	v_pk_fma_f32 v[78:79], v[20:21], v[48:49], v[78:79] op_sel:[0,1,0]
	v_pk_fma_f32 v[48:49], v[18:19], v[48:49], v[64:65] op_sel:[0,1,0]
	v_pk_fma_f32 v[64:65], v[28:29], v[50:51], v[72:73] op_sel_hi:[1,0,1]
	v_pk_fma_f32 v[72:73], v[26:27], v[50:51], v[94:95] op_sel_hi:[1,0,1]
	v_mov_b32_e32 v26, v51
	v_pk_fma_f32 v[50:51], v[20:21], v[26:27], v[66:67] op_sel_hi:[1,0,1]
	v_pk_fma_f32 v[66:67], v[18:19], v[26:27], v[74:75] op_sel_hi:[1,0,1]
	ds_read_b128 v[18:21], v34 offset:17856
	ds_read_b128 v[26:29], v34 offset:17872
	s_waitcnt vmcnt(9) lgkmcnt(1)
	v_pk_fma_f32 v[82:83], v[12:13], v[18:19], v[82:83] op_sel_hi:[1,0,1]
	v_pk_fma_f32 v[88:89], v[10:11], v[18:19], v[88:89] op_sel_hi:[1,0,1]
	s_waitcnt vmcnt(8)
	v_pk_fma_f32 v[80:81], v[4:5], v[18:19], v[80:81] op_sel:[0,1,0]
	v_pk_fma_f32 v[90:91], v[2:3], v[18:19], v[40:41] op_sel:[0,1,0]
	v_pk_fma_f32 v[94:95], v[10:11], v[20:21], v[68:69] op_sel_hi:[1,0,1]
	v_mov_b32_e32 v18, v21
	s_waitcnt lgkmcnt(0)
	v_pk_fma_f32 v[100:101], v[10:11], v[26:27], v[70:71] op_sel_hi:[1,0,1]
	v_pk_fma_f32 v[106:107], v[10:11], v[28:29], v[72:73] op_sel_hi:[1,0,1]
	v_mov_b32_e32 v10, v29
	v_pk_fma_f32 v[92:93], v[12:13], v[20:21], v[56:57] op_sel_hi:[1,0,1]
	v_pk_fma_f32 v[96:97], v[2:3], v[18:19], v[42:43] op_sel_hi:[1,0,1]
	v_pk_fma_f32 v[98:99], v[12:13], v[26:27], v[58:59] op_sel_hi:[1,0,1]
	v_pk_fma_f32 v[102:103], v[2:3], v[26:27], v[48:49] op_sel:[0,1,0]
	v_pk_fma_f32 v[104:105], v[12:13], v[28:29], v[64:65] op_sel_hi:[1,0,1]
	v_pk_fma_f32 v[108:109], v[4:5], v[10:11], v[50:51] op_sel_hi:[1,0,1]
	v_pk_fma_f32 v[110:111], v[2:3], v[10:11], v[66:67] op_sel_hi:[1,0,1]
	global_load_dwordx4 v[64:67], v[112:113], off nt
	global_load_dwordx4 v[56:59], v[112:113], off offset:1024 nt
	global_load_dwordx4 v[48:51], v[112:113], off offset:2048 nt
	global_load_dwordx4 v[40:43], v[112:113], off offset:3072 nt
	v_add_co_u32_e32 v2, vcc, s0, v86
	v_pk_fma_f32 v[76:77], v[4:5], v[18:19], v[76:77] op_sel_hi:[1,0,1]
	s_nop 0
	v_addc_co_u32_e32 v3, vcc, 0, v87, vcc
	v_pk_fma_f32 v[78:79], v[4:5], v[26:27], v[78:79] op_sel:[0,1,0]
	global_load_dwordx4 v[26:29], v[2:3], off nt
	global_load_dwordx4 v[18:21], v[2:3], off offset:1024 nt
	global_load_dwordx4 v[10:13], v[2:3], off offset:2048 nt
	s_nop 0
	global_load_dwordx4 v[2:5], v[2:3], off offset:3072 nt
	ds_read_b128 v[68:71], v34 offset:17920
	ds_read_b128 v[72:75], v34 offset:17936
	s_waitcnt vmcnt(15) lgkmcnt(1)
; #define DEC_LOADV(dst, i0) do { asm volatile("" ::: "memory"); _Pragma("unroll") for (int u = 0; u < 4; ++u) { const float* vr = cv + rbase + (size_t)((i0) + u) * 512; dst[u][0] = __builtin_nontemporal_load((const f32x4*)(vr + 4 * lane)); dst[u][1] = __builtin_nontemporal_load((const f32x4*)(vr + 256 + 4 * lane)); } } while (0)
; __device__ __forceinline__ void decode_item(Frame& F, const Args& a, int l, int item, unsigned char* ws) {
;     ...
;         DEC_LOADV(va, 0); DEC_LOADV(vb, 4); DEC_ACC(va, 0); DEC_LOADV(va, 8); DEC_ACC(vb, 4); DEC_LOADV(vb, 12); DEC_ACC(va, 8); DEC_LOADV(va, 16); DEC_ACC(vb, 12); DEC_LOADV(vb, 20); DEC_ACC(va, 16); DEC_LOADV(va, 24); DEC_ACC(vb, 20); DEC_LOADV(vb, 28); DEC_ACC(va, 24); DEC_ACC(vb, 28);
	v_pk_fma_f32 v[82:83], v[54:55], v[68:69], v[82:83] op_sel_hi:[1,0,1]
	v_pk_fma_f32 v[86:87], v[52:53], v[68:69], v[88:89] op_sel_hi:[1,0,1]
	s_waitcnt vmcnt(14)
	v_pk_fma_f32 v[80:81], v[62:63], v[68:69], v[80:81] op_sel:[0,1,0]
	v_pk_fma_f32 v[68:69], v[60:61], v[68:69], v[90:91] op_sel:[0,1,0]
	v_pk_fma_f32 v[88:89], v[54:55], v[70:71], v[92:93] op_sel_hi:[1,0,1]
	v_pk_fma_f32 v[90:91], v[52:53], v[70:71], v[94:95] op_sel_hi:[1,0,1]
	v_mov_b32_e32 v70, v71
	s_waitcnt lgkmcnt(0)
	v_pk_fma_f32 v[92:93], v[54:55], v[72:73], v[98:99] op_sel_hi:[1,0,1]
	v_pk_fma_f32 v[94:95], v[52:53], v[72:73], v[100:101] op_sel_hi:[1,0,1]
	v_pk_fma_f32 v[98:99], v[52:53], v[74:75], v[106:107] op_sel_hi:[1,0,1]
	v_mov_b32_e32 v52, v75
	v_pk_fma_f32 v[76:77], v[62:63], v[70:71], v[76:77] op_sel_hi:[1,0,1]
	v_pk_fma_f32 v[70:71], v[60:61], v[70:71], v[96:97] op_sel_hi:[1,0,1]
	v_pk_fma_f32 v[78:79], v[62:63], v[72:73], v[78:79] op_sel:[0,1,0]
	v_pk_fma_f32 v[72:73], v[60:61], v[72:73], v[102:103] op_sel:[0,1,0]
	v_pk_fma_f32 v[96:97], v[54:55], v[74:75], v[104:105] op_sel_hi:[1,0,1]
	v_pk_fma_f32 v[74:75], v[62:63], v[52:53], v[108:109] op_sel_hi:[1,0,1]
	v_pk_fma_f32 v[100:101], v[60:61], v[52:53], v[110:111] op_sel_hi:[1,0,1]
	ds_read_b128 v[52:55], v34 offset:17984
	ds_read_b128 v[60:63], v34 offset:18000
	s_waitcnt vmcnt(13) lgkmcnt(1)
	v_pk_fma_f32 v[82:83], v[46:47], v[52:53], v[82:83] op_sel_hi:[1,0,1]
	v_pk_fma_f32 v[86:87], v[44:45], v[52:53], v[86:87] op_sel_hi:[1,0,1]
	s_waitcnt vmcnt(12)
	v_pk_fma_f32 v[80:81], v[38:39], v[52:53], v[80:81] op_sel:[0,1,0]
	v_pk_fma_f32 v[52:53], v[36:37], v[52:53], v[68:69] op_sel:[0,1,0]
	v_pk_fma_f32 v[68:69], v[46:47], v[54:55], v[88:89] op_sel_hi:[1,0,1]
	v_pk_fma_f32 v[88:89], v[44:45], v[54:55], v[90:91] op_sel_hi:[1,0,1]
	v_mov_b32_e32 v54, v55
	v_pk_fma_f32 v[76:77], v[38:39], v[54:55], v[76:77] op_sel_hi:[1,0,1]
	v_pk_fma_f32 v[54:55], v[36:37], v[54:55], v[70:71] op_sel_hi:[1,0,1]
	s_waitcnt lgkmcnt(0)
	v_pk_fma_f32 v[70:71], v[46:47], v[60:61], v[92:93] op_sel_hi:[1,0,1]
	v_pk_fma_f32 v[90:91], v[44:45], v[60:61], v[94:95] op_sel_hi:[1,0,1]
	v_pk_fma_f32 v[92:93], v[44:45], v[62:63], v[98:99] op_sel_hi:[1,0,1]
	v_mov_b32_e32 v44, v63
	v_pk_fma_f32 v[78:79], v[38:39], v[60:61], v[78:79] op_sel:[0,1,0]
	v_pk_fma_f32 v[60:61], v[36:37], v[60:61], v[72:73] op_sel:[0,1,0]
	v_pk_fma_f32 v[72:73], v[46:47], v[62:63], v[96:97] op_sel_hi:[1,0,1]
	v_pk_fma_f32 v[62:63], v[38:39], v[44:45], v[74:75] op_sel_hi:[1,0,1]
	v_pk_fma_f32 v[74:75], v[36:37], v[44:45], v[100:101] op_sel_hi:[1,0,1]
	ds_read_b128 v[36:39], v34 offset:18048
	ds_read_b128 v[44:47], v34 offset:18064
	s_waitcnt vmcnt(11) lgkmcnt(1)
	v_pk_fma_f32 v[82:83], v[32:33], v[36:37], v[82:83] op_sel_hi:[1,0,1]
	v_pk_fma_f32 v[86:87], v[30:31], v[36:37], v[86:87] op_sel_hi:[1,0,1]
	s_waitcnt vmcnt(10)
	v_pk_fma_f32 v[80:81], v[24:25], v[36:37], v[80:81] op_sel:[0,1,0]
	v_pk_fma_f32 v[36:37], v[22:23], v[36:37], v[52:53] op_sel:[0,1,0]
	v_pk_fma_f32 v[52:53], v[32:33], v[38:39], v[68:69] op_sel_hi:[1,0,1]
	v_pk_fma_f32 v[68:69], v[30:31], v[38:39], v[88:89] op_sel_hi:[1,0,1]
	v_mov_b32_e32 v38, v39
	v_pk_fma_f32 v[76:77], v[24:25], v[38:39], v[76:77] op_sel_hi:[1,0,1]
	v_pk_fma_f32 v[38:39], v[22:23], v[38:39], v[54:55] op_sel_hi:[1,0,1]
	s_waitcnt lgkmcnt(0)
	v_pk_fma_f32 v[54:55], v[32:33], v[44:45], v[70:71] op_sel_hi:[1,0,1]
	v_pk_fma_f32 v[70:71], v[30:31], v[44:45], v[90:91] op_sel_hi:[1,0,1]
	v_pk_fma_f32 v[78:79], v[24:25], v[44:45], v[78:79] op_sel:[0,1,0]
	v_pk_fma_f32 v[44:45], v[22:23], v[44:45], v[60:61] op_sel:[0,1,0]
	v_pk_fma_f32 v[60:61], v[32:33], v[46:47], v[72:73] op_sel_hi:[1,0,1]
	v_pk_fma_f32 v[72:73], v[30:31], v[46:47], v[92:93] op_sel_hi:[1,0,1]
	v_mov_b32_e32 v30, v47
	v_pk_fma_f32 v[46:47], v[24:25], v[30:31], v[62:63] op_sel_hi:[1,0,1]
	v_pk_fma_f32 v[62:63], v[22:23], v[30:31], v[74:75] op_sel_hi:[1,0,1]
	ds_read_b128 v[22:25], v34 offset:18112
	ds_read_b128 v[30:33], v34 offset:18128
	s_waitcnt vmcnt(9) lgkmcnt(1)
	v_pk_fma_f32 v[74:75], v[16:17], v[22:23], v[82:83] op_sel_hi:[1,0,1]
	v_pk_fma_f32 v[82:83], v[14:15], v[22:23], v[86:87] op_sel_hi:[1,0,1]
	s_waitcnt vmcnt(8)
	v_pk_fma_f32 v[80:81], v[8:9], v[22:23], v[80:81] op_sel:[0,1,0]
	v_pk_fma_f32 v[22:23], v[6:7], v[22:23], v[36:37] op_sel:[0,1,0]
	v_pk_fma_f32 v[36:37], v[16:17], v[24:25], v[52:53] op_sel_hi:[1,0,1]
	v_pk_fma_f32 v[52:53], v[14:15], v[24:25], v[68:69] op_sel_hi:[1,0,1]
	v_mov_b32_e32 v24, v25
	v_pk_fma_f32 v[68:69], v[8:9], v[24:25], v[76:77] op_sel_hi:[1,0,1]
	v_pk_fma_f32 v[24:25], v[6:7], v[24:25], v[38:39] op_sel_hi:[1,0,1]
	s_waitcnt lgkmcnt(0)
	v_pk_fma_f32 v[38:39], v[16:17], v[30:31], v[54:55] op_sel_hi:[1,0,1]
	v_pk_fma_f32 v[54:55], v[14:15], v[30:31], v[70:71] op_sel_hi:[1,0,1]
	v_pk_fma_f32 v[70:71], v[8:9], v[30:31], v[78:79] op_sel:[0,1,0]
	v_pk_fma_f32 v[30:31], v[6:7], v[30:31], v[44:45] op_sel:[0,1,0]
	v_pk_fma_f32 v[44:45], v[16:17], v[32:33], v[60:61] op_sel_hi:[1,0,1]
	v_pk_fma_f32 v[60:61], v[14:15], v[32:33], v[72:73] op_sel_hi:[1,0,1]
	v_mov_b32_e32 v14, v33
	v_pk_fma_f32 v[32:33], v[8:9], v[14:15], v[46:47] op_sel_hi:[1,0,1]
	v_pk_fma_f32 v[46:47], v[6:7], v[14:15], v[62:63] op_sel_hi:[1,0,1]
	ds_read_b128 v[6:9], v34 offset:18176
	ds_read_b128 v[14:17], v34 offset:18192
	s_waitcnt vmcnt(7) lgkmcnt(1)
	v_pk_fma_f32 v[62:63], v[66:67], v[6:7], v[74:75] op_sel_hi:[1,0,1]
	v_pk_fma_f32 v[72:73], v[64:65], v[6:7], v[82:83] op_sel_hi:[1,0,1]
	s_waitcnt vmcnt(6)
	v_pk_fma_f32 v[74:75], v[58:59], v[6:7], v[80:81] op_sel:[0,1,0]
	v_pk_fma_f32 v[22:23], v[56:57], v[6:7], v[22:23] op_sel:[0,1,0]
	v_mov_b32_e32 v6, v9
	v_pk_fma_f32 v[68:69], v[58:59], v[6:7], v[68:69] op_sel_hi:[1,0,1]
	v_pk_fma_f32 v[24:25], v[56:57], v[6:7], v[24:25] op_sel_hi:[1,0,1]
	s_waitcnt lgkmcnt(0)
; #define LAS __attribute__((address_space(3)))
; #define LDS_WAIT() asm volatile("s_waitcnt lgkmcnt(0)" ::: "memory")
; #define DEC_LOADV(dst, i0) do { asm volatile("" ::: "memory"); _Pragma("unroll") for (int u = 0; u < 4; ++u) { const float* vr = cv + rbase + (size_t)((i0) + u) * 512; dst[u][0] = __builtin_nontemporal_load((const f32x4*)(vr + 4 * lane)); dst[u][1] = __builtin_nontemporal_load((const f32x4*)(vr + 256 + 4 * lane)); } } while (0)
; __device__ __forceinline__ void decode_item(Frame& F, const Args& a, int l, int item, unsigned char* ws) {
;     ...
;         DEC_LOADV(va, 0); DEC_LOADV(vb, 4); DEC_ACC(va, 0); DEC_LOADV(va, 8); DEC_ACC(vb, 4); DEC_LOADV(vb, 12); DEC_ACC(va, 8); DEC_LOADV(va, 16); DEC_ACC(vb, 12); DEC_LOADV(vb, 20); DEC_ACC(va, 16); DEC_LOADV(va, 24); DEC_ACC(vb, 20); DEC_LOADV(vb, 28); DEC_ACC(va, 24); DEC_ACC(vb, 28);
;     ...
;     }
;     __syncthreads();
;     LAS float* RED = (LAS float*)F.lds;
; #pragma unroll
;     for (int qi = 0; qi < 4; ++qi)
; #pragma unroll
;         for (int g = 0; g < 2; ++g) { LAS float* d = RED + ((w * 16 + qi * 4 + g * 2 + hh) * 128 + 4 * (lane & 31)); d[0] = O[qi][g][0]; d[1] = O[qi][g][1]; d[2] = O[qi][g][2]; d[3] = O[qi][g][3]; }
;     LDS_WAIT(); __syncthreads();
;     { f32x4 s = (f32x4){0.f, 0.f, 0.f, 0.f};
; #pragma unroll
;       for (int j = 0; j < 8; ++j) { const LAS float* p = RED + j * 2048 + tid * 4; s += (f32x4){p[0], p[1], p[2], p[3]}; }
;       *(f32x4*)((float*)(ws + WS_OSEG) + (size_t)(sb * 64 + seg) * 2048 + tid * 4) = s; }
	v_mov_b32_e32 v6, v17
	v_pk_fma_f32 v[36:37], v[66:67], v[8:9], v[36:37] op_sel_hi:[1,0,1]
	v_pk_fma_f32 v[52:53], v[64:65], v[8:9], v[52:53] op_sel_hi:[1,0,1]
	v_pk_fma_f32 v[38:39], v[66:67], v[14:15], v[38:39] op_sel_hi:[1,0,1]
	v_pk_fma_f32 v[54:55], v[64:65], v[14:15], v[54:55] op_sel_hi:[1,0,1]
	v_pk_fma_f32 v[70:71], v[58:59], v[14:15], v[70:71] op_sel:[0,1,0]
	v_pk_fma_f32 v[30:31], v[56:57], v[14:15], v[30:31] op_sel:[0,1,0]
	v_pk_fma_f32 v[44:45], v[66:67], v[16:17], v[44:45] op_sel_hi:[1,0,1]
	v_pk_fma_f32 v[60:61], v[64:65], v[16:17], v[60:61] op_sel_hi:[1,0,1]
	v_pk_fma_f32 v[32:33], v[58:59], v[6:7], v[32:33] op_sel_hi:[1,0,1]
	v_pk_fma_f32 v[46:47], v[56:57], v[6:7], v[46:47] op_sel_hi:[1,0,1]
	ds_read_b128 v[6:9], v34 offset:18240
	ds_read_b128 v[14:17], v34 offset:18256
	s_waitcnt vmcnt(5) lgkmcnt(1)
	v_pk_fma_f32 v[56:57], v[50:51], v[6:7], v[62:63] op_sel_hi:[1,0,1]
	v_pk_fma_f32 v[58:59], v[48:49], v[6:7], v[72:73] op_sel_hi:[1,0,1]
	s_waitcnt vmcnt(4)
	v_pk_fma_f32 v[62:63], v[42:43], v[6:7], v[74:75] op_sel:[0,1,0]
	v_pk_fma_f32 v[22:23], v[40:41], v[6:7], v[22:23] op_sel:[0,1,0]
	v_mov_b32_e32 v6, v9
	v_pk_fma_f32 v[64:65], v[42:43], v[6:7], v[68:69] op_sel_hi:[1,0,1]
	v_pk_fma_f32 v[24:25], v[40:41], v[6:7], v[24:25] op_sel_hi:[1,0,1]
	s_waitcnt lgkmcnt(0)
	v_mov_b32_e32 v6, v17
	v_pk_fma_f32 v[36:37], v[50:51], v[8:9], v[36:37] op_sel_hi:[1,0,1]
	v_pk_fma_f32 v[52:53], v[48:49], v[8:9], v[52:53] op_sel_hi:[1,0,1]
	v_pk_fma_f32 v[38:39], v[50:51], v[14:15], v[38:39] op_sel_hi:[1,0,1]
	v_pk_fma_f32 v[54:55], v[48:49], v[14:15], v[54:55] op_sel_hi:[1,0,1]
	v_pk_fma_f32 v[66:67], v[42:43], v[14:15], v[70:71] op_sel:[0,1,0]
	v_pk_fma_f32 v[30:31], v[40:41], v[14:15], v[30:31] op_sel:[0,1,0]
	v_pk_fma_f32 v[44:45], v[50:51], v[16:17], v[44:45] op_sel_hi:[1,0,1]
	v_pk_fma_f32 v[48:49], v[48:49], v[16:17], v[60:61] op_sel_hi:[1,0,1]
	v_pk_fma_f32 v[32:33], v[42:43], v[6:7], v[32:33] op_sel_hi:[1,0,1]
	v_pk_fma_f32 v[40:41], v[40:41], v[6:7], v[46:47] op_sel_hi:[1,0,1]
	ds_read_b128 v[6:9], v34 offset:18304
	ds_read_b128 v[14:17], v34 offset:18320
	s_waitcnt vmcnt(3) lgkmcnt(1)
	v_pk_fma_f32 v[42:43], v[28:29], v[6:7], v[56:57] op_sel_hi:[1,0,1]
	v_pk_fma_f32 v[46:47], v[26:27], v[6:7], v[58:59] op_sel_hi:[1,0,1]
	s_waitcnt vmcnt(2)
	v_pk_fma_f32 v[50:51], v[20:21], v[6:7], v[62:63] op_sel:[0,1,0]
	v_pk_fma_f32 v[22:23], v[18:19], v[6:7], v[22:23] op_sel:[0,1,0]
	v_mov_b32_e32 v6, v9
	v_pk_fma_f32 v[56:57], v[20:21], v[6:7], v[64:65] op_sel_hi:[1,0,1]
	v_pk_fma_f32 v[58:59], v[18:19], v[6:7], v[24:25] op_sel_hi:[1,0,1]
	s_waitcnt lgkmcnt(0)
	v_mov_b32_e32 v6, v17
	v_pk_fma_f32 v[36:37], v[28:29], v[8:9], v[36:37] op_sel_hi:[1,0,1]
	v_pk_fma_f32 v[52:53], v[26:27], v[8:9], v[52:53] op_sel_hi:[1,0,1]
	v_pk_fma_f32 v[38:39], v[28:29], v[14:15], v[38:39] op_sel_hi:[1,0,1]
	v_pk_fma_f32 v[54:55], v[26:27], v[14:15], v[54:55] op_sel_hi:[1,0,1]
	v_pk_fma_f32 v[60:61], v[20:21], v[14:15], v[66:67] op_sel:[0,1,0]
	v_pk_fma_f32 v[62:63], v[18:19], v[14:15], v[30:31] op_sel:[0,1,0]
	v_pk_fma_f32 v[44:45], v[28:29], v[16:17], v[44:45] op_sel_hi:[1,0,1]
	v_pk_fma_f32 v[48:49], v[26:27], v[16:17], v[48:49] op_sel_hi:[1,0,1]
	v_pk_fma_f32 v[64:65], v[20:21], v[6:7], v[32:33] op_sel_hi:[1,0,1]
	v_pk_fma_f32 v[40:41], v[18:19], v[6:7], v[40:41] op_sel_hi:[1,0,1]
	ds_read_b128 v[6:9], v34 offset:18368
	ds_read_b128 v[14:17], v34 offset:18384
	s_waitcnt lgkmcnt(0)
	s_barrier
	s_waitcnt vmcnt(1)
	v_pk_fma_f32 v[20:21], v[12:13], v[6:7], v[42:43] op_sel_hi:[1,0,1]
	v_pk_fma_f32 v[18:19], v[10:11], v[6:7], v[46:47] op_sel_hi:[1,0,1]
	s_waitcnt vmcnt(0)
	v_pk_fma_f32 v[24:25], v[4:5], v[6:7], v[50:51] op_sel:[0,1,0]
	v_pk_fma_f32 v[22:23], v[2:3], v[6:7], v[22:23] op_sel:[0,1,0]
	v_pk_fma_f32 v[28:29], v[12:13], v[8:9], v[36:37] op_sel_hi:[1,0,1]
	v_mov_b32_e32 v6, v9
	v_pk_fma_f32 v[32:33], v[12:13], v[14:15], v[38:39] op_sel_hi:[1,0,1]
	v_pk_fma_f32 v[30:31], v[10:11], v[14:15], v[54:55] op_sel_hi:[1,0,1]
	v_pk_fma_f32 v[38:39], v[4:5], v[14:15], v[60:61] op_sel:[0,1,0]
	v_pk_fma_f32 v[36:37], v[2:3], v[14:15], v[62:63] op_sel:[0,1,0]
	v_mov_b32_e32 v14, v17
	v_pk_fma_f32 v[26:27], v[10:11], v[8:9], v[52:53] op_sel_hi:[1,0,1]
	v_pk_fma_f32 v[8:9], v[4:5], v[6:7], v[56:57] op_sel_hi:[1,0,1]
	v_pk_fma_f32 v[6:7], v[2:3], v[6:7], v[58:59] op_sel_hi:[1,0,1]
	v_pk_fma_f32 v[4:5], v[4:5], v[14:15], v[64:65] op_sel_hi:[1,0,1]
	v_pk_fma_f32 v[2:3], v[2:3], v[14:15], v[40:41] op_sel_hi:[1,0,1]
	v_and_b32_e32 v14, 0x7c, v116
	v_pk_fma_f32 v[12:13], v[12:13], v[16:17], v[44:45] op_sel_hi:[1,0,1]
	v_pk_fma_f32 v[10:11], v[10:11], v[16:17], v[48:49] op_sel_hi:[1,0,1]
	v_lshl_add_u32 v14, v14, 2, 0
	v_lshlrev_b32_e64 v15, 13, s18
	v_lshlrev_b32_e32 v16, 9, v124
	v_add3_u32 v14, v14, v15, v16
	ds_write_b128 v14, v[18:21]
	ds_write_b128 v14, v[22:25] offset:1024
	ds_write_b128 v14, v[26:29] offset:2048
	ds_write_b128 v14, v[6:9] offset:3072
	ds_write_b128 v14, v[30:33] offset:4096
	ds_write_b128 v14, v[36:39] offset:5120
	ds_write_b128 v14, v[10:13] offset:6144
	ds_write_b128 v14, v[2:5] offset:7168
	v_lshl_add_u32 v10, v1, 4, 0
	s_waitcnt lgkmcnt(0)
	s_waitcnt lgkmcnt(0)
	s_barrier
	ds_read_b128 v[2:5], v10
	s_waitcnt lgkmcnt(0)
	v_pk_add_f32 v[6:7], v[4:5], 0 op_sel_hi:[1,0]
	v_pk_add_f32 v[8:9], v[2:3], 0 op_sel_hi:[1,0]
	ds_read_b128 v[2:5], v10 offset:8192
	s_waitcnt lgkmcnt(0)
	v_pk_add_f32 v[6:7], v[6:7], v[4:5]
	v_pk_add_f32 v[8:9], v[8:9], v[2:3]
	ds_read_b128 v[2:5], v10 offset:16384
	s_waitcnt lgkmcnt(0)
	v_pk_add_f32 v[6:7], v[6:7], v[4:5]
	v_pk_add_f32 v[8:9], v[8:9], v[2:3]
	ds_read_b128 v[2:5], v10 offset:24576
	s_waitcnt lgkmcnt(0)
	v_pk_add_f32 v[6:7], v[6:7], v[4:5]
	v_pk_add_f32 v[8:9], v[8:9], v[2:3]
	ds_read_b128 v[2:5], v10 offset:32768
	s_waitcnt lgkmcnt(0)
	v_pk_add_f32 v[6:7], v[6:7], v[4:5]
	v_pk_add_f32 v[8:9], v[8:9], v[2:3]
	ds_read_b128 v[2:5], v10 offset:40960
	s_waitcnt lgkmcnt(0)
	v_pk_add_f32 v[6:7], v[6:7], v[4:5]
	v_pk_add_f32 v[8:9], v[8:9], v[2:3]
	ds_read_b128 v[2:5], v10 offset:49152
	s_waitcnt lgkmcnt(0)
	v_pk_add_f32 v[6:7], v[6:7], v[4:5]
	v_pk_add_f32 v[8:9], v[8:9], v[2:3]
	ds_read_b128 v[2:5], v10 offset:57344
	s_waitcnt lgkmcnt(0)
	v_pk_add_f32 v[4:5], v[6:7], v[4:5]
	v_pk_add_f32 v[2:3], v[8:9], v[2:3]
	v_lshlrev_b64 v[6:7], 13, v[84:85]
	v_lshlrev_b32_e32 v8, 2, v1
	v_lshl_add_u64 v[6:7], s[10:11], 0, v[6:7]
	v_ashrrev_i32_e32 v9, 31, v8
	v_lshl_add_u64 v[6:7], v[8:9], 2, v[6:7]
	v_add_co_u32_e32 v6, vcc, 0x34700000, v6
	s_nop 1
	v_addc_co_u32_e32 v7, vcc, 0, v7, vcc
	global_store_dwordx4 v[6:7], v[2:5], off
	s_barrier
	s_cbranch_execnz .LBB0_1031
	s_branch .LBB0_1048
